# v40 + half of the K-loop DMA address adds replaced by the SGPR-base form
# baseline (speedup 1.0000x reference)
.LBB0_261:
	s_ashr_i32 s35, s34, 31
	s_lshl_b64 vcc, s[34:35], 21
	s_add_u32 s13, s30, vcc_lo
	s_addc_u32 s15, s31, vcc_hi
	s_add_u32 s54, s13, s54
	s_addc_u32 s55, s15, s55
	s_and_b64 s[86:87], s[86:87], exec
	s_cselect_b32 s13, s55, s11
	s_cselect_b32 s15, s54, s10
	s_add_i32 s35, s19, -2
	s_add_u32 s40, s10, 0x100
	s_addc_u32 s49, s11, 0
	s_add_u32 s10, s38, 0x100080
	s_addc_u32 s11, s39, 0
	s_mov_b32 s38, 0
	s_add_i32 vcc_lo, s38, 2
	s_add_u32 s39, s10, 0xfff00080
	s_addc_u32 s66, s11, -1
	s_add_i32 s67, 0, 0x10000
	s_cmp_eq_u32 s35, s38
	s_cselect_b32 s87, s53, s66
	s_cselect_b32 s86, s52, s39
	s_cselect_b32 s39, s13, s49
	s_cselect_b32 s38, s15, s40
	s_add_i32 vcc_hi, 0, 0x14000
	v_add_u32_e32 v142, s67, v1
	v_add_u32_e32 v180, vcc_hi, v1
	ds_read_b128 v[130:133], v142
	ds_read_b128 v[134:137], v142 offset:1024
	ds_read_b128 v[138:141], v142 offset:2048
	ds_read_b128 v[142:145], v142 offset:3072
	ds_read_b128 v[168:171], v180
	ds_read_b128 v[172:175], v180 offset:1024
	ds_read_b128 v[176:179], v180 offset:2048
	ds_read_b128 v[180:183], v180 offset:3072
	s_add_i32 m0, s85, 0xc000
	ds_read_b128 v[198:201], v197
	ds_read_b128 v[202:205], v197 offset:1024
	ds_read_b128 v[206:209], v197 offset:2048
	ds_read_b128 v[210:213], v197 offset:3072
	ds_read_b128 v[214:217], v197 offset:4096
	ds_read_b128 v[218:221], v197 offset:5120
	ds_read_b128 v[222:225], v197 offset:6144
	ds_read_b128 v[226:229], v197 offset:7168
	global_load_lds_dwordx4 v164, s[10:11]
	s_add_i32 m0, s85, 0xe000
	s_nop 0
	global_load_lds_dwordx4 v166, s[10:11]
	s_waitcnt vmcnt(8)
	s_waitcnt lgkmcnt(0)
	s_setprio 1
	s_barrier
	v_mfma_f32_16x16x32_bf16 v[114:117], v[130:133], v[198:201], 0
	v_mfma_f32_16x16x32_bf16 v[118:121], v[138:141], v[198:201], 0
	v_mfma_f32_16x16x32_bf16 v[102:105], v[130:133], v[206:209], 0
	v_mfma_f32_16x16x32_bf16 v[98:101], v[138:141], v[206:209], 0
	v_mfma_f32_16x16x32_bf16 v[86:89], v[130:133], v[214:217], 0
	v_mfma_f32_16x16x32_bf16 v[82:85], v[138:141], v[214:217], 0
	v_mfma_f32_16x16x32_bf16 v[54:57], v[130:133], v[222:225], 0
	v_mfma_f32_16x16x32_bf16 v[50:53], v[138:141], v[222:225], 0
	v_mfma_f32_16x16x32_bf16 v[114:117], v[134:137], v[202:205], v[114:117]
	v_mfma_f32_16x16x32_bf16 v[118:121], v[142:145], v[202:205], v[118:121]
	v_mfma_f32_16x16x32_bf16 v[102:105], v[134:137], v[210:213], v[102:105]
	v_mfma_f32_16x16x32_bf16 v[98:101], v[142:145], v[210:213], v[98:101]
	v_mfma_f32_16x16x32_bf16 v[86:89], v[134:137], v[218:221], v[86:89]
	v_mfma_f32_16x16x32_bf16 v[82:85], v[142:145], v[218:221], v[82:85]
	v_mfma_f32_16x16x32_bf16 v[54:57], v[134:137], v[226:229], v[54:57]
	v_mfma_f32_16x16x32_bf16 v[50:53], v[142:145], v[226:229], v[50:53]
	s_setprio 0
	s_setprio 1
	v_mfma_f32_16x16x32_bf16 v[126:129], v[168:171], v[198:201], 0
	v_mfma_f32_16x16x32_bf16 v[122:125], v[176:179], v[198:201], 0
	v_mfma_f32_16x16x32_bf16 v[110:113], v[168:171], v[206:209], 0
	v_mfma_f32_16x16x32_bf16 v[106:109], v[176:179], v[206:209], 0
	v_mfma_f32_16x16x32_bf16 v[94:97], v[168:171], v[214:217], 0
	v_mfma_f32_16x16x32_bf16 v[90:93], v[176:179], v[214:217], 0
	v_mfma_f32_16x16x32_bf16 v[70:73], v[168:171], v[222:225], 0
	v_mfma_f32_16x16x32_bf16 v[66:69], v[176:179], v[222:225], 0
	v_mfma_f32_16x16x32_bf16 v[126:129], v[172:175], v[202:205], v[126:129]
	v_mfma_f32_16x16x32_bf16 v[122:125], v[180:183], v[202:205], v[122:125]
	v_mfma_f32_16x16x32_bf16 v[110:113], v[172:175], v[210:213], v[110:113]
	v_mfma_f32_16x16x32_bf16 v[106:109], v[180:183], v[210:213], v[106:109]
	v_mfma_f32_16x16x32_bf16 v[94:97], v[172:175], v[218:221], v[94:97]
	v_mfma_f32_16x16x32_bf16 v[90:93], v[180:183], v[218:221], v[90:93]
	v_mfma_f32_16x16x32_bf16 v[70:73], v[172:175], v[226:229], v[70:73]
	v_mfma_f32_16x16x32_bf16 v[66:69], v[180:183], v[226:229], v[66:69]
	s_barrier
	s_setprio 0
	s_add_i32 s66, s67, s97
	v_lshl_add_u64 v[184:185], s[38:39], 0, v[156:157]
	s_mov_b32 m0, s66
	ds_read_b128 v[198:201], v197 offset:16384
	ds_read_b128 v[202:205], v197 offset:17408
	ds_read_b128 v[206:209], v197 offset:18432
	ds_read_b128 v[210:213], v197 offset:19456
	ds_read_b128 v[214:217], v197 offset:20480
	ds_read_b128 v[218:221], v197 offset:21504
	ds_read_b128 v[222:225], v197 offset:22528
	ds_read_b128 v[226:229], v197 offset:23552
	global_load_lds_dwordx4 v[184:185], off
	s_add_i32 m0, s66, 0x2000
	s_add_u32 s66, s38, 0x100000
	v_lshl_add_u64 v[230:231], s[38:39], 0, v[160:161]
	s_addc_u32 s67, s39, 0
	s_add_i32 vcc_hi, vcc_hi, s97
	global_load_lds_dwordx4 v[230:231], off
	s_mov_b32 m0, vcc_hi
	v_lshl_add_u64 v[234:235], s[86:87], 0, v[158:159]
	global_load_lds_dwordx4 v156, s[66:67]
	s_add_i32 m0, vcc_hi, 0x2000
	s_nop 0
	global_load_lds_dwordx4 v160, s[66:67]
	v_lshl_add_u64 v[232:233], s[86:87], 0, v[154:155]
	s_mov_b32 m0, s85
	s_nop 0
	global_load_lds_dwordx4 v[232:233], off
	s_mov_b32 m0, s92
	s_nop 0
	global_load_lds_dwordx4 v[234:235], off
	s_waitcnt vmcnt(8)
	s_waitcnt lgkmcnt(0)
	s_setprio 1
	s_barrier
	v_mfma_f32_16x16x32_bf16 v[62:65], v[130:133], v[198:201], 0
	v_mfma_f32_16x16x32_bf16 v[58:61], v[138:141], v[198:201], 0
	v_mfma_f32_16x16x32_bf16 v[38:41], v[130:133], v[206:209], 0
	v_mfma_f32_16x16x32_bf16 v[34:37], v[138:141], v[206:209], 0
	v_mfma_f32_16x16x32_bf16 v[22:25], v[130:133], v[214:217], 0
	v_mfma_f32_16x16x32_bf16 v[18:21], v[138:141], v[214:217], 0
	v_mfma_f32_16x16x32_bf16 v[6:9], v[130:133], v[222:225], 0
	v_mfma_f32_16x16x32_bf16 v[2:5], v[138:141], v[222:225], 0
	v_mfma_f32_16x16x32_bf16 v[62:65], v[134:137], v[202:205], v[62:65]
	v_mfma_f32_16x16x32_bf16 v[58:61], v[142:145], v[202:205], v[58:61]
	v_mfma_f32_16x16x32_bf16 v[38:41], v[134:137], v[210:213], v[38:41]
	v_mfma_f32_16x16x32_bf16 v[34:37], v[142:145], v[210:213], v[34:37]
	v_mfma_f32_16x16x32_bf16 v[22:25], v[134:137], v[218:221], v[22:25]
	v_mfma_f32_16x16x32_bf16 v[18:21], v[142:145], v[218:221], v[18:21]
	v_mfma_f32_16x16x32_bf16 v[6:9], v[134:137], v[226:229], v[6:9]
	v_mfma_f32_16x16x32_bf16 v[2:5], v[142:145], v[226:229], v[2:5]
	s_setprio 0
	s_setprio 1
	v_mfma_f32_16x16x32_bf16 v[78:81], v[168:171], v[198:201], 0
	v_mfma_f32_16x16x32_bf16 v[74:77], v[176:179], v[198:201], 0
	v_mfma_f32_16x16x32_bf16 v[46:49], v[168:171], v[206:209], 0
	v_mfma_f32_16x16x32_bf16 v[42:45], v[176:179], v[206:209], 0
	v_mfma_f32_16x16x32_bf16 v[30:33], v[168:171], v[214:217], 0
	v_mfma_f32_16x16x32_bf16 v[26:29], v[176:179], v[214:217], 0
	v_mfma_f32_16x16x32_bf16 v[14:17], v[168:171], v[222:225], 0
	v_mfma_f32_16x16x32_bf16 v[10:13], v[176:179], v[222:225], 0
	v_mfma_f32_16x16x32_bf16 v[78:81], v[172:175], v[202:205], v[78:81]
	v_mfma_f32_16x16x32_bf16 v[74:77], v[180:183], v[202:205], v[74:77]
	v_mfma_f32_16x16x32_bf16 v[46:49], v[172:175], v[210:213], v[46:49]
	v_mfma_f32_16x16x32_bf16 v[42:45], v[180:183], v[210:213], v[42:45]
	v_mfma_f32_16x16x32_bf16 v[30:33], v[172:175], v[218:221], v[30:33]
	v_mfma_f32_16x16x32_bf16 v[26:29], v[180:183], v[218:221], v[26:29]
	v_mfma_f32_16x16x32_bf16 v[14:17], v[172:175], v[226:229], v[14:17]
	v_mfma_f32_16x16x32_bf16 v[10:13], v[180:183], v[226:229], v[10:13]
	s_barrier
	s_setprio 0
	s_add_i32 vcc_hi, 0, 0x18000
	s_add_i32 s56, 0, 0x1c000
	v_add_u32_e32 v142, vcc_hi, v1
	v_add_u32_e32 v180, s56, v1
	ds_read_b128 v[130:133], v142
	ds_read_b128 v[134:137], v142 offset:1024
	ds_read_b128 v[138:141], v142 offset:2048
	ds_read_b128 v[142:145], v142 offset:3072
	ds_read_b128 v[168:171], v180
	ds_read_b128 v[172:175], v180 offset:1024
	ds_read_b128 v[176:179], v180 offset:2048
	ds_read_b128 v[180:183], v180 offset:3072
	s_add_u32 s66, s86, 0x100000
	s_addc_u32 s67, s87, 0
	s_mov_b32 m0, s93
	ds_read_b128 v[198:201], v197 offset:32768
	ds_read_b128 v[202:205], v197 offset:33792
	ds_read_b128 v[206:209], v197 offset:34816
	ds_read_b128 v[210:213], v197 offset:35840
	ds_read_b128 v[214:217], v197 offset:36864
	ds_read_b128 v[218:221], v197 offset:37888
	ds_read_b128 v[222:225], v197 offset:38912
	ds_read_b128 v[226:229], v197 offset:39936
	global_load_lds_dwordx4 v154, s[66:67]
	s_mov_b32 m0, s42
	s_nop 0
	global_load_lds_dwordx4 v158, s[66:67]
	s_waitcnt vmcnt(8)
	s_waitcnt lgkmcnt(0)
	s_setprio 1
	s_barrier
	v_mfma_f32_16x16x32_bf16 v[114:117], v[130:133], v[198:201], v[114:117]
	v_mfma_f32_16x16x32_bf16 v[118:121], v[138:141], v[198:201], v[118:121]
	v_mfma_f32_16x16x32_bf16 v[102:105], v[130:133], v[206:209], v[102:105]
	v_mfma_f32_16x16x32_bf16 v[98:101], v[138:141], v[206:209], v[98:101]
	v_mfma_f32_16x16x32_bf16 v[86:89], v[130:133], v[214:217], v[86:89]
	v_mfma_f32_16x16x32_bf16 v[82:85], v[138:141], v[214:217], v[82:85]
	v_mfma_f32_16x16x32_bf16 v[54:57], v[130:133], v[222:225], v[54:57]
	v_mfma_f32_16x16x32_bf16 v[50:53], v[138:141], v[222:225], v[50:53]
	v_mfma_f32_16x16x32_bf16 v[114:117], v[134:137], v[202:205], v[114:117]
	v_mfma_f32_16x16x32_bf16 v[118:121], v[142:145], v[202:205], v[118:121]
	v_mfma_f32_16x16x32_bf16 v[102:105], v[134:137], v[210:213], v[102:105]
	v_mfma_f32_16x16x32_bf16 v[98:101], v[142:145], v[210:213], v[98:101]
	v_mfma_f32_16x16x32_bf16 v[86:89], v[134:137], v[218:221], v[86:89]
	v_mfma_f32_16x16x32_bf16 v[82:85], v[142:145], v[218:221], v[82:85]
	v_mfma_f32_16x16x32_bf16 v[54:57], v[134:137], v[226:229], v[54:57]
	v_mfma_f32_16x16x32_bf16 v[50:53], v[142:145], v[226:229], v[50:53]
	s_setprio 0
	s_setprio 1
	v_mfma_f32_16x16x32_bf16 v[126:129], v[168:171], v[198:201], v[126:129]
	v_mfma_f32_16x16x32_bf16 v[122:125], v[176:179], v[198:201], v[122:125]
	v_mfma_f32_16x16x32_bf16 v[110:113], v[168:171], v[206:209], v[110:113]
	v_mfma_f32_16x16x32_bf16 v[106:109], v[176:179], v[206:209], v[106:109]
	v_mfma_f32_16x16x32_bf16 v[94:97], v[168:171], v[214:217], v[94:97]
	v_mfma_f32_16x16x32_bf16 v[90:93], v[176:179], v[214:217], v[90:93]
	v_mfma_f32_16x16x32_bf16 v[70:73], v[168:171], v[222:225], v[70:73]
	v_mfma_f32_16x16x32_bf16 v[66:69], v[176:179], v[222:225], v[66:69]
	v_mfma_f32_16x16x32_bf16 v[126:129], v[172:175], v[202:205], v[126:129]
	v_mfma_f32_16x16x32_bf16 v[122:125], v[180:183], v[202:205], v[122:125]
	v_mfma_f32_16x16x32_bf16 v[110:113], v[172:175], v[210:213], v[110:113]
	v_mfma_f32_16x16x32_bf16 v[106:109], v[180:183], v[210:213], v[106:109]
	v_mfma_f32_16x16x32_bf16 v[94:97], v[172:175], v[218:221], v[94:97]
	v_mfma_f32_16x16x32_bf16 v[90:93], v[180:183], v[218:221], v[90:93]
	v_mfma_f32_16x16x32_bf16 v[70:73], v[172:175], v[226:229], v[70:73]
	v_mfma_f32_16x16x32_bf16 v[66:69], v[180:183], v[226:229], v[66:69]
	s_barrier
	s_setprio 0
	s_add_i32 s57, vcc_hi, s97
	v_lshl_add_u64 v[184:185], v[184:185], 0, s[94:95]
	s_mov_b32 m0, s57
	ds_read_b128 v[198:201], v197 offset:49152
	ds_read_b128 v[202:205], v197 offset:50176
	ds_read_b128 v[206:209], v197 offset:51200
	ds_read_b128 v[210:213], v197 offset:52224
	ds_read_b128 v[214:217], v197 offset:53248
	ds_read_b128 v[218:221], v197 offset:54272
	ds_read_b128 v[222:225], v197 offset:55296
	ds_read_b128 v[226:229], v197 offset:56320
	global_load_lds_dwordx4 v[184:185], off
	s_add_i32 m0, s57, 0x2000
	s_add_u32 s38, s38, 0x100080
	v_lshl_add_u64 v[184:185], v[230:231], 0, s[94:95]
	s_addc_u32 s39, s39, 0
	s_add_i32 s56, s56, s97
	global_load_lds_dwordx4 v[184:185], off
	s_mov_b32 m0, s56
	s_nop 0
	global_load_lds_dwordx4 v156, s[38:39]
	s_add_i32 m0, s56, 0x2000
	s_nop 0
	global_load_lds_dwordx4 v160, s[38:39]
	v_lshl_add_u64 v[184:185], v[232:233], 0, s[94:95]
	s_mov_b32 m0, s43
	s_nop 0
	global_load_lds_dwordx4 v[184:185], off
	v_lshl_add_u64 v[184:185], v[234:235], 0, s[94:95]
	s_mov_b32 m0, s90
	s_nop 0
	global_load_lds_dwordx4 v[184:185], off
	s_waitcnt vmcnt(8)
	s_waitcnt lgkmcnt(0)
	s_setprio 1
	s_barrier
	v_mfma_f32_16x16x32_bf16 v[62:65], v[130:133], v[198:201], v[62:65]
	v_mfma_f32_16x16x32_bf16 v[58:61], v[138:141], v[198:201], v[58:61]
	v_mfma_f32_16x16x32_bf16 v[38:41], v[130:133], v[206:209], v[38:41]
	v_mfma_f32_16x16x32_bf16 v[34:37], v[138:141], v[206:209], v[34:37]
	v_mfma_f32_16x16x32_bf16 v[22:25], v[130:133], v[214:217], v[22:25]
	v_mfma_f32_16x16x32_bf16 v[18:21], v[138:141], v[214:217], v[18:21]
	v_mfma_f32_16x16x32_bf16 v[6:9], v[130:133], v[222:225], v[6:9]
	v_mfma_f32_16x16x32_bf16 v[2:5], v[138:141], v[222:225], v[2:5]
	v_mfma_f32_16x16x32_bf16 v[62:65], v[134:137], v[202:205], v[62:65]
	v_mfma_f32_16x16x32_bf16 v[58:61], v[142:145], v[202:205], v[58:61]
	v_mfma_f32_16x16x32_bf16 v[38:41], v[134:137], v[210:213], v[38:41]
	v_mfma_f32_16x16x32_bf16 v[34:37], v[142:145], v[210:213], v[34:37]
	v_mfma_f32_16x16x32_bf16 v[22:25], v[134:137], v[218:221], v[22:25]
	v_mfma_f32_16x16x32_bf16 v[18:21], v[142:145], v[218:221], v[18:21]
	v_mfma_f32_16x16x32_bf16 v[6:9], v[134:137], v[226:229], v[6:9]
	v_mfma_f32_16x16x32_bf16 v[2:5], v[142:145], v[226:229], v[2:5]
	s_setprio 0
	s_setprio 1
	v_mfma_f32_16x16x32_bf16 v[78:81], v[168:171], v[198:201], v[78:81]
	v_mfma_f32_16x16x32_bf16 v[74:77], v[176:179], v[198:201], v[74:77]
	v_mfma_f32_16x16x32_bf16 v[46:49], v[168:171], v[206:209], v[46:49]
	v_mfma_f32_16x16x32_bf16 v[42:45], v[176:179], v[206:209], v[42:45]
	v_mfma_f32_16x16x32_bf16 v[30:33], v[168:171], v[214:217], v[30:33]
	v_mfma_f32_16x16x32_bf16 v[26:29], v[176:179], v[214:217], v[26:29]
	v_mfma_f32_16x16x32_bf16 v[14:17], v[168:171], v[222:225], v[14:17]
	v_mfma_f32_16x16x32_bf16 v[10:13], v[176:179], v[222:225], v[10:13]
	v_mfma_f32_16x16x32_bf16 v[78:81], v[172:175], v[202:205], v[78:81]
	v_mfma_f32_16x16x32_bf16 v[74:77], v[180:183], v[202:205], v[74:77]
	v_mfma_f32_16x16x32_bf16 v[46:49], v[172:175], v[210:213], v[46:49]
	v_mfma_f32_16x16x32_bf16 v[42:45], v[180:183], v[210:213], v[42:45]
	v_mfma_f32_16x16x32_bf16 v[30:33], v[172:175], v[218:221], v[30:33]
	v_mfma_f32_16x16x32_bf16 v[26:29], v[180:183], v[218:221], v[26:29]
	v_mfma_f32_16x16x32_bf16 v[14:17], v[172:175], v[226:229], v[14:17]
	v_mfma_f32_16x16x32_bf16 v[10:13], v[180:183], v[226:229], v[10:13]
	s_barrier
	s_setprio 0
	s_add_u32 s40, s40, 0x100
	s_addc_u32 s49, s49, 0
	s_add_u32 s10, s10, 0x100
	s_addc_u32 s11, s11, 0
	s_cmp_ge_u32 vcc_lo, s19
	s_mov_b32 s38, vcc_lo
	s_cbranch_scc1 .Lpeel_done_0
.LBB0_262:
	s_add_i32 vcc_lo, s38, 2
	s_add_u32 s39, s10, 0xfff00080
	s_addc_u32 s66, s11, -1
	s_add_i32 s67, 0, 0x10000
	s_cmp_eq_u32 s35, s38
	s_cselect_b32 s87, s53, s66
	s_cselect_b32 s86, s52, s39
	s_cselect_b32 s39, s13, s49
	s_cselect_b32 s38, s15, s40
	s_add_i32 vcc_hi, 0, 0x14000
	v_add_u32_e32 v142, s67, v1
	v_add_u32_e32 v180, vcc_hi, v1
	ds_read_b128 v[130:133], v142
	ds_read_b128 v[134:137], v142 offset:1024
	ds_read_b128 v[138:141], v142 offset:2048
	ds_read_b128 v[142:145], v142 offset:3072
	ds_read_b128 v[168:171], v180
	ds_read_b128 v[172:175], v180 offset:1024
	ds_read_b128 v[176:179], v180 offset:2048
	ds_read_b128 v[180:183], v180 offset:3072
	s_add_i32 m0, s85, 0xc000
	ds_read_b128 v[198:201], v197
	ds_read_b128 v[202:205], v197 offset:1024
	ds_read_b128 v[206:209], v197 offset:2048
	ds_read_b128 v[210:213], v197 offset:3072
	ds_read_b128 v[214:217], v197 offset:4096
	ds_read_b128 v[218:221], v197 offset:5120
	ds_read_b128 v[222:225], v197 offset:6144
	ds_read_b128 v[226:229], v197 offset:7168
	global_load_lds_dwordx4 v164, s[10:11]
	s_add_i32 m0, s85, 0xe000
	s_nop 0
	global_load_lds_dwordx4 v166, s[10:11]
	s_waitcnt vmcnt(8)
	s_waitcnt lgkmcnt(0)
	s_setprio 1
	s_barrier
	v_mfma_f32_16x16x32_bf16 v[114:117], v[130:133], v[198:201], v[114:117]
	v_mfma_f32_16x16x32_bf16 v[118:121], v[138:141], v[198:201], v[118:121]
	v_mfma_f32_16x16x32_bf16 v[102:105], v[130:133], v[206:209], v[102:105]
	v_mfma_f32_16x16x32_bf16 v[98:101], v[138:141], v[206:209], v[98:101]
	v_mfma_f32_16x16x32_bf16 v[86:89], v[130:133], v[214:217], v[86:89]
	v_mfma_f32_16x16x32_bf16 v[82:85], v[138:141], v[214:217], v[82:85]
	v_mfma_f32_16x16x32_bf16 v[54:57], v[130:133], v[222:225], v[54:57]
	v_mfma_f32_16x16x32_bf16 v[50:53], v[138:141], v[222:225], v[50:53]
	v_mfma_f32_16x16x32_bf16 v[114:117], v[134:137], v[202:205], v[114:117]
	v_mfma_f32_16x16x32_bf16 v[118:121], v[142:145], v[202:205], v[118:121]
	v_mfma_f32_16x16x32_bf16 v[102:105], v[134:137], v[210:213], v[102:105]
	v_mfma_f32_16x16x32_bf16 v[98:101], v[142:145], v[210:213], v[98:101]
	v_mfma_f32_16x16x32_bf16 v[86:89], v[134:137], v[218:221], v[86:89]
	v_mfma_f32_16x16x32_bf16 v[82:85], v[142:145], v[218:221], v[82:85]
	v_mfma_f32_16x16x32_bf16 v[54:57], v[134:137], v[226:229], v[54:57]
	v_mfma_f32_16x16x32_bf16 v[50:53], v[142:145], v[226:229], v[50:53]
	s_setprio 0
	s_setprio 1
	v_mfma_f32_16x16x32_bf16 v[126:129], v[168:171], v[198:201], v[126:129]
	v_mfma_f32_16x16x32_bf16 v[122:125], v[176:179], v[198:201], v[122:125]
	v_mfma_f32_16x16x32_bf16 v[110:113], v[168:171], v[206:209], v[110:113]
	v_mfma_f32_16x16x32_bf16 v[106:109], v[176:179], v[206:209], v[106:109]
	v_mfma_f32_16x16x32_bf16 v[94:97], v[168:171], v[214:217], v[94:97]
	v_mfma_f32_16x16x32_bf16 v[90:93], v[176:179], v[214:217], v[90:93]
	v_mfma_f32_16x16x32_bf16 v[70:73], v[168:171], v[222:225], v[70:73]
	v_mfma_f32_16x16x32_bf16 v[66:69], v[176:179], v[222:225], v[66:69]
	v_mfma_f32_16x16x32_bf16 v[126:129], v[172:175], v[202:205], v[126:129]
	v_mfma_f32_16x16x32_bf16 v[122:125], v[180:183], v[202:205], v[122:125]
	v_mfma_f32_16x16x32_bf16 v[110:113], v[172:175], v[210:213], v[110:113]
	v_mfma_f32_16x16x32_bf16 v[106:109], v[180:183], v[210:213], v[106:109]
	v_mfma_f32_16x16x32_bf16 v[94:97], v[172:175], v[218:221], v[94:97]
	v_mfma_f32_16x16x32_bf16 v[90:93], v[180:183], v[218:221], v[90:93]
	v_mfma_f32_16x16x32_bf16 v[70:73], v[172:175], v[226:229], v[70:73]
	v_mfma_f32_16x16x32_bf16 v[66:69], v[180:183], v[226:229], v[66:69]
	s_barrier
	s_setprio 0
	s_add_i32 s66, s67, s97
	v_lshl_add_u64 v[184:185], s[38:39], 0, v[156:157]
	s_mov_b32 m0, s66
	ds_read_b128 v[198:201], v197 offset:16384
	ds_read_b128 v[202:205], v197 offset:17408
	ds_read_b128 v[206:209], v197 offset:18432
	ds_read_b128 v[210:213], v197 offset:19456
	ds_read_b128 v[214:217], v197 offset:20480
	ds_read_b128 v[218:221], v197 offset:21504
	ds_read_b128 v[222:225], v197 offset:22528
	ds_read_b128 v[226:229], v197 offset:23552
	global_load_lds_dwordx4 v[184:185], off
	s_add_i32 m0, s66, 0x2000
	s_add_u32 s66, s38, 0x100000
	v_lshl_add_u64 v[230:231], s[38:39], 0, v[160:161]
	s_addc_u32 s67, s39, 0
	s_add_i32 vcc_hi, vcc_hi, s97
	global_load_lds_dwordx4 v[230:231], off
	s_mov_b32 m0, vcc_hi
	v_lshl_add_u64 v[234:235], s[86:87], 0, v[158:159]
	global_load_lds_dwordx4 v156, s[66:67]
	s_add_i32 m0, vcc_hi, 0x2000
	s_nop 0
	global_load_lds_dwordx4 v160, s[66:67]
	v_lshl_add_u64 v[232:233], s[86:87], 0, v[154:155]
	s_mov_b32 m0, s85
	s_nop 0
	global_load_lds_dwordx4 v[232:233], off
	s_mov_b32 m0, s92
	s_nop 0
	global_load_lds_dwordx4 v[234:235], off
	s_waitcnt vmcnt(8)
	s_waitcnt lgkmcnt(0)
	s_setprio 1
	s_barrier
	v_mfma_f32_16x16x32_bf16 v[62:65], v[130:133], v[198:201], v[62:65]
	v_mfma_f32_16x16x32_bf16 v[58:61], v[138:141], v[198:201], v[58:61]
	v_mfma_f32_16x16x32_bf16 v[38:41], v[130:133], v[206:209], v[38:41]
	v_mfma_f32_16x16x32_bf16 v[34:37], v[138:141], v[206:209], v[34:37]
	v_mfma_f32_16x16x32_bf16 v[22:25], v[130:133], v[214:217], v[22:25]
	v_mfma_f32_16x16x32_bf16 v[18:21], v[138:141], v[214:217], v[18:21]
	v_mfma_f32_16x16x32_bf16 v[6:9], v[130:133], v[222:225], v[6:9]
	v_mfma_f32_16x16x32_bf16 v[2:5], v[138:141], v[222:225], v[2:5]
	v_mfma_f32_16x16x32_bf16 v[62:65], v[134:137], v[202:205], v[62:65]
	v_mfma_f32_16x16x32_bf16 v[58:61], v[142:145], v[202:205], v[58:61]
	v_mfma_f32_16x16x32_bf16 v[38:41], v[134:137], v[210:213], v[38:41]
	v_mfma_f32_16x16x32_bf16 v[34:37], v[142:145], v[210:213], v[34:37]
	v_mfma_f32_16x16x32_bf16 v[22:25], v[134:137], v[218:221], v[22:25]
	v_mfma_f32_16x16x32_bf16 v[18:21], v[142:145], v[218:221], v[18:21]
	v_mfma_f32_16x16x32_bf16 v[6:9], v[134:137], v[226:229], v[6:9]
	v_mfma_f32_16x16x32_bf16 v[2:5], v[142:145], v[226:229], v[2:5]
	s_setprio 0
	s_setprio 1
	v_mfma_f32_16x16x32_bf16 v[78:81], v[168:171], v[198:201], v[78:81]
	v_mfma_f32_16x16x32_bf16 v[74:77], v[176:179], v[198:201], v[74:77]
	v_mfma_f32_16x16x32_bf16 v[46:49], v[168:171], v[206:209], v[46:49]
	v_mfma_f32_16x16x32_bf16 v[42:45], v[176:179], v[206:209], v[42:45]
	v_mfma_f32_16x16x32_bf16 v[30:33], v[168:171], v[214:217], v[30:33]
	v_mfma_f32_16x16x32_bf16 v[26:29], v[176:179], v[214:217], v[26:29]
	v_mfma_f32_16x16x32_bf16 v[14:17], v[168:171], v[222:225], v[14:17]
	v_mfma_f32_16x16x32_bf16 v[10:13], v[176:179], v[222:225], v[10:13]
	v_mfma_f32_16x16x32_bf16 v[78:81], v[172:175], v[202:205], v[78:81]
	v_mfma_f32_16x16x32_bf16 v[74:77], v[180:183], v[202:205], v[74:77]
	v_mfma_f32_16x16x32_bf16 v[46:49], v[172:175], v[210:213], v[46:49]
	v_mfma_f32_16x16x32_bf16 v[42:45], v[180:183], v[210:213], v[42:45]
	v_mfma_f32_16x16x32_bf16 v[30:33], v[172:175], v[218:221], v[30:33]
	v_mfma_f32_16x16x32_bf16 v[26:29], v[180:183], v[218:221], v[26:29]
	v_mfma_f32_16x16x32_bf16 v[14:17], v[172:175], v[226:229], v[14:17]
	v_mfma_f32_16x16x32_bf16 v[10:13], v[180:183], v[226:229], v[10:13]
	s_barrier
	s_setprio 0
	s_add_i32 vcc_hi, 0, 0x18000
	s_add_i32 s56, 0, 0x1c000
	v_add_u32_e32 v142, vcc_hi, v1
	v_add_u32_e32 v180, s56, v1
	ds_read_b128 v[130:133], v142
	ds_read_b128 v[134:137], v142 offset:1024
	ds_read_b128 v[138:141], v142 offset:2048
	ds_read_b128 v[142:145], v142 offset:3072
	ds_read_b128 v[168:171], v180
	ds_read_b128 v[172:175], v180 offset:1024
	ds_read_b128 v[176:179], v180 offset:2048
	ds_read_b128 v[180:183], v180 offset:3072
	s_add_u32 s66, s86, 0x100000
	s_addc_u32 s67, s87, 0
	s_mov_b32 m0, s93
	ds_read_b128 v[198:201], v197 offset:32768
	ds_read_b128 v[202:205], v197 offset:33792
	ds_read_b128 v[206:209], v197 offset:34816
	ds_read_b128 v[210:213], v197 offset:35840
	ds_read_b128 v[214:217], v197 offset:36864
	ds_read_b128 v[218:221], v197 offset:37888
	ds_read_b128 v[222:225], v197 offset:38912
	ds_read_b128 v[226:229], v197 offset:39936
	global_load_lds_dwordx4 v154, s[66:67]
	s_mov_b32 m0, s42
	s_nop 0
	global_load_lds_dwordx4 v158, s[66:67]
	s_waitcnt vmcnt(8)
	s_waitcnt lgkmcnt(0)
	s_setprio 1
	s_barrier
	v_mfma_f32_16x16x32_bf16 v[114:117], v[130:133], v[198:201], v[114:117]
	v_mfma_f32_16x16x32_bf16 v[118:121], v[138:141], v[198:201], v[118:121]
	v_mfma_f32_16x16x32_bf16 v[102:105], v[130:133], v[206:209], v[102:105]
	v_mfma_f32_16x16x32_bf16 v[98:101], v[138:141], v[206:209], v[98:101]
	v_mfma_f32_16x16x32_bf16 v[86:89], v[130:133], v[214:217], v[86:89]
	v_mfma_f32_16x16x32_bf16 v[82:85], v[138:141], v[214:217], v[82:85]
	v_mfma_f32_16x16x32_bf16 v[54:57], v[130:133], v[222:225], v[54:57]
	v_mfma_f32_16x16x32_bf16 v[50:53], v[138:141], v[222:225], v[50:53]
	v_mfma_f32_16x16x32_bf16 v[114:117], v[134:137], v[202:205], v[114:117]
	v_mfma_f32_16x16x32_bf16 v[118:121], v[142:145], v[202:205], v[118:121]
	v_mfma_f32_16x16x32_bf16 v[102:105], v[134:137], v[210:213], v[102:105]
	v_mfma_f32_16x16x32_bf16 v[98:101], v[142:145], v[210:213], v[98:101]
	v_mfma_f32_16x16x32_bf16 v[86:89], v[134:137], v[218:221], v[86:89]
	v_mfma_f32_16x16x32_bf16 v[82:85], v[142:145], v[218:221], v[82:85]
	v_mfma_f32_16x16x32_bf16 v[54:57], v[134:137], v[226:229], v[54:57]
	v_mfma_f32_16x16x32_bf16 v[50:53], v[142:145], v[226:229], v[50:53]
	s_setprio 0
	s_setprio 1
	v_mfma_f32_16x16x32_bf16 v[126:129], v[168:171], v[198:201], v[126:129]
	v_mfma_f32_16x16x32_bf16 v[122:125], v[176:179], v[198:201], v[122:125]
	v_mfma_f32_16x16x32_bf16 v[110:113], v[168:171], v[206:209], v[110:113]
	v_mfma_f32_16x16x32_bf16 v[106:109], v[176:179], v[206:209], v[106:109]
	v_mfma_f32_16x16x32_bf16 v[94:97], v[168:171], v[214:217], v[94:97]
	v_mfma_f32_16x16x32_bf16 v[90:93], v[176:179], v[214:217], v[90:93]
	v_mfma_f32_16x16x32_bf16 v[70:73], v[168:171], v[222:225], v[70:73]
	v_mfma_f32_16x16x32_bf16 v[66:69], v[176:179], v[222:225], v[66:69]
	v_mfma_f32_16x16x32_bf16 v[126:129], v[172:175], v[202:205], v[126:129]
	v_mfma_f32_16x16x32_bf16 v[122:125], v[180:183], v[202:205], v[122:125]
	v_mfma_f32_16x16x32_bf16 v[110:113], v[172:175], v[210:213], v[110:113]
	v_mfma_f32_16x16x32_bf16 v[106:109], v[180:183], v[210:213], v[106:109]
	v_mfma_f32_16x16x32_bf16 v[94:97], v[172:175], v[218:221], v[94:97]
	v_mfma_f32_16x16x32_bf16 v[90:93], v[180:183], v[218:221], v[90:93]
	v_mfma_f32_16x16x32_bf16 v[70:73], v[172:175], v[226:229], v[70:73]
	v_mfma_f32_16x16x32_bf16 v[66:69], v[180:183], v[226:229], v[66:69]
	s_barrier
	s_setprio 0
	s_add_i32 s57, vcc_hi, s97
	v_lshl_add_u64 v[184:185], v[184:185], 0, s[94:95]
	s_mov_b32 m0, s57
	ds_read_b128 v[198:201], v197 offset:49152
	ds_read_b128 v[202:205], v197 offset:50176
	ds_read_b128 v[206:209], v197 offset:51200
	ds_read_b128 v[210:213], v197 offset:52224
	ds_read_b128 v[214:217], v197 offset:53248
	ds_read_b128 v[218:221], v197 offset:54272
	ds_read_b128 v[222:225], v197 offset:55296
	ds_read_b128 v[226:229], v197 offset:56320
	global_load_lds_dwordx4 v[184:185], off
	s_add_i32 m0, s57, 0x2000
	s_add_u32 s38, s38, 0x100080
	v_lshl_add_u64 v[184:185], v[230:231], 0, s[94:95]
	s_addc_u32 s39, s39, 0
	s_add_i32 s56, s56, s97
	global_load_lds_dwordx4 v[184:185], off
	s_mov_b32 m0, s56
	s_nop 0
	global_load_lds_dwordx4 v156, s[38:39]
	s_add_i32 m0, s56, 0x2000
	s_nop 0
	global_load_lds_dwordx4 v160, s[38:39]
	v_lshl_add_u64 v[184:185], v[232:233], 0, s[94:95]
	s_mov_b32 m0, s43
	s_nop 0
	global_load_lds_dwordx4 v[184:185], off
	v_lshl_add_u64 v[184:185], v[234:235], 0, s[94:95]
	s_mov_b32 m0, s90
	s_nop 0
	global_load_lds_dwordx4 v[184:185], off
	s_waitcnt vmcnt(8)
	s_waitcnt lgkmcnt(0)
	s_setprio 1
	s_barrier
	v_mfma_f32_16x16x32_bf16 v[62:65], v[130:133], v[198:201], v[62:65]
	v_mfma_f32_16x16x32_bf16 v[58:61], v[138:141], v[198:201], v[58:61]
	v_mfma_f32_16x16x32_bf16 v[38:41], v[130:133], v[206:209], v[38:41]
	v_mfma_f32_16x16x32_bf16 v[34:37], v[138:141], v[206:209], v[34:37]
	v_mfma_f32_16x16x32_bf16 v[22:25], v[130:133], v[214:217], v[22:25]
	v_mfma_f32_16x16x32_bf16 v[18:21], v[138:141], v[214:217], v[18:21]
	v_mfma_f32_16x16x32_bf16 v[6:9], v[130:133], v[222:225], v[6:9]
	v_mfma_f32_16x16x32_bf16 v[2:5], v[138:141], v[222:225], v[2:5]
	v_mfma_f32_16x16x32_bf16 v[62:65], v[134:137], v[202:205], v[62:65]
	v_mfma_f32_16x16x32_bf16 v[58:61], v[142:145], v[202:205], v[58:61]
	v_mfma_f32_16x16x32_bf16 v[38:41], v[134:137], v[210:213], v[38:41]
	v_mfma_f32_16x16x32_bf16 v[34:37], v[142:145], v[210:213], v[34:37]
	v_mfma_f32_16x16x32_bf16 v[22:25], v[134:137], v[218:221], v[22:25]
	v_mfma_f32_16x16x32_bf16 v[18:21], v[142:145], v[218:221], v[18:21]
	v_mfma_f32_16x16x32_bf16 v[6:9], v[134:137], v[226:229], v[6:9]
	v_mfma_f32_16x16x32_bf16 v[2:5], v[142:145], v[226:229], v[2:5]
	s_setprio 0
	s_setprio 1
	v_mfma_f32_16x16x32_bf16 v[78:81], v[168:171], v[198:201], v[78:81]
	v_mfma_f32_16x16x32_bf16 v[74:77], v[176:179], v[198:201], v[74:77]
	v_mfma_f32_16x16x32_bf16 v[46:49], v[168:171], v[206:209], v[46:49]
	v_mfma_f32_16x16x32_bf16 v[42:45], v[176:179], v[206:209], v[42:45]
	v_mfma_f32_16x16x32_bf16 v[30:33], v[168:171], v[214:217], v[30:33]
	v_mfma_f32_16x16x32_bf16 v[26:29], v[176:179], v[214:217], v[26:29]
	v_mfma_f32_16x16x32_bf16 v[14:17], v[168:171], v[222:225], v[14:17]
	v_mfma_f32_16x16x32_bf16 v[10:13], v[176:179], v[222:225], v[10:13]
	v_mfma_f32_16x16x32_bf16 v[78:81], v[172:175], v[202:205], v[78:81]
	v_mfma_f32_16x16x32_bf16 v[74:77], v[180:183], v[202:205], v[74:77]
	v_mfma_f32_16x16x32_bf16 v[46:49], v[172:175], v[210:213], v[46:49]
	v_mfma_f32_16x16x32_bf16 v[42:45], v[180:183], v[210:213], v[42:45]
	v_mfma_f32_16x16x32_bf16 v[30:33], v[172:175], v[218:221], v[30:33]
	v_mfma_f32_16x16x32_bf16 v[26:29], v[180:183], v[218:221], v[26:29]
	v_mfma_f32_16x16x32_bf16 v[14:17], v[172:175], v[226:229], v[14:17]
	v_mfma_f32_16x16x32_bf16 v[10:13], v[180:183], v[226:229], v[10:13]
	s_barrier
	s_setprio 0
	s_add_u32 s40, s40, 0x100
	s_addc_u32 s49, s49, 0
	s_add_u32 s10, s10, 0x100
	s_addc_u32 s11, s11, 0
	s_cmp_ge_u32 vcc_lo, s19
	s_mov_b32 s38, vcc_lo
	s_cbranch_scc0 .LBB0_262

.LBB0_1692:
	s_ashr_i32 s13, s12, 31
	s_lshl_b64 s[16:17], s[12:13], 18
	s_add_u32 s16, s45, s16
	s_addc_u32 s17, s44, s17
	s_and_b64 s[26:27], s[26:27], exec
	s_cselect_b32 s13, s17, s25
	s_cselect_b32 s15, s16, s24
	s_add_u32 s34, s24, 0x100
	s_addc_u32 s35, s25, 0
	s_add_u32 s22, s22, 0x80080
	s_addc_u32 s23, s23, 0
	s_mov_b32 s36, -2
	ds_read_b128 v[128:131], v169
	ds_read_b128 v[132:135], v169 offset:1024
	ds_read_b128 v[136:139], v169 offset:2048
	ds_read_b128 v[140:143], v169 offset:3072
	ds_read_b128 v[158:161], v170
	ds_read_b128 v[162:165], v170 offset:1024
	ds_read_b128 v[172:175], v170 offset:2048
	ds_read_b128 v[176:179], v170 offset:3072
	s_add_u32 s24, s22, 0xfff80080
	s_addc_u32 s25, s23, -1
	s_cmp_eq_u32 s36, 4
	s_cselect_b32 s27, s5, s25
	s_cselect_b32 s26, s4, s24
	s_cselect_b32 s25, s13, s35
	s_cselect_b32 s24, s15, s34
	s_add_i32 m0, s94, 0xc000
	ds_read_b128 v[180:183], v171
	ds_read_b128 v[184:187], v171 offset:1024
	ds_read_b128 v[188:191], v171 offset:2048
	ds_read_b128 v[192:195], v171 offset:3072
	ds_read_b128 v[196:199], v171 offset:4096
	ds_read_b128 v[200:203], v171 offset:5120
	ds_read_b128 v[204:207], v171 offset:6144
	ds_read_b128 v[208:211], v171 offset:7168
	global_load_lds_dwordx4 v152, s[22:23]
	s_add_i32 m0, s94, 0xe000
	s_nop 0
	global_load_lds_dwordx4 v154, s[22:23]
	s_waitcnt vmcnt(8)
	s_waitcnt lgkmcnt(0)
	s_setprio 1
	s_barrier
	v_mfma_f32_16x16x32_bf16 v[80:83], v[128:131], v[180:183], 0
	v_mfma_f32_16x16x32_bf16 v[92:95], v[136:139], v[180:183], 0
	v_mfma_f32_16x16x32_bf16 v[84:87], v[128:131], v[188:191], 0
	v_mfma_f32_16x16x32_bf16 v[96:99], v[136:139], v[188:191], 0
	v_mfma_f32_16x16x32_bf16 v[88:91], v[128:131], v[196:199], 0
	v_mfma_f32_16x16x32_bf16 v[100:103], v[136:139], v[196:199], 0
	v_mfma_f32_16x16x32_bf16 v[72:75], v[128:131], v[204:207], 0
	v_mfma_f32_16x16x32_bf16 v[76:79], v[136:139], v[204:207], 0
	v_mfma_f32_16x16x32_bf16 v[80:83], v[132:135], v[184:187], v[80:83]
	v_mfma_f32_16x16x32_bf16 v[92:95], v[140:143], v[184:187], v[92:95]
	v_mfma_f32_16x16x32_bf16 v[84:87], v[132:135], v[192:195], v[84:87]
	v_mfma_f32_16x16x32_bf16 v[96:99], v[140:143], v[192:195], v[96:99]
	v_mfma_f32_16x16x32_bf16 v[88:91], v[132:135], v[200:203], v[88:91]
	v_mfma_f32_16x16x32_bf16 v[100:103], v[140:143], v[200:203], v[100:103]
	v_mfma_f32_16x16x32_bf16 v[72:75], v[132:135], v[208:211], v[72:75]
	v_mfma_f32_16x16x32_bf16 v[76:79], v[140:143], v[208:211], v[76:79]
	s_setprio 0
	s_setprio 1
	v_mfma_f32_16x16x32_bf16 v[104:107], v[158:161], v[180:183], 0
	v_mfma_f32_16x16x32_bf16 v[116:119], v[172:175], v[180:183], 0
	v_mfma_f32_16x16x32_bf16 v[108:111], v[158:161], v[188:191], 0
	v_mfma_f32_16x16x32_bf16 v[120:123], v[172:175], v[188:191], 0
	v_mfma_f32_16x16x32_bf16 v[112:115], v[158:161], v[196:199], 0
	v_mfma_f32_16x16x32_bf16 v[124:127], v[172:175], v[196:199], 0
	v_mfma_f32_16x16x32_bf16 v[68:71], v[158:161], v[204:207], 0
	v_mfma_f32_16x16x32_bf16 v[64:67], v[172:175], v[204:207], 0
	v_mfma_f32_16x16x32_bf16 v[104:107], v[162:165], v[184:187], v[104:107]
	v_mfma_f32_16x16x32_bf16 v[116:119], v[176:179], v[184:187], v[116:119]
	v_mfma_f32_16x16x32_bf16 v[108:111], v[162:165], v[192:195], v[108:111]
	v_mfma_f32_16x16x32_bf16 v[120:123], v[176:179], v[192:195], v[120:123]
	v_mfma_f32_16x16x32_bf16 v[112:115], v[162:165], v[200:203], v[112:115]
	v_mfma_f32_16x16x32_bf16 v[124:127], v[176:179], v[200:203], v[124:127]
	v_mfma_f32_16x16x32_bf16 v[68:71], v[162:165], v[208:211], v[68:71]
	v_mfma_f32_16x16x32_bf16 v[64:67], v[176:179], v[208:211], v[64:67]
	s_barrier
	s_setprio 0
	s_add_i32 s37, s31, s97
	v_lshl_add_u64 v[212:213], s[24:25], 0, v[148:149]
	s_mov_b32 m0, s37
	ds_read_b128 v[180:183], v171 offset:16384
	ds_read_b128 v[184:187], v171 offset:17408
	ds_read_b128 v[188:191], v171 offset:18432
	ds_read_b128 v[192:195], v171 offset:19456
	ds_read_b128 v[196:199], v171 offset:20480
	ds_read_b128 v[200:203], v171 offset:21504
	ds_read_b128 v[204:207], v171 offset:22528
	ds_read_b128 v[208:211], v171 offset:23552
	global_load_lds_dwordx4 v[212:213], off
	s_add_i32 m0, s37, 0x2000
	s_add_u32 s38, s24, 0x20000
	v_lshl_add_u64 v[214:215], s[24:25], 0, v[144:145]
	s_addc_u32 s39, s25, 0
	s_add_i32 s37, s33, s97
	global_load_lds_dwordx4 v[214:215], off
	s_mov_b32 m0, s37
	v_lshl_add_u64 v[218:219], s[26:27], 0, v[146:147]
	global_load_lds_dwordx4 v148, s[38:39]
	s_add_i32 m0, s37, 0x2000
	s_nop 0
	global_load_lds_dwordx4 v144, s[38:39]
	v_lshl_add_u64 v[216:217], s[26:27], 0, v[150:151]
	s_mov_b32 m0, s94
	s_nop 0
	global_load_lds_dwordx4 v[216:217], off
	s_mov_b32 m0, s3
	s_nop 0
	global_load_lds_dwordx4 v[218:219], off
	s_waitcnt vmcnt(8)
	s_waitcnt lgkmcnt(0)
	s_setprio 1
	s_barrier
	v_mfma_f32_16x16x32_bf16 v[48:51], v[128:131], v[180:183], 0
	v_mfma_f32_16x16x32_bf16 v[52:55], v[136:139], v[180:183], 0
	v_mfma_f32_16x16x32_bf16 v[32:35], v[128:131], v[188:191], 0
	v_mfma_f32_16x16x32_bf16 v[36:39], v[136:139], v[188:191], 0
	v_mfma_f32_16x16x32_bf16 v[16:19], v[128:131], v[196:199], 0
	v_mfma_f32_16x16x32_bf16 v[20:23], v[136:139], v[196:199], 0
	v_mfma_f32_16x16x32_bf16 v[0:3], v[128:131], v[204:207], 0
	v_mfma_f32_16x16x32_bf16 v[4:7], v[136:139], v[204:207], 0
	v_mfma_f32_16x16x32_bf16 v[48:51], v[132:135], v[184:187], v[48:51]
	v_mfma_f32_16x16x32_bf16 v[52:55], v[140:143], v[184:187], v[52:55]
	v_mfma_f32_16x16x32_bf16 v[32:35], v[132:135], v[192:195], v[32:35]
	v_mfma_f32_16x16x32_bf16 v[36:39], v[140:143], v[192:195], v[36:39]
	v_mfma_f32_16x16x32_bf16 v[16:19], v[132:135], v[200:203], v[16:19]
	v_mfma_f32_16x16x32_bf16 v[20:23], v[140:143], v[200:203], v[20:23]
	v_mfma_f32_16x16x32_bf16 v[0:3], v[132:135], v[208:211], v[0:3]
	v_mfma_f32_16x16x32_bf16 v[4:7], v[140:143], v[208:211], v[4:7]
	s_setprio 0
	s_setprio 1
	v_mfma_f32_16x16x32_bf16 v[56:59], v[158:161], v[180:183], 0
	v_mfma_f32_16x16x32_bf16 v[60:63], v[172:175], v[180:183], 0
	v_mfma_f32_16x16x32_bf16 v[40:43], v[158:161], v[188:191], 0
	v_mfma_f32_16x16x32_bf16 v[44:47], v[172:175], v[188:191], 0
	v_mfma_f32_16x16x32_bf16 v[24:27], v[158:161], v[196:199], 0
	v_mfma_f32_16x16x32_bf16 v[28:31], v[172:175], v[196:199], 0
	v_mfma_f32_16x16x32_bf16 v[8:11], v[158:161], v[204:207], 0
	v_mfma_f32_16x16x32_bf16 v[12:15], v[172:175], v[204:207], 0
	v_mfma_f32_16x16x32_bf16 v[56:59], v[162:165], v[184:187], v[56:59]
	v_mfma_f32_16x16x32_bf16 v[60:63], v[176:179], v[184:187], v[60:63]
	v_mfma_f32_16x16x32_bf16 v[40:43], v[162:165], v[192:195], v[40:43]
	v_mfma_f32_16x16x32_bf16 v[44:47], v[176:179], v[192:195], v[44:47]
	v_mfma_f32_16x16x32_bf16 v[24:27], v[162:165], v[200:203], v[24:27]
	v_mfma_f32_16x16x32_bf16 v[28:31], v[176:179], v[200:203], v[28:31]
	v_mfma_f32_16x16x32_bf16 v[8:11], v[162:165], v[208:211], v[8:11]
	v_mfma_f32_16x16x32_bf16 v[12:15], v[176:179], v[208:211], v[12:15]
	s_barrier
	s_setprio 0
	s_add_i32 s37, 0, 0x18000
	s_add_i32 s38, 0, 0x1c000
	v_add_u32_e32 v140, s37, v167
	v_add_u32_e32 v176, s38, v167
	ds_read_b128 v[128:131], v140
	ds_read_b128 v[132:135], v140 offset:1024
	ds_read_b128 v[136:139], v140 offset:2048
	ds_read_b128 v[140:143], v140 offset:3072
	ds_read_b128 v[158:161], v176
	ds_read_b128 v[162:165], v176 offset:1024
	ds_read_b128 v[172:175], v176 offset:2048
	ds_read_b128 v[176:179], v176 offset:3072
	s_add_u32 s26, s26, 0x80000
	s_addc_u32 s27, s27, 0
	s_mov_b32 m0, s7
	ds_read_b128 v[180:183], v171 offset:32768
	ds_read_b128 v[184:187], v171 offset:33792
	ds_read_b128 v[188:191], v171 offset:34816
	ds_read_b128 v[192:195], v171 offset:35840
	ds_read_b128 v[196:199], v171 offset:36864
	ds_read_b128 v[200:203], v171 offset:37888
	ds_read_b128 v[204:207], v171 offset:38912
	ds_read_b128 v[208:211], v171 offset:39936
	global_load_lds_dwordx4 v150, s[26:27]
	s_mov_b32 m0, s19
	s_nop 0
	global_load_lds_dwordx4 v146, s[26:27]
	s_waitcnt vmcnt(8)
	s_waitcnt lgkmcnt(0)
	s_setprio 1
	s_barrier
	v_mfma_f32_16x16x32_bf16 v[80:83], v[128:131], v[180:183], v[80:83]
	v_mfma_f32_16x16x32_bf16 v[92:95], v[136:139], v[180:183], v[92:95]
	v_mfma_f32_16x16x32_bf16 v[84:87], v[128:131], v[188:191], v[84:87]
	v_mfma_f32_16x16x32_bf16 v[96:99], v[136:139], v[188:191], v[96:99]
	v_mfma_f32_16x16x32_bf16 v[88:91], v[128:131], v[196:199], v[88:91]
	v_mfma_f32_16x16x32_bf16 v[100:103], v[136:139], v[196:199], v[100:103]
	v_mfma_f32_16x16x32_bf16 v[72:75], v[128:131], v[204:207], v[72:75]
	v_mfma_f32_16x16x32_bf16 v[76:79], v[136:139], v[204:207], v[76:79]
	v_mfma_f32_16x16x32_bf16 v[80:83], v[132:135], v[184:187], v[80:83]
	v_mfma_f32_16x16x32_bf16 v[92:95], v[140:143], v[184:187], v[92:95]
	v_mfma_f32_16x16x32_bf16 v[84:87], v[132:135], v[192:195], v[84:87]
	v_mfma_f32_16x16x32_bf16 v[96:99], v[140:143], v[192:195], v[96:99]
	v_mfma_f32_16x16x32_bf16 v[88:91], v[132:135], v[200:203], v[88:91]
	v_mfma_f32_16x16x32_bf16 v[100:103], v[140:143], v[200:203], v[100:103]
	v_mfma_f32_16x16x32_bf16 v[72:75], v[132:135], v[208:211], v[72:75]
	v_mfma_f32_16x16x32_bf16 v[76:79], v[140:143], v[208:211], v[76:79]
	s_setprio 0
	s_setprio 1
	v_mfma_f32_16x16x32_bf16 v[104:107], v[158:161], v[180:183], v[104:107]
	v_mfma_f32_16x16x32_bf16 v[116:119], v[172:175], v[180:183], v[116:119]
	v_mfma_f32_16x16x32_bf16 v[108:111], v[158:161], v[188:191], v[108:111]
	v_mfma_f32_16x16x32_bf16 v[120:123], v[172:175], v[188:191], v[120:123]
	v_mfma_f32_16x16x32_bf16 v[112:115], v[158:161], v[196:199], v[112:115]
	v_mfma_f32_16x16x32_bf16 v[124:127], v[172:175], v[196:199], v[124:127]
	v_mfma_f32_16x16x32_bf16 v[68:71], v[158:161], v[204:207], v[68:71]
	v_mfma_f32_16x16x32_bf16 v[64:67], v[172:175], v[204:207], v[64:67]
	v_mfma_f32_16x16x32_bf16 v[104:107], v[162:165], v[184:187], v[104:107]
	v_mfma_f32_16x16x32_bf16 v[116:119], v[176:179], v[184:187], v[116:119]
	v_mfma_f32_16x16x32_bf16 v[108:111], v[162:165], v[192:195], v[108:111]
	v_mfma_f32_16x16x32_bf16 v[120:123], v[176:179], v[192:195], v[120:123]
	v_mfma_f32_16x16x32_bf16 v[112:115], v[162:165], v[200:203], v[112:115]
	v_mfma_f32_16x16x32_bf16 v[124:127], v[176:179], v[200:203], v[124:127]
	v_mfma_f32_16x16x32_bf16 v[68:71], v[162:165], v[208:211], v[68:71]
	v_mfma_f32_16x16x32_bf16 v[64:67], v[176:179], v[208:211], v[64:67]
	s_barrier
	s_setprio 0
	s_add_i32 s26, s37, s97
	v_lshl_add_u64 v[212:213], v[212:213], 0, s[0:1]
	s_mov_b32 m0, s26
	ds_read_b128 v[180:183], v171 offset:49152
	ds_read_b128 v[184:187], v171 offset:50176
	ds_read_b128 v[188:191], v171 offset:51200
	ds_read_b128 v[192:195], v171 offset:52224
	ds_read_b128 v[196:199], v171 offset:53248
	ds_read_b128 v[200:203], v171 offset:54272
	ds_read_b128 v[204:207], v171 offset:55296
	ds_read_b128 v[208:211], v171 offset:56320
	global_load_lds_dwordx4 v[212:213], off
	s_add_i32 m0, s26, 0x2000
	s_add_u32 s24, s24, 0x20080
	v_lshl_add_u64 v[212:213], v[214:215], 0, s[0:1]
	s_addc_u32 s25, s25, 0
	s_add_i32 s26, s38, s97
	global_load_lds_dwordx4 v[212:213], off
	s_mov_b32 m0, s26
	s_nop 0
	global_load_lds_dwordx4 v148, s[24:25]
	s_add_i32 m0, s26, 0x2000
	s_nop 0
	global_load_lds_dwordx4 v144, s[24:25]
	v_lshl_add_u64 v[212:213], v[216:217], 0, s[0:1]
	s_mov_b32 m0, s28
	s_nop 0
	global_load_lds_dwordx4 v[212:213], off
	v_lshl_add_u64 v[212:213], v[218:219], 0, s[0:1]
	s_mov_b32 m0, s29
	s_nop 0
	global_load_lds_dwordx4 v[212:213], off
	s_waitcnt vmcnt(8)
	s_waitcnt lgkmcnt(0)
	s_setprio 1
	s_barrier
	v_mfma_f32_16x16x32_bf16 v[48:51], v[128:131], v[180:183], v[48:51]
	v_mfma_f32_16x16x32_bf16 v[52:55], v[136:139], v[180:183], v[52:55]
	v_mfma_f32_16x16x32_bf16 v[32:35], v[128:131], v[188:191], v[32:35]
	v_mfma_f32_16x16x32_bf16 v[36:39], v[136:139], v[188:191], v[36:39]
	v_mfma_f32_16x16x32_bf16 v[16:19], v[128:131], v[196:199], v[16:19]
	v_mfma_f32_16x16x32_bf16 v[20:23], v[136:139], v[196:199], v[20:23]
	v_mfma_f32_16x16x32_bf16 v[0:3], v[128:131], v[204:207], v[0:3]
	v_mfma_f32_16x16x32_bf16 v[4:7], v[136:139], v[204:207], v[4:7]
	v_mfma_f32_16x16x32_bf16 v[48:51], v[132:135], v[184:187], v[48:51]
	v_mfma_f32_16x16x32_bf16 v[52:55], v[140:143], v[184:187], v[52:55]
	v_mfma_f32_16x16x32_bf16 v[32:35], v[132:135], v[192:195], v[32:35]
	v_mfma_f32_16x16x32_bf16 v[36:39], v[140:143], v[192:195], v[36:39]
	v_mfma_f32_16x16x32_bf16 v[16:19], v[132:135], v[200:203], v[16:19]
	v_mfma_f32_16x16x32_bf16 v[20:23], v[140:143], v[200:203], v[20:23]
	v_mfma_f32_16x16x32_bf16 v[0:3], v[132:135], v[208:211], v[0:3]
	v_mfma_f32_16x16x32_bf16 v[4:7], v[140:143], v[208:211], v[4:7]
	s_setprio 0
	s_setprio 1
	v_mfma_f32_16x16x32_bf16 v[56:59], v[158:161], v[180:183], v[56:59]
	v_mfma_f32_16x16x32_bf16 v[60:63], v[172:175], v[180:183], v[60:63]
	v_mfma_f32_16x16x32_bf16 v[40:43], v[158:161], v[188:191], v[40:43]
	v_mfma_f32_16x16x32_bf16 v[44:47], v[172:175], v[188:191], v[44:47]
	v_mfma_f32_16x16x32_bf16 v[24:27], v[158:161], v[196:199], v[24:27]
	v_mfma_f32_16x16x32_bf16 v[28:31], v[172:175], v[196:199], v[28:31]
	v_mfma_f32_16x16x32_bf16 v[8:11], v[158:161], v[204:207], v[8:11]
	v_mfma_f32_16x16x32_bf16 v[12:15], v[172:175], v[204:207], v[12:15]
	v_mfma_f32_16x16x32_bf16 v[56:59], v[162:165], v[184:187], v[56:59]
	v_mfma_f32_16x16x32_bf16 v[60:63], v[176:179], v[184:187], v[60:63]
	v_mfma_f32_16x16x32_bf16 v[40:43], v[162:165], v[192:195], v[40:43]
	v_mfma_f32_16x16x32_bf16 v[44:47], v[176:179], v[192:195], v[44:47]
	v_mfma_f32_16x16x32_bf16 v[24:27], v[162:165], v[200:203], v[24:27]
	v_mfma_f32_16x16x32_bf16 v[28:31], v[176:179], v[200:203], v[28:31]
	v_mfma_f32_16x16x32_bf16 v[8:11], v[162:165], v[208:211], v[8:11]
	v_mfma_f32_16x16x32_bf16 v[12:15], v[176:179], v[208:211], v[12:15]
	s_barrier
	s_setprio 0
	s_add_i32 s36, s36, 2
	s_add_u32 s34, s34, 0x100
	s_addc_u32 s35, s35, 0
	s_add_u32 s22, s22, 0x100
	s_addc_u32 s23, s23, 0
	s_cmp_gt_u32 s36, 5
	s_cbranch_scc1 .Lpeel_done_1
.LBB0_1693:
	ds_read_b128 v[128:131], v169
	ds_read_b128 v[132:135], v169 offset:1024
	ds_read_b128 v[136:139], v169 offset:2048
	ds_read_b128 v[140:143], v169 offset:3072
	ds_read_b128 v[158:161], v170
	ds_read_b128 v[162:165], v170 offset:1024
	ds_read_b128 v[172:175], v170 offset:2048
	ds_read_b128 v[176:179], v170 offset:3072
	s_add_u32 s24, s22, 0xfff80080
	s_addc_u32 s25, s23, -1
	s_cmp_eq_u32 s36, 4
	s_cselect_b32 s27, s5, s25
	s_cselect_b32 s26, s4, s24
	s_cselect_b32 s25, s13, s35
	s_cselect_b32 s24, s15, s34
	s_add_i32 m0, s94, 0xc000
	ds_read_b128 v[180:183], v171
	ds_read_b128 v[184:187], v171 offset:1024
	ds_read_b128 v[188:191], v171 offset:2048
	ds_read_b128 v[192:195], v171 offset:3072
	ds_read_b128 v[196:199], v171 offset:4096
	ds_read_b128 v[200:203], v171 offset:5120
	ds_read_b128 v[204:207], v171 offset:6144
	ds_read_b128 v[208:211], v171 offset:7168
	global_load_lds_dwordx4 v152, s[22:23]
	s_add_i32 m0, s94, 0xe000
	s_nop 0
	global_load_lds_dwordx4 v154, s[22:23]
	s_waitcnt vmcnt(8)
	s_waitcnt lgkmcnt(0)
	s_setprio 1
	s_barrier
	v_mfma_f32_16x16x32_bf16 v[80:83], v[128:131], v[180:183], v[80:83]
	v_mfma_f32_16x16x32_bf16 v[92:95], v[136:139], v[180:183], v[92:95]
	v_mfma_f32_16x16x32_bf16 v[84:87], v[128:131], v[188:191], v[84:87]
	v_mfma_f32_16x16x32_bf16 v[96:99], v[136:139], v[188:191], v[96:99]
	v_mfma_f32_16x16x32_bf16 v[88:91], v[128:131], v[196:199], v[88:91]
	v_mfma_f32_16x16x32_bf16 v[100:103], v[136:139], v[196:199], v[100:103]
	v_mfma_f32_16x16x32_bf16 v[72:75], v[128:131], v[204:207], v[72:75]
	v_mfma_f32_16x16x32_bf16 v[76:79], v[136:139], v[204:207], v[76:79]
	v_mfma_f32_16x16x32_bf16 v[80:83], v[132:135], v[184:187], v[80:83]
	v_mfma_f32_16x16x32_bf16 v[92:95], v[140:143], v[184:187], v[92:95]
	v_mfma_f32_16x16x32_bf16 v[84:87], v[132:135], v[192:195], v[84:87]
	v_mfma_f32_16x16x32_bf16 v[96:99], v[140:143], v[192:195], v[96:99]
	v_mfma_f32_16x16x32_bf16 v[88:91], v[132:135], v[200:203], v[88:91]
	v_mfma_f32_16x16x32_bf16 v[100:103], v[140:143], v[200:203], v[100:103]
	v_mfma_f32_16x16x32_bf16 v[72:75], v[132:135], v[208:211], v[72:75]
	v_mfma_f32_16x16x32_bf16 v[76:79], v[140:143], v[208:211], v[76:79]
	s_setprio 0
	s_setprio 1
	v_mfma_f32_16x16x32_bf16 v[104:107], v[158:161], v[180:183], v[104:107]
	v_mfma_f32_16x16x32_bf16 v[116:119], v[172:175], v[180:183], v[116:119]
	v_mfma_f32_16x16x32_bf16 v[108:111], v[158:161], v[188:191], v[108:111]
	v_mfma_f32_16x16x32_bf16 v[120:123], v[172:175], v[188:191], v[120:123]
	v_mfma_f32_16x16x32_bf16 v[112:115], v[158:161], v[196:199], v[112:115]
	v_mfma_f32_16x16x32_bf16 v[124:127], v[172:175], v[196:199], v[124:127]
	v_mfma_f32_16x16x32_bf16 v[68:71], v[158:161], v[204:207], v[68:71]
	v_mfma_f32_16x16x32_bf16 v[64:67], v[172:175], v[204:207], v[64:67]
	v_mfma_f32_16x16x32_bf16 v[104:107], v[162:165], v[184:187], v[104:107]
	v_mfma_f32_16x16x32_bf16 v[116:119], v[176:179], v[184:187], v[116:119]
	v_mfma_f32_16x16x32_bf16 v[108:111], v[162:165], v[192:195], v[108:111]
	v_mfma_f32_16x16x32_bf16 v[120:123], v[176:179], v[192:195], v[120:123]
	v_mfma_f32_16x16x32_bf16 v[112:115], v[162:165], v[200:203], v[112:115]
	v_mfma_f32_16x16x32_bf16 v[124:127], v[176:179], v[200:203], v[124:127]
	v_mfma_f32_16x16x32_bf16 v[68:71], v[162:165], v[208:211], v[68:71]
	v_mfma_f32_16x16x32_bf16 v[64:67], v[176:179], v[208:211], v[64:67]
	s_barrier
	s_setprio 0
	s_add_i32 s37, s31, s97
	v_lshl_add_u64 v[212:213], s[24:25], 0, v[148:149]
	s_mov_b32 m0, s37
	ds_read_b128 v[180:183], v171 offset:16384
	ds_read_b128 v[184:187], v171 offset:17408
	ds_read_b128 v[188:191], v171 offset:18432
	ds_read_b128 v[192:195], v171 offset:19456
	ds_read_b128 v[196:199], v171 offset:20480
	ds_read_b128 v[200:203], v171 offset:21504
	ds_read_b128 v[204:207], v171 offset:22528
	ds_read_b128 v[208:211], v171 offset:23552
	global_load_lds_dwordx4 v[212:213], off
	s_add_i32 m0, s37, 0x2000
	s_add_u32 s38, s24, 0x20000
	v_lshl_add_u64 v[214:215], s[24:25], 0, v[144:145]
	s_addc_u32 s39, s25, 0
	s_add_i32 s37, s33, s97
	global_load_lds_dwordx4 v[214:215], off
	s_mov_b32 m0, s37
	v_lshl_add_u64 v[218:219], s[26:27], 0, v[146:147]
	global_load_lds_dwordx4 v148, s[38:39]
	s_add_i32 m0, s37, 0x2000
	s_nop 0
	global_load_lds_dwordx4 v144, s[38:39]
	v_lshl_add_u64 v[216:217], s[26:27], 0, v[150:151]
	s_mov_b32 m0, s94
	s_nop 0
	global_load_lds_dwordx4 v[216:217], off
	s_mov_b32 m0, s3
	s_nop 0
	global_load_lds_dwordx4 v[218:219], off
	s_waitcnt vmcnt(8)
	s_waitcnt lgkmcnt(0)
	s_setprio 1
	s_barrier
	v_mfma_f32_16x16x32_bf16 v[48:51], v[128:131], v[180:183], v[48:51]
	v_mfma_f32_16x16x32_bf16 v[52:55], v[136:139], v[180:183], v[52:55]
	v_mfma_f32_16x16x32_bf16 v[32:35], v[128:131], v[188:191], v[32:35]
	v_mfma_f32_16x16x32_bf16 v[36:39], v[136:139], v[188:191], v[36:39]
	v_mfma_f32_16x16x32_bf16 v[16:19], v[128:131], v[196:199], v[16:19]
	v_mfma_f32_16x16x32_bf16 v[20:23], v[136:139], v[196:199], v[20:23]
	v_mfma_f32_16x16x32_bf16 v[0:3], v[128:131], v[204:207], v[0:3]
	v_mfma_f32_16x16x32_bf16 v[4:7], v[136:139], v[204:207], v[4:7]
	v_mfma_f32_16x16x32_bf16 v[48:51], v[132:135], v[184:187], v[48:51]
	v_mfma_f32_16x16x32_bf16 v[52:55], v[140:143], v[184:187], v[52:55]
	v_mfma_f32_16x16x32_bf16 v[32:35], v[132:135], v[192:195], v[32:35]
	v_mfma_f32_16x16x32_bf16 v[36:39], v[140:143], v[192:195], v[36:39]
	v_mfma_f32_16x16x32_bf16 v[16:19], v[132:135], v[200:203], v[16:19]
	v_mfma_f32_16x16x32_bf16 v[20:23], v[140:143], v[200:203], v[20:23]
	v_mfma_f32_16x16x32_bf16 v[0:3], v[132:135], v[208:211], v[0:3]
	v_mfma_f32_16x16x32_bf16 v[4:7], v[140:143], v[208:211], v[4:7]
	s_setprio 0
	s_setprio 1
	v_mfma_f32_16x16x32_bf16 v[56:59], v[158:161], v[180:183], v[56:59]
	v_mfma_f32_16x16x32_bf16 v[60:63], v[172:175], v[180:183], v[60:63]
	v_mfma_f32_16x16x32_bf16 v[40:43], v[158:161], v[188:191], v[40:43]
	v_mfma_f32_16x16x32_bf16 v[44:47], v[172:175], v[188:191], v[44:47]
	v_mfma_f32_16x16x32_bf16 v[24:27], v[158:161], v[196:199], v[24:27]
	v_mfma_f32_16x16x32_bf16 v[28:31], v[172:175], v[196:199], v[28:31]
	v_mfma_f32_16x16x32_bf16 v[8:11], v[158:161], v[204:207], v[8:11]
	v_mfma_f32_16x16x32_bf16 v[12:15], v[172:175], v[204:207], v[12:15]
	v_mfma_f32_16x16x32_bf16 v[56:59], v[162:165], v[184:187], v[56:59]
	v_mfma_f32_16x16x32_bf16 v[60:63], v[176:179], v[184:187], v[60:63]
	v_mfma_f32_16x16x32_bf16 v[40:43], v[162:165], v[192:195], v[40:43]
	v_mfma_f32_16x16x32_bf16 v[44:47], v[176:179], v[192:195], v[44:47]
	v_mfma_f32_16x16x32_bf16 v[24:27], v[162:165], v[200:203], v[24:27]
	v_mfma_f32_16x16x32_bf16 v[28:31], v[176:179], v[200:203], v[28:31]
	v_mfma_f32_16x16x32_bf16 v[8:11], v[162:165], v[208:211], v[8:11]
	v_mfma_f32_16x16x32_bf16 v[12:15], v[176:179], v[208:211], v[12:15]
	s_barrier
	s_setprio 0
	s_add_i32 s37, 0, 0x18000
	s_add_i32 s38, 0, 0x1c000
	v_add_u32_e32 v140, s37, v167
	v_add_u32_e32 v176, s38, v167
	ds_read_b128 v[128:131], v140
	ds_read_b128 v[132:135], v140 offset:1024
	ds_read_b128 v[136:139], v140 offset:2048
	ds_read_b128 v[140:143], v140 offset:3072
	ds_read_b128 v[158:161], v176
	ds_read_b128 v[162:165], v176 offset:1024
	ds_read_b128 v[172:175], v176 offset:2048
	ds_read_b128 v[176:179], v176 offset:3072
	s_add_u32 s26, s26, 0x80000
	s_addc_u32 s27, s27, 0
	s_mov_b32 m0, s7
	ds_read_b128 v[180:183], v171 offset:32768
	ds_read_b128 v[184:187], v171 offset:33792
	ds_read_b128 v[188:191], v171 offset:34816
	ds_read_b128 v[192:195], v171 offset:35840
	ds_read_b128 v[196:199], v171 offset:36864
	ds_read_b128 v[200:203], v171 offset:37888
	ds_read_b128 v[204:207], v171 offset:38912
	ds_read_b128 v[208:211], v171 offset:39936
	global_load_lds_dwordx4 v150, s[26:27]
	s_mov_b32 m0, s19
	s_nop 0
	global_load_lds_dwordx4 v146, s[26:27]
	s_waitcnt vmcnt(8)
	s_waitcnt lgkmcnt(0)
	s_setprio 1
	s_barrier
	v_mfma_f32_16x16x32_bf16 v[80:83], v[128:131], v[180:183], v[80:83]
	v_mfma_f32_16x16x32_bf16 v[92:95], v[136:139], v[180:183], v[92:95]
	v_mfma_f32_16x16x32_bf16 v[84:87], v[128:131], v[188:191], v[84:87]
	v_mfma_f32_16x16x32_bf16 v[96:99], v[136:139], v[188:191], v[96:99]
	v_mfma_f32_16x16x32_bf16 v[88:91], v[128:131], v[196:199], v[88:91]
	v_mfma_f32_16x16x32_bf16 v[100:103], v[136:139], v[196:199], v[100:103]
	v_mfma_f32_16x16x32_bf16 v[72:75], v[128:131], v[204:207], v[72:75]
	v_mfma_f32_16x16x32_bf16 v[76:79], v[136:139], v[204:207], v[76:79]
	v_mfma_f32_16x16x32_bf16 v[80:83], v[132:135], v[184:187], v[80:83]
	v_mfma_f32_16x16x32_bf16 v[92:95], v[140:143], v[184:187], v[92:95]
	v_mfma_f32_16x16x32_bf16 v[84:87], v[132:135], v[192:195], v[84:87]
	v_mfma_f32_16x16x32_bf16 v[96:99], v[140:143], v[192:195], v[96:99]
	v_mfma_f32_16x16x32_bf16 v[88:91], v[132:135], v[200:203], v[88:91]
	v_mfma_f32_16x16x32_bf16 v[100:103], v[140:143], v[200:203], v[100:103]
	v_mfma_f32_16x16x32_bf16 v[72:75], v[132:135], v[208:211], v[72:75]
	v_mfma_f32_16x16x32_bf16 v[76:79], v[140:143], v[208:211], v[76:79]
	s_setprio 0
	s_setprio 1
	v_mfma_f32_16x16x32_bf16 v[104:107], v[158:161], v[180:183], v[104:107]
	v_mfma_f32_16x16x32_bf16 v[116:119], v[172:175], v[180:183], v[116:119]
	v_mfma_f32_16x16x32_bf16 v[108:111], v[158:161], v[188:191], v[108:111]
	v_mfma_f32_16x16x32_bf16 v[120:123], v[172:175], v[188:191], v[120:123]
	v_mfma_f32_16x16x32_bf16 v[112:115], v[158:161], v[196:199], v[112:115]
	v_mfma_f32_16x16x32_bf16 v[124:127], v[172:175], v[196:199], v[124:127]
	v_mfma_f32_16x16x32_bf16 v[68:71], v[158:161], v[204:207], v[68:71]
	v_mfma_f32_16x16x32_bf16 v[64:67], v[172:175], v[204:207], v[64:67]
	v_mfma_f32_16x16x32_bf16 v[104:107], v[162:165], v[184:187], v[104:107]
	v_mfma_f32_16x16x32_bf16 v[116:119], v[176:179], v[184:187], v[116:119]
	v_mfma_f32_16x16x32_bf16 v[108:111], v[162:165], v[192:195], v[108:111]
	v_mfma_f32_16x16x32_bf16 v[120:123], v[176:179], v[192:195], v[120:123]
	v_mfma_f32_16x16x32_bf16 v[112:115], v[162:165], v[200:203], v[112:115]
	v_mfma_f32_16x16x32_bf16 v[124:127], v[176:179], v[200:203], v[124:127]
	v_mfma_f32_16x16x32_bf16 v[68:71], v[162:165], v[208:211], v[68:71]
	v_mfma_f32_16x16x32_bf16 v[64:67], v[176:179], v[208:211], v[64:67]
	s_barrier
	s_setprio 0
	s_add_i32 s26, s37, s97
	v_lshl_add_u64 v[212:213], v[212:213], 0, s[0:1]
	s_mov_b32 m0, s26
	ds_read_b128 v[180:183], v171 offset:49152
	ds_read_b128 v[184:187], v171 offset:50176
	ds_read_b128 v[188:191], v171 offset:51200
	ds_read_b128 v[192:195], v171 offset:52224
	ds_read_b128 v[196:199], v171 offset:53248
	ds_read_b128 v[200:203], v171 offset:54272
	ds_read_b128 v[204:207], v171 offset:55296
	ds_read_b128 v[208:211], v171 offset:56320
	global_load_lds_dwordx4 v[212:213], off
	s_add_i32 m0, s26, 0x2000
	s_add_u32 s24, s24, 0x20080
	v_lshl_add_u64 v[212:213], v[214:215], 0, s[0:1]
	s_addc_u32 s25, s25, 0
	s_add_i32 s26, s38, s97
	global_load_lds_dwordx4 v[212:213], off
	s_mov_b32 m0, s26
	s_nop 0
	global_load_lds_dwordx4 v148, s[24:25]
	s_add_i32 m0, s26, 0x2000
	s_nop 0
	global_load_lds_dwordx4 v144, s[24:25]
	v_lshl_add_u64 v[212:213], v[216:217], 0, s[0:1]
	s_mov_b32 m0, s28
	s_nop 0
	global_load_lds_dwordx4 v[212:213], off
	v_lshl_add_u64 v[212:213], v[218:219], 0, s[0:1]
	s_mov_b32 m0, s29
	s_nop 0
	global_load_lds_dwordx4 v[212:213], off
	s_waitcnt vmcnt(8)
	s_waitcnt lgkmcnt(0)
	s_setprio 1
	s_barrier
	v_mfma_f32_16x16x32_bf16 v[48:51], v[128:131], v[180:183], v[48:51]
	v_mfma_f32_16x16x32_bf16 v[52:55], v[136:139], v[180:183], v[52:55]
	v_mfma_f32_16x16x32_bf16 v[32:35], v[128:131], v[188:191], v[32:35]
	v_mfma_f32_16x16x32_bf16 v[36:39], v[136:139], v[188:191], v[36:39]
	v_mfma_f32_16x16x32_bf16 v[16:19], v[128:131], v[196:199], v[16:19]
	v_mfma_f32_16x16x32_bf16 v[20:23], v[136:139], v[196:199], v[20:23]
	v_mfma_f32_16x16x32_bf16 v[0:3], v[128:131], v[204:207], v[0:3]
	v_mfma_f32_16x16x32_bf16 v[4:7], v[136:139], v[204:207], v[4:7]
	v_mfma_f32_16x16x32_bf16 v[48:51], v[132:135], v[184:187], v[48:51]
	v_mfma_f32_16x16x32_bf16 v[52:55], v[140:143], v[184:187], v[52:55]
	v_mfma_f32_16x16x32_bf16 v[32:35], v[132:135], v[192:195], v[32:35]
	v_mfma_f32_16x16x32_bf16 v[36:39], v[140:143], v[192:195], v[36:39]
	v_mfma_f32_16x16x32_bf16 v[16:19], v[132:135], v[200:203], v[16:19]
	v_mfma_f32_16x16x32_bf16 v[20:23], v[140:143], v[200:203], v[20:23]
	v_mfma_f32_16x16x32_bf16 v[0:3], v[132:135], v[208:211], v[0:3]
	v_mfma_f32_16x16x32_bf16 v[4:7], v[140:143], v[208:211], v[4:7]
	s_setprio 0
	s_setprio 1
	v_mfma_f32_16x16x32_bf16 v[56:59], v[158:161], v[180:183], v[56:59]
	v_mfma_f32_16x16x32_bf16 v[60:63], v[172:175], v[180:183], v[60:63]
	v_mfma_f32_16x16x32_bf16 v[40:43], v[158:161], v[188:191], v[40:43]
	v_mfma_f32_16x16x32_bf16 v[44:47], v[172:175], v[188:191], v[44:47]
	v_mfma_f32_16x16x32_bf16 v[24:27], v[158:161], v[196:199], v[24:27]
	v_mfma_f32_16x16x32_bf16 v[28:31], v[172:175], v[196:199], v[28:31]
	v_mfma_f32_16x16x32_bf16 v[8:11], v[158:161], v[204:207], v[8:11]
	v_mfma_f32_16x16x32_bf16 v[12:15], v[172:175], v[204:207], v[12:15]
	v_mfma_f32_16x16x32_bf16 v[56:59], v[162:165], v[184:187], v[56:59]
	v_mfma_f32_16x16x32_bf16 v[60:63], v[176:179], v[184:187], v[60:63]
	v_mfma_f32_16x16x32_bf16 v[40:43], v[162:165], v[192:195], v[40:43]
	v_mfma_f32_16x16x32_bf16 v[44:47], v[176:179], v[192:195], v[44:47]
	v_mfma_f32_16x16x32_bf16 v[24:27], v[162:165], v[200:203], v[24:27]
	v_mfma_f32_16x16x32_bf16 v[28:31], v[176:179], v[200:203], v[28:31]
	v_mfma_f32_16x16x32_bf16 v[8:11], v[162:165], v[208:211], v[8:11]
	v_mfma_f32_16x16x32_bf16 v[12:15], v[176:179], v[208:211], v[12:15]
	s_barrier
	s_setprio 0
	s_add_i32 s36, s36, 2
	s_add_u32 s34, s34, 0x100
	s_addc_u32 s35, s35, 0
	s_add_u32 s22, s22, 0x100
	s_addc_u32 s23, s23, 0
	s_cmp_gt_u32 s36, 5
	s_cbranch_scc0 .LBB0_1693

.LBB0_2019:
	s_cmp_lt_u32 s5, 0x3fffffff
	s_cselect_b64 s[40:41], -1, 0
	s_ashr_i32 s23, s22, 31
	s_and_b64 s[40:41], s[36:37], s[40:41]
	s_lshl_b64 s[36:37], s[22:23], 21
	s_add_u32 s5, s86, s36
	s_addc_u32 s21, s87, s37
	s_add_u32 s36, s5, s38
	s_addc_u32 s37, s21, s39
	s_and_b64 s[48:49], s[40:41], exec
	s_cselect_b32 s5, s37, s47
	s_cselect_b32 s23, s36, s46
	s_ashr_i32 s21, s20, 31
	s_lshl_b64 s[48:49], s[20:21], 21
	v_readlane_b32 s68, v254, 13
	v_readlane_b32 s69, v254, 14
	s_add_u32 s21, s68, s48
	s_addc_u32 s43, s69, s49
	s_add_u32 s38, s21, s38
	s_addc_u32 s39, s43, s39
	s_and_b64 s[48:49], s[40:41], exec
	s_cselect_b32 s21, s39, s45
	s_cselect_b32 s43, s38, s44
	s_add_i32 s68, s67, -2
	s_add_u32 s69, s44, 0x100
	s_addc_u32 s70, s45, 0
	s_add_u32 s44, s46, 0x100080
	s_addc_u32 s45, s47, 0
	s_mov_b32 s46, 0
	s_waitcnt vmcnt(0)
	ds_read_b128 v[128:131], v244
	ds_read_b128 v[132:135], v244 offset:1024
	ds_read_b128 v[136:139], v244 offset:2048
	ds_read_b128 v[140:143], v244 offset:3072
	ds_read_b128 v[144:147], v245
	ds_read_b128 v[148:151], v245 offset:1024
	ds_read_b128 v[152:155], v245 offset:2048
	ds_read_b128 v[156:159], v245 offset:3072
	s_add_i32 s71, s46, 2
	s_add_u32 s47, s44, 0xfff00080
	s_addc_u32 s48, s45, -1
	s_cmp_eq_u32 s68, s46
	s_cselect_b32 s46, s43, s69
	s_cselect_b32 s49, s5, s48
	s_cselect_b32 s48, s23, s47
	s_cselect_b32 s47, s21, s70
	s_add_i32 m0, s94, 0xc000
	ds_read_b128 v[160:163], v246
	ds_read_b128 v[164:167], v246 offset:1024
	ds_read_b128 v[168:171], v246 offset:2048
	ds_read_b128 v[172:175], v246 offset:3072
	ds_read_b128 v[176:179], v246 offset:4096
	ds_read_b128 v[180:183], v246 offset:5120
	ds_read_b128 v[184:187], v246 offset:6144
	ds_read_b128 v[188:191], v246 offset:7168
	global_load_lds_dwordx4 v218, s[44:45]
	s_add_i32 m0, s94, 0xe000
	s_nop 0
	global_load_lds_dwordx4 v220, s[44:45]
	s_waitcnt vmcnt(8)
	s_waitcnt lgkmcnt(0)
	s_setprio 1
	s_barrier
	v_mfma_f32_16x16x32_bf16 v[112:115], v[128:131], v[160:163], 0
	v_mfma_f32_16x16x32_bf16 v[116:119], v[136:139], v[160:163], 0
	v_mfma_f32_16x16x32_bf16 v[100:103], v[128:131], v[168:171], 0
	v_mfma_f32_16x16x32_bf16 v[96:99], v[136:139], v[168:171], 0
	v_mfma_f32_16x16x32_bf16 v[84:87], v[128:131], v[176:179], 0
	v_mfma_f32_16x16x32_bf16 v[80:83], v[136:139], v[176:179], 0
	v_mfma_f32_16x16x32_bf16 v[52:55], v[128:131], v[184:187], 0
	v_mfma_f32_16x16x32_bf16 v[48:51], v[136:139], v[184:187], 0
	v_mfma_f32_16x16x32_bf16 v[112:115], v[132:135], v[164:167], v[112:115]
	v_mfma_f32_16x16x32_bf16 v[116:119], v[140:143], v[164:167], v[116:119]
	v_mfma_f32_16x16x32_bf16 v[100:103], v[132:135], v[172:175], v[100:103]
	v_mfma_f32_16x16x32_bf16 v[96:99], v[140:143], v[172:175], v[96:99]
	v_mfma_f32_16x16x32_bf16 v[84:87], v[132:135], v[180:183], v[84:87]
	v_mfma_f32_16x16x32_bf16 v[80:83], v[140:143], v[180:183], v[80:83]
	v_mfma_f32_16x16x32_bf16 v[52:55], v[132:135], v[188:191], v[52:55]
	v_mfma_f32_16x16x32_bf16 v[48:51], v[140:143], v[188:191], v[48:51]
	s_setprio 0
	s_setprio 1
	v_mfma_f32_16x16x32_bf16 v[124:127], v[144:147], v[160:163], 0
	v_mfma_f32_16x16x32_bf16 v[120:123], v[152:155], v[160:163], 0
	v_mfma_f32_16x16x32_bf16 v[108:111], v[144:147], v[168:171], 0
	v_mfma_f32_16x16x32_bf16 v[104:107], v[152:155], v[168:171], 0
	v_mfma_f32_16x16x32_bf16 v[92:95], v[144:147], v[176:179], 0
	v_mfma_f32_16x16x32_bf16 v[88:91], v[152:155], v[176:179], 0
	v_mfma_f32_16x16x32_bf16 v[68:71], v[144:147], v[184:187], 0
	v_mfma_f32_16x16x32_bf16 v[64:67], v[152:155], v[184:187], 0
	v_mfma_f32_16x16x32_bf16 v[124:127], v[148:151], v[164:167], v[124:127]
	v_mfma_f32_16x16x32_bf16 v[120:123], v[156:159], v[164:167], v[120:123]
	v_mfma_f32_16x16x32_bf16 v[108:111], v[148:151], v[172:175], v[108:111]
	v_mfma_f32_16x16x32_bf16 v[104:107], v[156:159], v[172:175], v[104:107]
	v_mfma_f32_16x16x32_bf16 v[92:95], v[148:151], v[180:183], v[92:95]
	v_mfma_f32_16x16x32_bf16 v[88:91], v[156:159], v[180:183], v[88:91]
	v_mfma_f32_16x16x32_bf16 v[68:71], v[148:151], v[188:191], v[68:71]
	v_mfma_f32_16x16x32_bf16 v[64:67], v[156:159], v[188:191], v[64:67]
	s_barrier
	s_setprio 0
	s_add_i32 s76, s60, s97
	v_lshl_add_u64 v[192:193], s[46:47], 0, v[210:211]
	s_mov_b32 m0, s76
	ds_read_b128 v[160:163], v246 offset:16384
	ds_read_b128 v[164:167], v246 offset:17408
	ds_read_b128 v[168:171], v246 offset:18432
	ds_read_b128 v[172:175], v246 offset:19456
	ds_read_b128 v[176:179], v246 offset:20480
	ds_read_b128 v[180:183], v246 offset:21504
	ds_read_b128 v[184:187], v246 offset:22528
	ds_read_b128 v[188:191], v246 offset:23552
	global_load_lds_dwordx4 v[192:193], off
	s_add_i32 m0, s76, 0x2000
	s_add_u32 s76, s46, 0x100000
	v_lshl_add_u64 v[194:195], s[46:47], 0, v[214:215]
	s_addc_u32 s77, s47, 0
	s_add_i32 s78, s61, s97
	global_load_lds_dwordx4 v[194:195], off
	s_mov_b32 m0, s78
	v_lshl_add_u64 v[198:199], s[48:49], 0, v[212:213]
	global_load_lds_dwordx4 v210, s[76:77]
	s_add_i32 m0, s78, 0x2000
	s_nop 0
	global_load_lds_dwordx4 v214, s[76:77]
	v_lshl_add_u64 v[196:197], s[48:49], 0, v[208:209]
	s_mov_b32 m0, s94
	s_nop 0
	global_load_lds_dwordx4 v[196:197], off
	s_mov_b32 m0, s2
	s_nop 0
	global_load_lds_dwordx4 v[198:199], off
	s_waitcnt vmcnt(8)
	s_waitcnt lgkmcnt(0)
	s_setprio 1
	s_barrier
	v_mfma_f32_16x16x32_bf16 v[60:63], v[128:131], v[160:163], 0
	v_mfma_f32_16x16x32_bf16 v[56:59], v[136:139], v[160:163], 0
	v_mfma_f32_16x16x32_bf16 v[36:39], v[128:131], v[168:171], 0
	v_mfma_f32_16x16x32_bf16 v[32:35], v[136:139], v[168:171], 0
	v_mfma_f32_16x16x32_bf16 v[20:23], v[128:131], v[176:179], 0
	v_mfma_f32_16x16x32_bf16 v[16:19], v[136:139], v[176:179], 0
	v_mfma_f32_16x16x32_bf16 v[4:7], v[128:131], v[184:187], 0
	v_mfma_f32_16x16x32_bf16 v[0:3], v[136:139], v[184:187], 0
	v_mfma_f32_16x16x32_bf16 v[60:63], v[132:135], v[164:167], v[60:63]
	v_mfma_f32_16x16x32_bf16 v[56:59], v[140:143], v[164:167], v[56:59]
	v_mfma_f32_16x16x32_bf16 v[36:39], v[132:135], v[172:175], v[36:39]
	v_mfma_f32_16x16x32_bf16 v[32:35], v[140:143], v[172:175], v[32:35]
	v_mfma_f32_16x16x32_bf16 v[20:23], v[132:135], v[180:183], v[20:23]
	v_mfma_f32_16x16x32_bf16 v[16:19], v[140:143], v[180:183], v[16:19]
	v_mfma_f32_16x16x32_bf16 v[4:7], v[132:135], v[188:191], v[4:7]
	v_mfma_f32_16x16x32_bf16 v[0:3], v[140:143], v[188:191], v[0:3]
	s_setprio 0
	s_setprio 1
	v_mfma_f32_16x16x32_bf16 v[76:79], v[144:147], v[160:163], 0
	v_mfma_f32_16x16x32_bf16 v[72:75], v[152:155], v[160:163], 0
	v_mfma_f32_16x16x32_bf16 v[44:47], v[144:147], v[168:171], 0
	v_mfma_f32_16x16x32_bf16 v[40:43], v[152:155], v[168:171], 0
	v_mfma_f32_16x16x32_bf16 v[28:31], v[144:147], v[176:179], 0
	v_mfma_f32_16x16x32_bf16 v[24:27], v[152:155], v[176:179], 0
	v_mfma_f32_16x16x32_bf16 v[12:15], v[144:147], v[184:187], 0
	v_mfma_f32_16x16x32_bf16 v[8:11], v[152:155], v[184:187], 0
	v_mfma_f32_16x16x32_bf16 v[76:79], v[148:151], v[164:167], v[76:79]
	v_mfma_f32_16x16x32_bf16 v[72:75], v[156:159], v[164:167], v[72:75]
	v_mfma_f32_16x16x32_bf16 v[44:47], v[148:151], v[172:175], v[44:47]
	v_mfma_f32_16x16x32_bf16 v[40:43], v[156:159], v[172:175], v[40:43]
	v_mfma_f32_16x16x32_bf16 v[28:31], v[148:151], v[180:183], v[28:31]
	v_mfma_f32_16x16x32_bf16 v[24:27], v[156:159], v[180:183], v[24:27]
	v_mfma_f32_16x16x32_bf16 v[12:15], v[148:151], v[188:191], v[12:15]
	v_mfma_f32_16x16x32_bf16 v[8:11], v[156:159], v[188:191], v[8:11]
	s_barrier
	s_setprio 0
	s_add_i32 s76, 0, 0x18000
	s_add_i32 s77, 0, 0x1c000
	v_add_u32_e32 v140, s76, v243
	v_add_u32_e32 v156, s77, v243
	ds_read_b128 v[128:131], v140
	ds_read_b128 v[132:135], v140 offset:1024
	ds_read_b128 v[136:139], v140 offset:2048
	ds_read_b128 v[140:143], v140 offset:3072
	ds_read_b128 v[144:147], v156
	ds_read_b128 v[148:151], v156 offset:1024
	ds_read_b128 v[152:155], v156 offset:2048
	ds_read_b128 v[156:159], v156 offset:3072
	s_add_u32 s48, s48, 0x100000
	s_addc_u32 s49, s49, 0
	s_mov_b32 m0, s3
	ds_read_b128 v[160:163], v246 offset:32768
	ds_read_b128 v[164:167], v246 offset:33792
	ds_read_b128 v[168:171], v246 offset:34816
	ds_read_b128 v[172:175], v246 offset:35840
	ds_read_b128 v[176:179], v246 offset:36864
	ds_read_b128 v[180:183], v246 offset:37888
	ds_read_b128 v[184:187], v246 offset:38912
	ds_read_b128 v[188:191], v246 offset:39936
	global_load_lds_dwordx4 v208, s[48:49]
	s_mov_b32 m0, s33
	s_nop 0
	global_load_lds_dwordx4 v212, s[48:49]
	s_waitcnt vmcnt(8)
	s_waitcnt lgkmcnt(0)
	s_setprio 1
	s_barrier
	v_mfma_f32_16x16x32_bf16 v[112:115], v[128:131], v[160:163], v[112:115]
	v_mfma_f32_16x16x32_bf16 v[116:119], v[136:139], v[160:163], v[116:119]
	v_mfma_f32_16x16x32_bf16 v[100:103], v[128:131], v[168:171], v[100:103]
	v_mfma_f32_16x16x32_bf16 v[96:99], v[136:139], v[168:171], v[96:99]
	v_mfma_f32_16x16x32_bf16 v[84:87], v[128:131], v[176:179], v[84:87]
	v_mfma_f32_16x16x32_bf16 v[80:83], v[136:139], v[176:179], v[80:83]
	v_mfma_f32_16x16x32_bf16 v[52:55], v[128:131], v[184:187], v[52:55]
	v_mfma_f32_16x16x32_bf16 v[48:51], v[136:139], v[184:187], v[48:51]
	v_mfma_f32_16x16x32_bf16 v[112:115], v[132:135], v[164:167], v[112:115]
	v_mfma_f32_16x16x32_bf16 v[116:119], v[140:143], v[164:167], v[116:119]
	v_mfma_f32_16x16x32_bf16 v[100:103], v[132:135], v[172:175], v[100:103]
	v_mfma_f32_16x16x32_bf16 v[96:99], v[140:143], v[172:175], v[96:99]
	v_mfma_f32_16x16x32_bf16 v[84:87], v[132:135], v[180:183], v[84:87]
	v_mfma_f32_16x16x32_bf16 v[80:83], v[140:143], v[180:183], v[80:83]
	v_mfma_f32_16x16x32_bf16 v[52:55], v[132:135], v[188:191], v[52:55]
	v_mfma_f32_16x16x32_bf16 v[48:51], v[140:143], v[188:191], v[48:51]
	s_setprio 0
	s_setprio 1
	v_mfma_f32_16x16x32_bf16 v[124:127], v[144:147], v[160:163], v[124:127]
	v_mfma_f32_16x16x32_bf16 v[120:123], v[152:155], v[160:163], v[120:123]
	v_mfma_f32_16x16x32_bf16 v[108:111], v[144:147], v[168:171], v[108:111]
	v_mfma_f32_16x16x32_bf16 v[104:107], v[152:155], v[168:171], v[104:107]
	v_mfma_f32_16x16x32_bf16 v[92:95], v[144:147], v[176:179], v[92:95]
	v_mfma_f32_16x16x32_bf16 v[88:91], v[152:155], v[176:179], v[88:91]
	v_mfma_f32_16x16x32_bf16 v[68:71], v[144:147], v[184:187], v[68:71]
	v_mfma_f32_16x16x32_bf16 v[64:67], v[152:155], v[184:187], v[64:67]
	v_mfma_f32_16x16x32_bf16 v[124:127], v[148:151], v[164:167], v[124:127]
	v_mfma_f32_16x16x32_bf16 v[120:123], v[156:159], v[164:167], v[120:123]
	v_mfma_f32_16x16x32_bf16 v[108:111], v[148:151], v[172:175], v[108:111]
	v_mfma_f32_16x16x32_bf16 v[104:107], v[156:159], v[172:175], v[104:107]
	v_mfma_f32_16x16x32_bf16 v[92:95], v[148:151], v[180:183], v[92:95]
	v_mfma_f32_16x16x32_bf16 v[88:91], v[156:159], v[180:183], v[88:91]
	v_mfma_f32_16x16x32_bf16 v[68:71], v[148:151], v[188:191], v[68:71]
	v_mfma_f32_16x16x32_bf16 v[64:67], v[156:159], v[188:191], v[64:67]
	s_barrier
	s_setprio 0
	s_add_i32 s48, s76, s97
	v_lshl_add_u64 v[192:193], v[192:193], 0, s[16:17]
	s_mov_b32 m0, s48
	ds_read_b128 v[160:163], v246 offset:49152
	ds_read_b128 v[164:167], v246 offset:50176
	ds_read_b128 v[168:171], v246 offset:51200
	ds_read_b128 v[172:175], v246 offset:52224
	ds_read_b128 v[176:179], v246 offset:53248
	ds_read_b128 v[180:183], v246 offset:54272
	ds_read_b128 v[184:187], v246 offset:55296
	ds_read_b128 v[188:191], v246 offset:56320
	global_load_lds_dwordx4 v[192:193], off
	s_add_i32 m0, s48, 0x2000
	s_add_u32 s46, s46, 0x100080
	v_lshl_add_u64 v[192:193], v[194:195], 0, s[16:17]
	s_addc_u32 s47, s47, 0
	s_add_i32 s48, s77, s97
	global_load_lds_dwordx4 v[192:193], off
	s_mov_b32 m0, s48
	s_nop 0
	global_load_lds_dwordx4 v210, s[46:47]
	s_add_i32 m0, s48, 0x2000
	s_nop 0
	global_load_lds_dwordx4 v214, s[46:47]
	v_lshl_add_u64 v[192:193], v[196:197], 0, s[16:17]
	s_mov_b32 m0, s54
	s_nop 0
	global_load_lds_dwordx4 v[192:193], off
	v_lshl_add_u64 v[192:193], v[198:199], 0, s[16:17]
	s_mov_b32 m0, s55
	s_nop 0
	global_load_lds_dwordx4 v[192:193], off
	s_waitcnt vmcnt(8)
	s_waitcnt lgkmcnt(0)
	s_setprio 1
	s_barrier
	v_mfma_f32_16x16x32_bf16 v[60:63], v[128:131], v[160:163], v[60:63]
	v_mfma_f32_16x16x32_bf16 v[56:59], v[136:139], v[160:163], v[56:59]
	v_mfma_f32_16x16x32_bf16 v[36:39], v[128:131], v[168:171], v[36:39]
	v_mfma_f32_16x16x32_bf16 v[32:35], v[136:139], v[168:171], v[32:35]
	v_mfma_f32_16x16x32_bf16 v[20:23], v[128:131], v[176:179], v[20:23]
	v_mfma_f32_16x16x32_bf16 v[16:19], v[136:139], v[176:179], v[16:19]
	v_mfma_f32_16x16x32_bf16 v[4:7], v[128:131], v[184:187], v[4:7]
	v_mfma_f32_16x16x32_bf16 v[0:3], v[136:139], v[184:187], v[0:3]
	v_mfma_f32_16x16x32_bf16 v[60:63], v[132:135], v[164:167], v[60:63]
	v_mfma_f32_16x16x32_bf16 v[56:59], v[140:143], v[164:167], v[56:59]
	v_mfma_f32_16x16x32_bf16 v[36:39], v[132:135], v[172:175], v[36:39]
	v_mfma_f32_16x16x32_bf16 v[32:35], v[140:143], v[172:175], v[32:35]
	v_mfma_f32_16x16x32_bf16 v[20:23], v[132:135], v[180:183], v[20:23]
	v_mfma_f32_16x16x32_bf16 v[16:19], v[140:143], v[180:183], v[16:19]
	v_mfma_f32_16x16x32_bf16 v[4:7], v[132:135], v[188:191], v[4:7]
	v_mfma_f32_16x16x32_bf16 v[0:3], v[140:143], v[188:191], v[0:3]
	s_setprio 0
	s_setprio 1
	v_mfma_f32_16x16x32_bf16 v[76:79], v[144:147], v[160:163], v[76:79]
	v_mfma_f32_16x16x32_bf16 v[72:75], v[152:155], v[160:163], v[72:75]
	v_mfma_f32_16x16x32_bf16 v[44:47], v[144:147], v[168:171], v[44:47]
	v_mfma_f32_16x16x32_bf16 v[40:43], v[152:155], v[168:171], v[40:43]
	v_mfma_f32_16x16x32_bf16 v[28:31], v[144:147], v[176:179], v[28:31]
	v_mfma_f32_16x16x32_bf16 v[24:27], v[152:155], v[176:179], v[24:27]
	v_mfma_f32_16x16x32_bf16 v[12:15], v[144:147], v[184:187], v[12:15]
	v_mfma_f32_16x16x32_bf16 v[8:11], v[152:155], v[184:187], v[8:11]
	v_mfma_f32_16x16x32_bf16 v[76:79], v[148:151], v[164:167], v[76:79]
	v_mfma_f32_16x16x32_bf16 v[72:75], v[156:159], v[164:167], v[72:75]
	v_mfma_f32_16x16x32_bf16 v[44:47], v[148:151], v[172:175], v[44:47]
	v_mfma_f32_16x16x32_bf16 v[40:43], v[156:159], v[172:175], v[40:43]
	v_mfma_f32_16x16x32_bf16 v[28:31], v[148:151], v[180:183], v[28:31]
	v_mfma_f32_16x16x32_bf16 v[24:27], v[156:159], v[180:183], v[24:27]
	v_mfma_f32_16x16x32_bf16 v[12:15], v[148:151], v[188:191], v[12:15]
	v_mfma_f32_16x16x32_bf16 v[8:11], v[156:159], v[188:191], v[8:11]
	s_barrier
	s_setprio 0
	s_add_u32 s69, s69, 0x100
	s_addc_u32 s70, s70, 0
	s_add_u32 s44, s44, 0x100
	s_addc_u32 s45, s45, 0
	s_cmp_ge_u32 s71, s67
	s_mov_b32 s46, s71
	s_cbranch_scc1 .Lpeel_done_2
.LBB0_2020:
	ds_read_b128 v[128:131], v244
	ds_read_b128 v[132:135], v244 offset:1024
	ds_read_b128 v[136:139], v244 offset:2048
	ds_read_b128 v[140:143], v244 offset:3072
	ds_read_b128 v[144:147], v245
	ds_read_b128 v[148:151], v245 offset:1024
	ds_read_b128 v[152:155], v245 offset:2048
	ds_read_b128 v[156:159], v245 offset:3072
	s_add_i32 s71, s46, 2
	s_add_u32 s47, s44, 0xfff00080
	s_addc_u32 s48, s45, -1
	s_cmp_eq_u32 s68, s46
	s_cselect_b32 s46, s43, s69
	s_cselect_b32 s49, s5, s48
	s_cselect_b32 s48, s23, s47
	s_cselect_b32 s47, s21, s70
	s_add_i32 m0, s94, 0xc000
	ds_read_b128 v[160:163], v246
	ds_read_b128 v[164:167], v246 offset:1024
	ds_read_b128 v[168:171], v246 offset:2048
	ds_read_b128 v[172:175], v246 offset:3072
	ds_read_b128 v[176:179], v246 offset:4096
	ds_read_b128 v[180:183], v246 offset:5120
	ds_read_b128 v[184:187], v246 offset:6144
	ds_read_b128 v[188:191], v246 offset:7168
	global_load_lds_dwordx4 v218, s[44:45]
	s_add_i32 m0, s94, 0xe000
	s_nop 0
	global_load_lds_dwordx4 v220, s[44:45]
	s_waitcnt vmcnt(8)
	s_waitcnt lgkmcnt(0)
	s_setprio 1
	s_barrier
	v_mfma_f32_16x16x32_bf16 v[112:115], v[128:131], v[160:163], v[112:115]
	v_mfma_f32_16x16x32_bf16 v[116:119], v[136:139], v[160:163], v[116:119]
	v_mfma_f32_16x16x32_bf16 v[100:103], v[128:131], v[168:171], v[100:103]
	v_mfma_f32_16x16x32_bf16 v[96:99], v[136:139], v[168:171], v[96:99]
	v_mfma_f32_16x16x32_bf16 v[84:87], v[128:131], v[176:179], v[84:87]
	v_mfma_f32_16x16x32_bf16 v[80:83], v[136:139], v[176:179], v[80:83]
	v_mfma_f32_16x16x32_bf16 v[52:55], v[128:131], v[184:187], v[52:55]
	v_mfma_f32_16x16x32_bf16 v[48:51], v[136:139], v[184:187], v[48:51]
	v_mfma_f32_16x16x32_bf16 v[112:115], v[132:135], v[164:167], v[112:115]
	v_mfma_f32_16x16x32_bf16 v[116:119], v[140:143], v[164:167], v[116:119]
	v_mfma_f32_16x16x32_bf16 v[100:103], v[132:135], v[172:175], v[100:103]
	v_mfma_f32_16x16x32_bf16 v[96:99], v[140:143], v[172:175], v[96:99]
	v_mfma_f32_16x16x32_bf16 v[84:87], v[132:135], v[180:183], v[84:87]
	v_mfma_f32_16x16x32_bf16 v[80:83], v[140:143], v[180:183], v[80:83]
	v_mfma_f32_16x16x32_bf16 v[52:55], v[132:135], v[188:191], v[52:55]
	v_mfma_f32_16x16x32_bf16 v[48:51], v[140:143], v[188:191], v[48:51]
	s_setprio 0
	s_setprio 1
	v_mfma_f32_16x16x32_bf16 v[124:127], v[144:147], v[160:163], v[124:127]
	v_mfma_f32_16x16x32_bf16 v[120:123], v[152:155], v[160:163], v[120:123]
	v_mfma_f32_16x16x32_bf16 v[108:111], v[144:147], v[168:171], v[108:111]
	v_mfma_f32_16x16x32_bf16 v[104:107], v[152:155], v[168:171], v[104:107]
	v_mfma_f32_16x16x32_bf16 v[92:95], v[144:147], v[176:179], v[92:95]
	v_mfma_f32_16x16x32_bf16 v[88:91], v[152:155], v[176:179], v[88:91]
	v_mfma_f32_16x16x32_bf16 v[68:71], v[144:147], v[184:187], v[68:71]
	v_mfma_f32_16x16x32_bf16 v[64:67], v[152:155], v[184:187], v[64:67]
	v_mfma_f32_16x16x32_bf16 v[124:127], v[148:151], v[164:167], v[124:127]
	v_mfma_f32_16x16x32_bf16 v[120:123], v[156:159], v[164:167], v[120:123]
	v_mfma_f32_16x16x32_bf16 v[108:111], v[148:151], v[172:175], v[108:111]
	v_mfma_f32_16x16x32_bf16 v[104:107], v[156:159], v[172:175], v[104:107]
	v_mfma_f32_16x16x32_bf16 v[92:95], v[148:151], v[180:183], v[92:95]
	v_mfma_f32_16x16x32_bf16 v[88:91], v[156:159], v[180:183], v[88:91]
	v_mfma_f32_16x16x32_bf16 v[68:71], v[148:151], v[188:191], v[68:71]
	v_mfma_f32_16x16x32_bf16 v[64:67], v[156:159], v[188:191], v[64:67]
	s_barrier
	s_setprio 0
	s_add_i32 s76, s60, s97
	v_lshl_add_u64 v[192:193], s[46:47], 0, v[210:211]
	s_mov_b32 m0, s76
	ds_read_b128 v[160:163], v246 offset:16384
	ds_read_b128 v[164:167], v246 offset:17408
	ds_read_b128 v[168:171], v246 offset:18432
	ds_read_b128 v[172:175], v246 offset:19456
	ds_read_b128 v[176:179], v246 offset:20480
	ds_read_b128 v[180:183], v246 offset:21504
	ds_read_b128 v[184:187], v246 offset:22528
	ds_read_b128 v[188:191], v246 offset:23552
	global_load_lds_dwordx4 v[192:193], off
	s_add_i32 m0, s76, 0x2000
	s_add_u32 s76, s46, 0x100000
	v_lshl_add_u64 v[194:195], s[46:47], 0, v[214:215]
	s_addc_u32 s77, s47, 0
	s_add_i32 s78, s61, s97
	global_load_lds_dwordx4 v[194:195], off
	s_mov_b32 m0, s78
	v_lshl_add_u64 v[198:199], s[48:49], 0, v[212:213]
	global_load_lds_dwordx4 v210, s[76:77]
	s_add_i32 m0, s78, 0x2000
	s_nop 0
	global_load_lds_dwordx4 v214, s[76:77]
	v_lshl_add_u64 v[196:197], s[48:49], 0, v[208:209]
	s_mov_b32 m0, s94
	s_nop 0
	global_load_lds_dwordx4 v[196:197], off
	s_mov_b32 m0, s2
	s_nop 0
	global_load_lds_dwordx4 v[198:199], off
	s_waitcnt vmcnt(8)
	s_waitcnt lgkmcnt(0)
	s_setprio 1
	s_barrier
	v_mfma_f32_16x16x32_bf16 v[60:63], v[128:131], v[160:163], v[60:63]
	v_mfma_f32_16x16x32_bf16 v[56:59], v[136:139], v[160:163], v[56:59]
	v_mfma_f32_16x16x32_bf16 v[36:39], v[128:131], v[168:171], v[36:39]
	v_mfma_f32_16x16x32_bf16 v[32:35], v[136:139], v[168:171], v[32:35]
	v_mfma_f32_16x16x32_bf16 v[20:23], v[128:131], v[176:179], v[20:23]
	v_mfma_f32_16x16x32_bf16 v[16:19], v[136:139], v[176:179], v[16:19]
	v_mfma_f32_16x16x32_bf16 v[4:7], v[128:131], v[184:187], v[4:7]
	v_mfma_f32_16x16x32_bf16 v[0:3], v[136:139], v[184:187], v[0:3]
	v_mfma_f32_16x16x32_bf16 v[60:63], v[132:135], v[164:167], v[60:63]
	v_mfma_f32_16x16x32_bf16 v[56:59], v[140:143], v[164:167], v[56:59]
	v_mfma_f32_16x16x32_bf16 v[36:39], v[132:135], v[172:175], v[36:39]
	v_mfma_f32_16x16x32_bf16 v[32:35], v[140:143], v[172:175], v[32:35]
	v_mfma_f32_16x16x32_bf16 v[20:23], v[132:135], v[180:183], v[20:23]
	v_mfma_f32_16x16x32_bf16 v[16:19], v[140:143], v[180:183], v[16:19]
	v_mfma_f32_16x16x32_bf16 v[4:7], v[132:135], v[188:191], v[4:7]
	v_mfma_f32_16x16x32_bf16 v[0:3], v[140:143], v[188:191], v[0:3]
	s_setprio 0
	s_setprio 1
	v_mfma_f32_16x16x32_bf16 v[76:79], v[144:147], v[160:163], v[76:79]
	v_mfma_f32_16x16x32_bf16 v[72:75], v[152:155], v[160:163], v[72:75]
	v_mfma_f32_16x16x32_bf16 v[44:47], v[144:147], v[168:171], v[44:47]
	v_mfma_f32_16x16x32_bf16 v[40:43], v[152:155], v[168:171], v[40:43]
	v_mfma_f32_16x16x32_bf16 v[28:31], v[144:147], v[176:179], v[28:31]
	v_mfma_f32_16x16x32_bf16 v[24:27], v[152:155], v[176:179], v[24:27]
	v_mfma_f32_16x16x32_bf16 v[12:15], v[144:147], v[184:187], v[12:15]
	v_mfma_f32_16x16x32_bf16 v[8:11], v[152:155], v[184:187], v[8:11]
	v_mfma_f32_16x16x32_bf16 v[76:79], v[148:151], v[164:167], v[76:79]
	v_mfma_f32_16x16x32_bf16 v[72:75], v[156:159], v[164:167], v[72:75]
	v_mfma_f32_16x16x32_bf16 v[44:47], v[148:151], v[172:175], v[44:47]
	v_mfma_f32_16x16x32_bf16 v[40:43], v[156:159], v[172:175], v[40:43]
	v_mfma_f32_16x16x32_bf16 v[28:31], v[148:151], v[180:183], v[28:31]
	v_mfma_f32_16x16x32_bf16 v[24:27], v[156:159], v[180:183], v[24:27]
	v_mfma_f32_16x16x32_bf16 v[12:15], v[148:151], v[188:191], v[12:15]
	v_mfma_f32_16x16x32_bf16 v[8:11], v[156:159], v[188:191], v[8:11]
	s_barrier
	s_setprio 0
	s_add_i32 s76, 0, 0x18000
	s_add_i32 s77, 0, 0x1c000
	v_add_u32_e32 v140, s76, v243
	v_add_u32_e32 v156, s77, v243
	ds_read_b128 v[128:131], v140
	ds_read_b128 v[132:135], v140 offset:1024
	ds_read_b128 v[136:139], v140 offset:2048
	ds_read_b128 v[140:143], v140 offset:3072
	ds_read_b128 v[144:147], v156
	ds_read_b128 v[148:151], v156 offset:1024
	ds_read_b128 v[152:155], v156 offset:2048
	ds_read_b128 v[156:159], v156 offset:3072
	s_add_u32 s48, s48, 0x100000
	s_addc_u32 s49, s49, 0
	s_mov_b32 m0, s3
	ds_read_b128 v[160:163], v246 offset:32768
	ds_read_b128 v[164:167], v246 offset:33792
	ds_read_b128 v[168:171], v246 offset:34816
	ds_read_b128 v[172:175], v246 offset:35840
	ds_read_b128 v[176:179], v246 offset:36864
	ds_read_b128 v[180:183], v246 offset:37888
	ds_read_b128 v[184:187], v246 offset:38912
	ds_read_b128 v[188:191], v246 offset:39936
	global_load_lds_dwordx4 v208, s[48:49]
	s_mov_b32 m0, s33
	s_nop 0
	global_load_lds_dwordx4 v212, s[48:49]
	s_waitcnt vmcnt(8)
	s_waitcnt lgkmcnt(0)
	s_setprio 1
	s_barrier
	v_mfma_f32_16x16x32_bf16 v[112:115], v[128:131], v[160:163], v[112:115]
	v_mfma_f32_16x16x32_bf16 v[116:119], v[136:139], v[160:163], v[116:119]
	v_mfma_f32_16x16x32_bf16 v[100:103], v[128:131], v[168:171], v[100:103]
	v_mfma_f32_16x16x32_bf16 v[96:99], v[136:139], v[168:171], v[96:99]
	v_mfma_f32_16x16x32_bf16 v[84:87], v[128:131], v[176:179], v[84:87]
	v_mfma_f32_16x16x32_bf16 v[80:83], v[136:139], v[176:179], v[80:83]
	v_mfma_f32_16x16x32_bf16 v[52:55], v[128:131], v[184:187], v[52:55]
	v_mfma_f32_16x16x32_bf16 v[48:51], v[136:139], v[184:187], v[48:51]
	v_mfma_f32_16x16x32_bf16 v[112:115], v[132:135], v[164:167], v[112:115]
	v_mfma_f32_16x16x32_bf16 v[116:119], v[140:143], v[164:167], v[116:119]
	v_mfma_f32_16x16x32_bf16 v[100:103], v[132:135], v[172:175], v[100:103]
	v_mfma_f32_16x16x32_bf16 v[96:99], v[140:143], v[172:175], v[96:99]
	v_mfma_f32_16x16x32_bf16 v[84:87], v[132:135], v[180:183], v[84:87]
	v_mfma_f32_16x16x32_bf16 v[80:83], v[140:143], v[180:183], v[80:83]
	v_mfma_f32_16x16x32_bf16 v[52:55], v[132:135], v[188:191], v[52:55]
	v_mfma_f32_16x16x32_bf16 v[48:51], v[140:143], v[188:191], v[48:51]
	s_setprio 0
	s_setprio 1
	v_mfma_f32_16x16x32_bf16 v[124:127], v[144:147], v[160:163], v[124:127]
	v_mfma_f32_16x16x32_bf16 v[120:123], v[152:155], v[160:163], v[120:123]
	v_mfma_f32_16x16x32_bf16 v[108:111], v[144:147], v[168:171], v[108:111]
	v_mfma_f32_16x16x32_bf16 v[104:107], v[152:155], v[168:171], v[104:107]
	v_mfma_f32_16x16x32_bf16 v[92:95], v[144:147], v[176:179], v[92:95]
	v_mfma_f32_16x16x32_bf16 v[88:91], v[152:155], v[176:179], v[88:91]
	v_mfma_f32_16x16x32_bf16 v[68:71], v[144:147], v[184:187], v[68:71]
	v_mfma_f32_16x16x32_bf16 v[64:67], v[152:155], v[184:187], v[64:67]
	v_mfma_f32_16x16x32_bf16 v[124:127], v[148:151], v[164:167], v[124:127]
	v_mfma_f32_16x16x32_bf16 v[120:123], v[156:159], v[164:167], v[120:123]
	v_mfma_f32_16x16x32_bf16 v[108:111], v[148:151], v[172:175], v[108:111]
	v_mfma_f32_16x16x32_bf16 v[104:107], v[156:159], v[172:175], v[104:107]
	v_mfma_f32_16x16x32_bf16 v[92:95], v[148:151], v[180:183], v[92:95]
	v_mfma_f32_16x16x32_bf16 v[88:91], v[156:159], v[180:183], v[88:91]
	v_mfma_f32_16x16x32_bf16 v[68:71], v[148:151], v[188:191], v[68:71]
	v_mfma_f32_16x16x32_bf16 v[64:67], v[156:159], v[188:191], v[64:67]
	s_barrier
	s_setprio 0
	s_add_i32 s48, s76, s97
	v_lshl_add_u64 v[192:193], v[192:193], 0, s[16:17]
	s_mov_b32 m0, s48
	ds_read_b128 v[160:163], v246 offset:49152
	ds_read_b128 v[164:167], v246 offset:50176
	ds_read_b128 v[168:171], v246 offset:51200
	ds_read_b128 v[172:175], v246 offset:52224
	ds_read_b128 v[176:179], v246 offset:53248
	ds_read_b128 v[180:183], v246 offset:54272
	ds_read_b128 v[184:187], v246 offset:55296
	ds_read_b128 v[188:191], v246 offset:56320
	global_load_lds_dwordx4 v[192:193], off
	s_add_i32 m0, s48, 0x2000
	s_add_u32 s46, s46, 0x100080
	v_lshl_add_u64 v[192:193], v[194:195], 0, s[16:17]
	s_addc_u32 s47, s47, 0
	s_add_i32 s48, s77, s97
	global_load_lds_dwordx4 v[192:193], off
	s_mov_b32 m0, s48
	s_nop 0
	global_load_lds_dwordx4 v210, s[46:47]
	s_add_i32 m0, s48, 0x2000
	s_nop 0
	global_load_lds_dwordx4 v214, s[46:47]
	v_lshl_add_u64 v[192:193], v[196:197], 0, s[16:17]
	s_mov_b32 m0, s54
	s_nop 0
	global_load_lds_dwordx4 v[192:193], off
	v_lshl_add_u64 v[192:193], v[198:199], 0, s[16:17]
	s_mov_b32 m0, s55
	s_nop 0
	global_load_lds_dwordx4 v[192:193], off
	s_waitcnt vmcnt(8)
	s_waitcnt lgkmcnt(0)
	s_setprio 1
	s_barrier
	v_mfma_f32_16x16x32_bf16 v[60:63], v[128:131], v[160:163], v[60:63]
	v_mfma_f32_16x16x32_bf16 v[56:59], v[136:139], v[160:163], v[56:59]
	v_mfma_f32_16x16x32_bf16 v[36:39], v[128:131], v[168:171], v[36:39]
	v_mfma_f32_16x16x32_bf16 v[32:35], v[136:139], v[168:171], v[32:35]
	v_mfma_f32_16x16x32_bf16 v[20:23], v[128:131], v[176:179], v[20:23]
	v_mfma_f32_16x16x32_bf16 v[16:19], v[136:139], v[176:179], v[16:19]
	v_mfma_f32_16x16x32_bf16 v[4:7], v[128:131], v[184:187], v[4:7]
	v_mfma_f32_16x16x32_bf16 v[0:3], v[136:139], v[184:187], v[0:3]
	v_mfma_f32_16x16x32_bf16 v[60:63], v[132:135], v[164:167], v[60:63]
	v_mfma_f32_16x16x32_bf16 v[56:59], v[140:143], v[164:167], v[56:59]
	v_mfma_f32_16x16x32_bf16 v[36:39], v[132:135], v[172:175], v[36:39]
	v_mfma_f32_16x16x32_bf16 v[32:35], v[140:143], v[172:175], v[32:35]
	v_mfma_f32_16x16x32_bf16 v[20:23], v[132:135], v[180:183], v[20:23]
	v_mfma_f32_16x16x32_bf16 v[16:19], v[140:143], v[180:183], v[16:19]
	v_mfma_f32_16x16x32_bf16 v[4:7], v[132:135], v[188:191], v[4:7]
	v_mfma_f32_16x16x32_bf16 v[0:3], v[140:143], v[188:191], v[0:3]
	s_setprio 0
	s_setprio 1
	v_mfma_f32_16x16x32_bf16 v[76:79], v[144:147], v[160:163], v[76:79]
	v_mfma_f32_16x16x32_bf16 v[72:75], v[152:155], v[160:163], v[72:75]
	v_mfma_f32_16x16x32_bf16 v[44:47], v[144:147], v[168:171], v[44:47]
	v_mfma_f32_16x16x32_bf16 v[40:43], v[152:155], v[168:171], v[40:43]
	v_mfma_f32_16x16x32_bf16 v[28:31], v[144:147], v[176:179], v[28:31]
	v_mfma_f32_16x16x32_bf16 v[24:27], v[152:155], v[176:179], v[24:27]
	v_mfma_f32_16x16x32_bf16 v[12:15], v[144:147], v[184:187], v[12:15]
	v_mfma_f32_16x16x32_bf16 v[8:11], v[152:155], v[184:187], v[8:11]
	v_mfma_f32_16x16x32_bf16 v[76:79], v[148:151], v[164:167], v[76:79]
	v_mfma_f32_16x16x32_bf16 v[72:75], v[156:159], v[164:167], v[72:75]
	v_mfma_f32_16x16x32_bf16 v[44:47], v[148:151], v[172:175], v[44:47]
	v_mfma_f32_16x16x32_bf16 v[40:43], v[156:159], v[172:175], v[40:43]
	v_mfma_f32_16x16x32_bf16 v[28:31], v[148:151], v[180:183], v[28:31]
	v_mfma_f32_16x16x32_bf16 v[24:27], v[156:159], v[180:183], v[24:27]
	v_mfma_f32_16x16x32_bf16 v[12:15], v[148:151], v[188:191], v[12:15]
	v_mfma_f32_16x16x32_bf16 v[8:11], v[156:159], v[188:191], v[8:11]
	s_barrier
	s_setprio 0
	s_add_u32 s69, s69, 0x100
	s_addc_u32 s70, s70, 0
	s_add_u32 s44, s44, 0x100
	s_addc_u32 s45, s45, 0
	s_cmp_ge_u32 s71, s67
	s_mov_b32 s46, s71
	s_cbranch_scc0 .LBB0_2020

.LBB0_2288:
	s_ashr_i32 s25, s24, 31
	s_lshl_b64 s[86:87], s[24:25], 21
	v_readlane_b32 s88, v254, 52
	v_readlane_b32 s89, v254, 53
	s_add_u32 s5, s88, s86
	s_addc_u32 s25, s89, s87
	s_add_u32 s38, s5, s38
	s_addc_u32 s39, s25, s39
	s_and_b64 s[48:49], s[48:49], exec
	s_cselect_b32 s5, s39, s45
	s_cselect_b32 s25, s38, s44
	s_add_i32 s43, s84, -2
	s_add_u32 s85, s44, 0x100
	s_addc_u32 s86, s45, 0
	s_add_u32 s44, s46, 0x100080
	s_addc_u32 s45, s47, 0
	s_mov_b32 s46, 0
	ds_read_b128 v[148:151], v159
	ds_read_b128 v[164:167], v159 offset:1024
	ds_read_b128 v[168:171], v159 offset:2048
	ds_read_b128 v[172:175], v159 offset:3072
	ds_read_b128 v[176:179], v160
	ds_read_b128 v[180:183], v160 offset:1024
	ds_read_b128 v[184:187], v160 offset:2048
	ds_read_b128 v[188:191], v160 offset:3072
	s_add_i32 s87, s46, 2
	s_add_u32 s47, s44, 0xfff00080
	s_addc_u32 s48, s45, -1
	s_cmp_eq_u32 s43, s46
	s_cselect_b32 s46, s25, s85
	s_cselect_b32 s49, s37, s48
	s_cselect_b32 s48, s36, s47
	s_cselect_b32 s47, s5, s86
	s_add_i32 m0, s94, 0xc000
	ds_read_b128 v[192:195], v161
	ds_read_b128 v[196:199], v161 offset:1024
	ds_read_b128 v[200:203], v161 offset:2048
	ds_read_b128 v[204:207], v161 offset:3072
	ds_read_b128 v[208:211], v161 offset:4096
	ds_read_b128 v[212:215], v161 offset:5120
	ds_read_b128 v[216:219], v161 offset:6144
	ds_read_b128 v[220:223], v161 offset:7168
	global_load_lds_dwordx4 v142, s[44:45]
	s_add_i32 m0, s94, 0xe000
	s_nop 0
	global_load_lds_dwordx4 v144, s[44:45]
	s_waitcnt vmcnt(8)
	s_waitcnt lgkmcnt(0)
	s_setprio 1
	s_barrier
	v_mfma_f32_16x16x32_bf16 v[112:115], v[148:151], v[192:195], 0
	v_mfma_f32_16x16x32_bf16 v[116:119], v[168:171], v[192:195], 0
	v_mfma_f32_16x16x32_bf16 v[100:103], v[148:151], v[200:203], 0
	v_mfma_f32_16x16x32_bf16 v[96:99], v[168:171], v[200:203], 0
	v_mfma_f32_16x16x32_bf16 v[84:87], v[148:151], v[208:211], 0
	v_mfma_f32_16x16x32_bf16 v[80:83], v[168:171], v[208:211], 0
	v_mfma_f32_16x16x32_bf16 v[52:55], v[148:151], v[216:219], 0
	v_mfma_f32_16x16x32_bf16 v[48:51], v[168:171], v[216:219], 0
	v_mfma_f32_16x16x32_bf16 v[112:115], v[164:167], v[196:199], v[112:115]
	v_mfma_f32_16x16x32_bf16 v[116:119], v[172:175], v[196:199], v[116:119]
	v_mfma_f32_16x16x32_bf16 v[100:103], v[164:167], v[204:207], v[100:103]
	v_mfma_f32_16x16x32_bf16 v[96:99], v[172:175], v[204:207], v[96:99]
	v_mfma_f32_16x16x32_bf16 v[84:87], v[164:167], v[212:215], v[84:87]
	v_mfma_f32_16x16x32_bf16 v[80:83], v[172:175], v[212:215], v[80:83]
	v_mfma_f32_16x16x32_bf16 v[52:55], v[164:167], v[220:223], v[52:55]
	v_mfma_f32_16x16x32_bf16 v[48:51], v[172:175], v[220:223], v[48:51]
	s_setprio 0
	s_setprio 1
	v_mfma_f32_16x16x32_bf16 v[124:127], v[176:179], v[192:195], 0
	v_mfma_f32_16x16x32_bf16 v[120:123], v[184:187], v[192:195], 0
	v_mfma_f32_16x16x32_bf16 v[108:111], v[176:179], v[200:203], 0
	v_mfma_f32_16x16x32_bf16 v[104:107], v[184:187], v[200:203], 0
	v_mfma_f32_16x16x32_bf16 v[92:95], v[176:179], v[208:211], 0
	v_mfma_f32_16x16x32_bf16 v[88:91], v[184:187], v[208:211], 0
	v_mfma_f32_16x16x32_bf16 v[68:71], v[176:179], v[216:219], 0
	v_mfma_f32_16x16x32_bf16 v[64:67], v[184:187], v[216:219], 0
	v_mfma_f32_16x16x32_bf16 v[124:127], v[180:183], v[196:199], v[124:127]
	v_mfma_f32_16x16x32_bf16 v[120:123], v[188:191], v[196:199], v[120:123]
	v_mfma_f32_16x16x32_bf16 v[108:111], v[180:183], v[204:207], v[108:111]
	v_mfma_f32_16x16x32_bf16 v[104:107], v[188:191], v[204:207], v[104:107]
	v_mfma_f32_16x16x32_bf16 v[92:95], v[180:183], v[212:215], v[92:95]
	v_mfma_f32_16x16x32_bf16 v[88:91], v[188:191], v[212:215], v[88:91]
	v_mfma_f32_16x16x32_bf16 v[68:71], v[180:183], v[220:223], v[68:71]
	v_mfma_f32_16x16x32_bf16 v[64:67], v[188:191], v[220:223], v[64:67]
	s_barrier
	s_setprio 0
	s_add_i32 s88, s77, s97
	v_lshl_add_u64 v[152:153], s[46:47], 0, v[132:133]
	s_mov_b32 m0, s88
	ds_read_b128 v[192:195], v161 offset:16384
	ds_read_b128 v[196:199], v161 offset:17408
	ds_read_b128 v[200:203], v161 offset:18432
	ds_read_b128 v[204:207], v161 offset:19456
	ds_read_b128 v[208:211], v161 offset:20480
	ds_read_b128 v[212:215], v161 offset:21504
	ds_read_b128 v[216:219], v161 offset:22528
	ds_read_b128 v[220:223], v161 offset:23552
	global_load_lds_dwordx4 v[152:153], off
	s_add_i32 m0, s88, 0x2000
	s_add_u32 s88, s46, 0x100000
	v_lshl_add_u64 v[224:225], s[46:47], 0, v[136:137]
	s_addc_u32 s89, s47, 0
	s_add_i32 s90, s78, s97
	global_load_lds_dwordx4 v[224:225], off
	s_mov_b32 m0, s90
	v_lshl_add_u64 v[228:229], s[48:49], 0, v[134:135]
	global_load_lds_dwordx4 v132, s[88:89]
	s_add_i32 m0, s90, 0x2000
	s_nop 0
	global_load_lds_dwordx4 v136, s[88:89]
	v_lshl_add_u64 v[226:227], s[48:49], 0, v[130:131]
	s_mov_b32 m0, s94
	s_nop 0
	global_load_lds_dwordx4 v[226:227], off
	s_mov_b32 m0, s52
	s_nop 0
	global_load_lds_dwordx4 v[228:229], off
	s_waitcnt vmcnt(8)
	s_waitcnt lgkmcnt(0)
	s_setprio 1
	s_barrier
	v_mfma_f32_16x16x32_bf16 v[60:63], v[148:151], v[192:195], 0
	v_mfma_f32_16x16x32_bf16 v[56:59], v[168:171], v[192:195], 0
	v_mfma_f32_16x16x32_bf16 v[36:39], v[148:151], v[200:203], 0
	v_mfma_f32_16x16x32_bf16 v[32:35], v[168:171], v[200:203], 0
	v_mfma_f32_16x16x32_bf16 v[20:23], v[148:151], v[208:211], 0
	v_mfma_f32_16x16x32_bf16 v[16:19], v[168:171], v[208:211], 0
	v_mfma_f32_16x16x32_bf16 v[4:7], v[148:151], v[216:219], 0
	v_mfma_f32_16x16x32_bf16 v[0:3], v[168:171], v[216:219], 0
	v_mfma_f32_16x16x32_bf16 v[60:63], v[164:167], v[196:199], v[60:63]
	v_mfma_f32_16x16x32_bf16 v[56:59], v[172:175], v[196:199], v[56:59]
	v_mfma_f32_16x16x32_bf16 v[36:39], v[164:167], v[204:207], v[36:39]
	v_mfma_f32_16x16x32_bf16 v[32:35], v[172:175], v[204:207], v[32:35]
	v_mfma_f32_16x16x32_bf16 v[20:23], v[164:167], v[212:215], v[20:23]
	v_mfma_f32_16x16x32_bf16 v[16:19], v[172:175], v[212:215], v[16:19]
	v_mfma_f32_16x16x32_bf16 v[4:7], v[164:167], v[220:223], v[4:7]
	v_mfma_f32_16x16x32_bf16 v[0:3], v[172:175], v[220:223], v[0:3]
	s_setprio 0
	s_setprio 1
	v_mfma_f32_16x16x32_bf16 v[76:79], v[176:179], v[192:195], 0
	v_mfma_f32_16x16x32_bf16 v[72:75], v[184:187], v[192:195], 0
	v_mfma_f32_16x16x32_bf16 v[44:47], v[176:179], v[200:203], 0
	v_mfma_f32_16x16x32_bf16 v[40:43], v[184:187], v[200:203], 0
	v_mfma_f32_16x16x32_bf16 v[28:31], v[176:179], v[208:211], 0
	v_mfma_f32_16x16x32_bf16 v[24:27], v[184:187], v[208:211], 0
	v_mfma_f32_16x16x32_bf16 v[12:15], v[176:179], v[216:219], 0
	v_mfma_f32_16x16x32_bf16 v[8:11], v[184:187], v[216:219], 0
	v_mfma_f32_16x16x32_bf16 v[76:79], v[180:183], v[196:199], v[76:79]
	v_mfma_f32_16x16x32_bf16 v[72:75], v[188:191], v[196:199], v[72:75]
	v_mfma_f32_16x16x32_bf16 v[44:47], v[180:183], v[204:207], v[44:47]
	v_mfma_f32_16x16x32_bf16 v[40:43], v[188:191], v[204:207], v[40:43]
	v_mfma_f32_16x16x32_bf16 v[28:31], v[180:183], v[212:215], v[28:31]
	v_mfma_f32_16x16x32_bf16 v[24:27], v[188:191], v[212:215], v[24:27]
	v_mfma_f32_16x16x32_bf16 v[12:15], v[180:183], v[220:223], v[12:15]
	v_mfma_f32_16x16x32_bf16 v[8:11], v[188:191], v[220:223], v[8:11]
	s_barrier
	s_setprio 0
	s_add_i32 s88, 0, 0x18000
	v_add_u32_e32 v163, s88, v157
	s_add_i32 s89, 0, 0x1c000
	ds_read_b128 v[148:151], v163
	ds_read_b128 v[164:167], v163 offset:1024
	ds_read_b128 v[168:171], v163 offset:2048
	ds_read_b128 v[172:175], v163 offset:3072
	v_add_u32_e32 v163, s89, v157
	ds_read_b128 v[176:179], v163
	ds_read_b128 v[180:183], v163 offset:1024
	ds_read_b128 v[184:187], v163 offset:2048
	ds_read_b128 v[188:191], v163 offset:3072
	s_add_u32 s48, s48, 0x100000
	s_addc_u32 s49, s49, 0
	s_mov_b32 m0, s53
	ds_read_b128 v[192:195], v161 offset:32768
	ds_read_b128 v[196:199], v161 offset:33792
	ds_read_b128 v[200:203], v161 offset:34816
	ds_read_b128 v[204:207], v161 offset:35840
	ds_read_b128 v[208:211], v161 offset:36864
	ds_read_b128 v[212:215], v161 offset:37888
	ds_read_b128 v[216:219], v161 offset:38912
	ds_read_b128 v[220:223], v161 offset:39936
	global_load_lds_dwordx4 v130, s[48:49]
	s_mov_b32 m0, s54
	s_nop 0
	global_load_lds_dwordx4 v134, s[48:49]
	s_waitcnt vmcnt(8)
	s_waitcnt lgkmcnt(0)
	s_setprio 1
	s_barrier
	v_mfma_f32_16x16x32_bf16 v[112:115], v[148:151], v[192:195], v[112:115]
	v_mfma_f32_16x16x32_bf16 v[116:119], v[168:171], v[192:195], v[116:119]
	v_mfma_f32_16x16x32_bf16 v[100:103], v[148:151], v[200:203], v[100:103]
	v_mfma_f32_16x16x32_bf16 v[96:99], v[168:171], v[200:203], v[96:99]
	v_mfma_f32_16x16x32_bf16 v[84:87], v[148:151], v[208:211], v[84:87]
	v_mfma_f32_16x16x32_bf16 v[80:83], v[168:171], v[208:211], v[80:83]
	v_mfma_f32_16x16x32_bf16 v[52:55], v[148:151], v[216:219], v[52:55]
	v_mfma_f32_16x16x32_bf16 v[48:51], v[168:171], v[216:219], v[48:51]
	v_mfma_f32_16x16x32_bf16 v[112:115], v[164:167], v[196:199], v[112:115]
	v_mfma_f32_16x16x32_bf16 v[116:119], v[172:175], v[196:199], v[116:119]
	v_mfma_f32_16x16x32_bf16 v[100:103], v[164:167], v[204:207], v[100:103]
	v_mfma_f32_16x16x32_bf16 v[96:99], v[172:175], v[204:207], v[96:99]
	v_mfma_f32_16x16x32_bf16 v[84:87], v[164:167], v[212:215], v[84:87]
	v_mfma_f32_16x16x32_bf16 v[80:83], v[172:175], v[212:215], v[80:83]
	v_mfma_f32_16x16x32_bf16 v[52:55], v[164:167], v[220:223], v[52:55]
	v_mfma_f32_16x16x32_bf16 v[48:51], v[172:175], v[220:223], v[48:51]
	s_setprio 0
	s_setprio 1
	v_mfma_f32_16x16x32_bf16 v[124:127], v[176:179], v[192:195], v[124:127]
	v_mfma_f32_16x16x32_bf16 v[120:123], v[184:187], v[192:195], v[120:123]
	v_mfma_f32_16x16x32_bf16 v[108:111], v[176:179], v[200:203], v[108:111]
	v_mfma_f32_16x16x32_bf16 v[104:107], v[184:187], v[200:203], v[104:107]
	v_mfma_f32_16x16x32_bf16 v[92:95], v[176:179], v[208:211], v[92:95]
	v_mfma_f32_16x16x32_bf16 v[88:91], v[184:187], v[208:211], v[88:91]
	v_mfma_f32_16x16x32_bf16 v[68:71], v[176:179], v[216:219], v[68:71]
	v_mfma_f32_16x16x32_bf16 v[64:67], v[184:187], v[216:219], v[64:67]
	v_mfma_f32_16x16x32_bf16 v[124:127], v[180:183], v[196:199], v[124:127]
	v_mfma_f32_16x16x32_bf16 v[120:123], v[188:191], v[196:199], v[120:123]
	v_mfma_f32_16x16x32_bf16 v[108:111], v[180:183], v[204:207], v[108:111]
	v_mfma_f32_16x16x32_bf16 v[104:107], v[188:191], v[204:207], v[104:107]
	v_mfma_f32_16x16x32_bf16 v[92:95], v[180:183], v[212:215], v[92:95]
	v_mfma_f32_16x16x32_bf16 v[88:91], v[188:191], v[212:215], v[88:91]
	v_mfma_f32_16x16x32_bf16 v[68:71], v[180:183], v[220:223], v[68:71]
	v_mfma_f32_16x16x32_bf16 v[64:67], v[188:191], v[220:223], v[64:67]
	s_barrier
	s_setprio 0
	s_add_i32 s48, s88, s97
	v_lshl_add_u64 v[152:153], v[152:153], 0, s[18:19]
	s_mov_b32 m0, s48
	ds_read_b128 v[192:195], v161 offset:49152
	ds_read_b128 v[196:199], v161 offset:50176
	ds_read_b128 v[200:203], v161 offset:51200
	ds_read_b128 v[204:207], v161 offset:52224
	ds_read_b128 v[208:211], v161 offset:53248
	ds_read_b128 v[212:215], v161 offset:54272
	ds_read_b128 v[216:219], v161 offset:55296
	ds_read_b128 v[220:223], v161 offset:56320
	global_load_lds_dwordx4 v[152:153], off
	s_add_i32 m0, s48, 0x2000
	s_add_u32 s46, s46, 0x100080
	v_lshl_add_u64 v[152:153], v[224:225], 0, s[18:19]
	s_addc_u32 s47, s47, 0
	s_add_i32 s48, s89, s97
	global_load_lds_dwordx4 v[152:153], off
	s_mov_b32 m0, s48
	s_nop 0
	global_load_lds_dwordx4 v132, s[46:47]
	s_add_i32 m0, s48, 0x2000
	s_nop 0
	global_load_lds_dwordx4 v136, s[46:47]
	v_lshl_add_u64 v[152:153], v[226:227], 0, s[18:19]
	s_mov_b32 m0, s68
	s_nop 0
	global_load_lds_dwordx4 v[152:153], off
	v_lshl_add_u64 v[152:153], v[228:229], 0, s[18:19]
	s_mov_b32 m0, s69
	s_nop 0
	global_load_lds_dwordx4 v[152:153], off
	s_waitcnt vmcnt(8)
	s_waitcnt lgkmcnt(0)
	s_setprio 1
	s_barrier
	v_mfma_f32_16x16x32_bf16 v[60:63], v[148:151], v[192:195], v[60:63]
	v_mfma_f32_16x16x32_bf16 v[56:59], v[168:171], v[192:195], v[56:59]
	v_mfma_f32_16x16x32_bf16 v[36:39], v[148:151], v[200:203], v[36:39]
	v_mfma_f32_16x16x32_bf16 v[32:35], v[168:171], v[200:203], v[32:35]
	v_mfma_f32_16x16x32_bf16 v[20:23], v[148:151], v[208:211], v[20:23]
	v_mfma_f32_16x16x32_bf16 v[16:19], v[168:171], v[208:211], v[16:19]
	v_mfma_f32_16x16x32_bf16 v[4:7], v[148:151], v[216:219], v[4:7]
	v_mfma_f32_16x16x32_bf16 v[0:3], v[168:171], v[216:219], v[0:3]
	v_mfma_f32_16x16x32_bf16 v[60:63], v[164:167], v[196:199], v[60:63]
	v_mfma_f32_16x16x32_bf16 v[56:59], v[172:175], v[196:199], v[56:59]
	v_mfma_f32_16x16x32_bf16 v[36:39], v[164:167], v[204:207], v[36:39]
	v_mfma_f32_16x16x32_bf16 v[32:35], v[172:175], v[204:207], v[32:35]
	v_mfma_f32_16x16x32_bf16 v[20:23], v[164:167], v[212:215], v[20:23]
	v_mfma_f32_16x16x32_bf16 v[16:19], v[172:175], v[212:215], v[16:19]
	v_mfma_f32_16x16x32_bf16 v[4:7], v[164:167], v[220:223], v[4:7]
	v_mfma_f32_16x16x32_bf16 v[0:3], v[172:175], v[220:223], v[0:3]
	s_setprio 0
	s_setprio 1
	v_mfma_f32_16x16x32_bf16 v[76:79], v[176:179], v[192:195], v[76:79]
	v_mfma_f32_16x16x32_bf16 v[72:75], v[184:187], v[192:195], v[72:75]
	v_mfma_f32_16x16x32_bf16 v[44:47], v[176:179], v[200:203], v[44:47]
	v_mfma_f32_16x16x32_bf16 v[40:43], v[184:187], v[200:203], v[40:43]
	v_mfma_f32_16x16x32_bf16 v[28:31], v[176:179], v[208:211], v[28:31]
	v_mfma_f32_16x16x32_bf16 v[24:27], v[184:187], v[208:211], v[24:27]
	v_mfma_f32_16x16x32_bf16 v[12:15], v[176:179], v[216:219], v[12:15]
	v_mfma_f32_16x16x32_bf16 v[8:11], v[184:187], v[216:219], v[8:11]
	v_mfma_f32_16x16x32_bf16 v[76:79], v[180:183], v[196:199], v[76:79]
	v_mfma_f32_16x16x32_bf16 v[72:75], v[188:191], v[196:199], v[72:75]
	v_mfma_f32_16x16x32_bf16 v[44:47], v[180:183], v[204:207], v[44:47]
	v_mfma_f32_16x16x32_bf16 v[40:43], v[188:191], v[204:207], v[40:43]
	v_mfma_f32_16x16x32_bf16 v[28:31], v[180:183], v[212:215], v[28:31]
	v_mfma_f32_16x16x32_bf16 v[24:27], v[188:191], v[212:215], v[24:27]
	v_mfma_f32_16x16x32_bf16 v[12:15], v[180:183], v[220:223], v[12:15]
	v_mfma_f32_16x16x32_bf16 v[8:11], v[188:191], v[220:223], v[8:11]
	s_barrier
	s_setprio 0
	s_add_u32 s85, s85, 0x100
	s_addc_u32 s86, s86, 0
	s_add_u32 s44, s44, 0x100
	s_addc_u32 s45, s45, 0
	s_cmp_ge_u32 s87, s84
	s_mov_b32 s46, s87
	s_cbranch_scc1 .Lpeel_done_3
.LBB0_2289:
	ds_read_b128 v[148:151], v159
	ds_read_b128 v[164:167], v159 offset:1024
	ds_read_b128 v[168:171], v159 offset:2048
	ds_read_b128 v[172:175], v159 offset:3072
	ds_read_b128 v[176:179], v160
	ds_read_b128 v[180:183], v160 offset:1024
	ds_read_b128 v[184:187], v160 offset:2048
	ds_read_b128 v[188:191], v160 offset:3072
	s_add_i32 s87, s46, 2
	s_add_u32 s47, s44, 0xfff00080
	s_addc_u32 s48, s45, -1
	s_cmp_eq_u32 s43, s46
	s_cselect_b32 s46, s25, s85
	s_cselect_b32 s49, s37, s48
	s_cselect_b32 s48, s36, s47
	s_cselect_b32 s47, s5, s86
	s_add_i32 m0, s94, 0xc000
	ds_read_b128 v[192:195], v161
	ds_read_b128 v[196:199], v161 offset:1024
	ds_read_b128 v[200:203], v161 offset:2048
	ds_read_b128 v[204:207], v161 offset:3072
	ds_read_b128 v[208:211], v161 offset:4096
	ds_read_b128 v[212:215], v161 offset:5120
	ds_read_b128 v[216:219], v161 offset:6144
	ds_read_b128 v[220:223], v161 offset:7168
	global_load_lds_dwordx4 v142, s[44:45]
	s_add_i32 m0, s94, 0xe000
	s_nop 0
	global_load_lds_dwordx4 v144, s[44:45]
	s_waitcnt vmcnt(8)
	s_waitcnt lgkmcnt(0)
	s_setprio 1
	s_barrier
	v_mfma_f32_16x16x32_bf16 v[112:115], v[148:151], v[192:195], v[112:115]
	v_mfma_f32_16x16x32_bf16 v[116:119], v[168:171], v[192:195], v[116:119]
	v_mfma_f32_16x16x32_bf16 v[100:103], v[148:151], v[200:203], v[100:103]
	v_mfma_f32_16x16x32_bf16 v[96:99], v[168:171], v[200:203], v[96:99]
	v_mfma_f32_16x16x32_bf16 v[84:87], v[148:151], v[208:211], v[84:87]
	v_mfma_f32_16x16x32_bf16 v[80:83], v[168:171], v[208:211], v[80:83]
	v_mfma_f32_16x16x32_bf16 v[52:55], v[148:151], v[216:219], v[52:55]
	v_mfma_f32_16x16x32_bf16 v[48:51], v[168:171], v[216:219], v[48:51]
	v_mfma_f32_16x16x32_bf16 v[112:115], v[164:167], v[196:199], v[112:115]
	v_mfma_f32_16x16x32_bf16 v[116:119], v[172:175], v[196:199], v[116:119]
	v_mfma_f32_16x16x32_bf16 v[100:103], v[164:167], v[204:207], v[100:103]
	v_mfma_f32_16x16x32_bf16 v[96:99], v[172:175], v[204:207], v[96:99]
	v_mfma_f32_16x16x32_bf16 v[84:87], v[164:167], v[212:215], v[84:87]
	v_mfma_f32_16x16x32_bf16 v[80:83], v[172:175], v[212:215], v[80:83]
	v_mfma_f32_16x16x32_bf16 v[52:55], v[164:167], v[220:223], v[52:55]
	v_mfma_f32_16x16x32_bf16 v[48:51], v[172:175], v[220:223], v[48:51]
	s_setprio 0
	s_setprio 1
	v_mfma_f32_16x16x32_bf16 v[124:127], v[176:179], v[192:195], v[124:127]
	v_mfma_f32_16x16x32_bf16 v[120:123], v[184:187], v[192:195], v[120:123]
	v_mfma_f32_16x16x32_bf16 v[108:111], v[176:179], v[200:203], v[108:111]
	v_mfma_f32_16x16x32_bf16 v[104:107], v[184:187], v[200:203], v[104:107]
	v_mfma_f32_16x16x32_bf16 v[92:95], v[176:179], v[208:211], v[92:95]
	v_mfma_f32_16x16x32_bf16 v[88:91], v[184:187], v[208:211], v[88:91]
	v_mfma_f32_16x16x32_bf16 v[68:71], v[176:179], v[216:219], v[68:71]
	v_mfma_f32_16x16x32_bf16 v[64:67], v[184:187], v[216:219], v[64:67]
	v_mfma_f32_16x16x32_bf16 v[124:127], v[180:183], v[196:199], v[124:127]
	v_mfma_f32_16x16x32_bf16 v[120:123], v[188:191], v[196:199], v[120:123]
	v_mfma_f32_16x16x32_bf16 v[108:111], v[180:183], v[204:207], v[108:111]
	v_mfma_f32_16x16x32_bf16 v[104:107], v[188:191], v[204:207], v[104:107]
	v_mfma_f32_16x16x32_bf16 v[92:95], v[180:183], v[212:215], v[92:95]
	v_mfma_f32_16x16x32_bf16 v[88:91], v[188:191], v[212:215], v[88:91]
	v_mfma_f32_16x16x32_bf16 v[68:71], v[180:183], v[220:223], v[68:71]
	v_mfma_f32_16x16x32_bf16 v[64:67], v[188:191], v[220:223], v[64:67]
	s_barrier
	s_setprio 0
	s_add_i32 s88, s77, s97
	v_lshl_add_u64 v[152:153], s[46:47], 0, v[132:133]
	s_mov_b32 m0, s88
	ds_read_b128 v[192:195], v161 offset:16384
	ds_read_b128 v[196:199], v161 offset:17408
	ds_read_b128 v[200:203], v161 offset:18432
	ds_read_b128 v[204:207], v161 offset:19456
	ds_read_b128 v[208:211], v161 offset:20480
	ds_read_b128 v[212:215], v161 offset:21504
	ds_read_b128 v[216:219], v161 offset:22528
	ds_read_b128 v[220:223], v161 offset:23552
	global_load_lds_dwordx4 v[152:153], off
	s_add_i32 m0, s88, 0x2000
	s_add_u32 s88, s46, 0x100000
	v_lshl_add_u64 v[224:225], s[46:47], 0, v[136:137]
	s_addc_u32 s89, s47, 0
	s_add_i32 s90, s78, s97
	global_load_lds_dwordx4 v[224:225], off
	s_mov_b32 m0, s90
	v_lshl_add_u64 v[228:229], s[48:49], 0, v[134:135]
	global_load_lds_dwordx4 v132, s[88:89]
	s_add_i32 m0, s90, 0x2000
	s_nop 0
	global_load_lds_dwordx4 v136, s[88:89]
	v_lshl_add_u64 v[226:227], s[48:49], 0, v[130:131]
	s_mov_b32 m0, s94
	s_nop 0
	global_load_lds_dwordx4 v[226:227], off
	s_mov_b32 m0, s52
	s_nop 0
	global_load_lds_dwordx4 v[228:229], off
	s_waitcnt vmcnt(8)
	s_waitcnt lgkmcnt(0)
	s_setprio 1
	s_barrier
	v_mfma_f32_16x16x32_bf16 v[60:63], v[148:151], v[192:195], v[60:63]
	v_mfma_f32_16x16x32_bf16 v[56:59], v[168:171], v[192:195], v[56:59]
	v_mfma_f32_16x16x32_bf16 v[36:39], v[148:151], v[200:203], v[36:39]
	v_mfma_f32_16x16x32_bf16 v[32:35], v[168:171], v[200:203], v[32:35]
	v_mfma_f32_16x16x32_bf16 v[20:23], v[148:151], v[208:211], v[20:23]
	v_mfma_f32_16x16x32_bf16 v[16:19], v[168:171], v[208:211], v[16:19]
	v_mfma_f32_16x16x32_bf16 v[4:7], v[148:151], v[216:219], v[4:7]
	v_mfma_f32_16x16x32_bf16 v[0:3], v[168:171], v[216:219], v[0:3]
	v_mfma_f32_16x16x32_bf16 v[60:63], v[164:167], v[196:199], v[60:63]
	v_mfma_f32_16x16x32_bf16 v[56:59], v[172:175], v[196:199], v[56:59]
	v_mfma_f32_16x16x32_bf16 v[36:39], v[164:167], v[204:207], v[36:39]
	v_mfma_f32_16x16x32_bf16 v[32:35], v[172:175], v[204:207], v[32:35]
	v_mfma_f32_16x16x32_bf16 v[20:23], v[164:167], v[212:215], v[20:23]
	v_mfma_f32_16x16x32_bf16 v[16:19], v[172:175], v[212:215], v[16:19]
	v_mfma_f32_16x16x32_bf16 v[4:7], v[164:167], v[220:223], v[4:7]
	v_mfma_f32_16x16x32_bf16 v[0:3], v[172:175], v[220:223], v[0:3]
	s_setprio 0
	s_setprio 1
	v_mfma_f32_16x16x32_bf16 v[76:79], v[176:179], v[192:195], v[76:79]
	v_mfma_f32_16x16x32_bf16 v[72:75], v[184:187], v[192:195], v[72:75]
	v_mfma_f32_16x16x32_bf16 v[44:47], v[176:179], v[200:203], v[44:47]
	v_mfma_f32_16x16x32_bf16 v[40:43], v[184:187], v[200:203], v[40:43]
	v_mfma_f32_16x16x32_bf16 v[28:31], v[176:179], v[208:211], v[28:31]
	v_mfma_f32_16x16x32_bf16 v[24:27], v[184:187], v[208:211], v[24:27]
	v_mfma_f32_16x16x32_bf16 v[12:15], v[176:179], v[216:219], v[12:15]
	v_mfma_f32_16x16x32_bf16 v[8:11], v[184:187], v[216:219], v[8:11]
	v_mfma_f32_16x16x32_bf16 v[76:79], v[180:183], v[196:199], v[76:79]
	v_mfma_f32_16x16x32_bf16 v[72:75], v[188:191], v[196:199], v[72:75]
	v_mfma_f32_16x16x32_bf16 v[44:47], v[180:183], v[204:207], v[44:47]
	v_mfma_f32_16x16x32_bf16 v[40:43], v[188:191], v[204:207], v[40:43]
	v_mfma_f32_16x16x32_bf16 v[28:31], v[180:183], v[212:215], v[28:31]
	v_mfma_f32_16x16x32_bf16 v[24:27], v[188:191], v[212:215], v[24:27]
	v_mfma_f32_16x16x32_bf16 v[12:15], v[180:183], v[220:223], v[12:15]
	v_mfma_f32_16x16x32_bf16 v[8:11], v[188:191], v[220:223], v[8:11]
	s_barrier
	s_setprio 0
	s_add_i32 s88, 0, 0x18000
	v_add_u32_e32 v163, s88, v157
	s_add_i32 s89, 0, 0x1c000
	ds_read_b128 v[148:151], v163
	ds_read_b128 v[164:167], v163 offset:1024
	ds_read_b128 v[168:171], v163 offset:2048
	ds_read_b128 v[172:175], v163 offset:3072
	v_add_u32_e32 v163, s89, v157
	ds_read_b128 v[176:179], v163
	ds_read_b128 v[180:183], v163 offset:1024
	ds_read_b128 v[184:187], v163 offset:2048
	ds_read_b128 v[188:191], v163 offset:3072
	s_add_u32 s48, s48, 0x100000
	s_addc_u32 s49, s49, 0
	s_mov_b32 m0, s53
	ds_read_b128 v[192:195], v161 offset:32768
	ds_read_b128 v[196:199], v161 offset:33792
	ds_read_b128 v[200:203], v161 offset:34816
	ds_read_b128 v[204:207], v161 offset:35840
	ds_read_b128 v[208:211], v161 offset:36864
	ds_read_b128 v[212:215], v161 offset:37888
	ds_read_b128 v[216:219], v161 offset:38912
	ds_read_b128 v[220:223], v161 offset:39936
	global_load_lds_dwordx4 v130, s[48:49]
	s_mov_b32 m0, s54
	s_nop 0
	global_load_lds_dwordx4 v134, s[48:49]
	s_waitcnt vmcnt(8)
	s_waitcnt lgkmcnt(0)
	s_setprio 1
	s_barrier
	v_mfma_f32_16x16x32_bf16 v[112:115], v[148:151], v[192:195], v[112:115]
	v_mfma_f32_16x16x32_bf16 v[116:119], v[168:171], v[192:195], v[116:119]
	v_mfma_f32_16x16x32_bf16 v[100:103], v[148:151], v[200:203], v[100:103]
	v_mfma_f32_16x16x32_bf16 v[96:99], v[168:171], v[200:203], v[96:99]
	v_mfma_f32_16x16x32_bf16 v[84:87], v[148:151], v[208:211], v[84:87]
	v_mfma_f32_16x16x32_bf16 v[80:83], v[168:171], v[208:211], v[80:83]
	v_mfma_f32_16x16x32_bf16 v[52:55], v[148:151], v[216:219], v[52:55]
	v_mfma_f32_16x16x32_bf16 v[48:51], v[168:171], v[216:219], v[48:51]
	v_mfma_f32_16x16x32_bf16 v[112:115], v[164:167], v[196:199], v[112:115]
	v_mfma_f32_16x16x32_bf16 v[116:119], v[172:175], v[196:199], v[116:119]
	v_mfma_f32_16x16x32_bf16 v[100:103], v[164:167], v[204:207], v[100:103]
	v_mfma_f32_16x16x32_bf16 v[96:99], v[172:175], v[204:207], v[96:99]
	v_mfma_f32_16x16x32_bf16 v[84:87], v[164:167], v[212:215], v[84:87]
	v_mfma_f32_16x16x32_bf16 v[80:83], v[172:175], v[212:215], v[80:83]
	v_mfma_f32_16x16x32_bf16 v[52:55], v[164:167], v[220:223], v[52:55]
	v_mfma_f32_16x16x32_bf16 v[48:51], v[172:175], v[220:223], v[48:51]
	s_setprio 0
	s_setprio 1
	v_mfma_f32_16x16x32_bf16 v[124:127], v[176:179], v[192:195], v[124:127]
	v_mfma_f32_16x16x32_bf16 v[120:123], v[184:187], v[192:195], v[120:123]
	v_mfma_f32_16x16x32_bf16 v[108:111], v[176:179], v[200:203], v[108:111]
	v_mfma_f32_16x16x32_bf16 v[104:107], v[184:187], v[200:203], v[104:107]
	v_mfma_f32_16x16x32_bf16 v[92:95], v[176:179], v[208:211], v[92:95]
	v_mfma_f32_16x16x32_bf16 v[88:91], v[184:187], v[208:211], v[88:91]
	v_mfma_f32_16x16x32_bf16 v[68:71], v[176:179], v[216:219], v[68:71]
	v_mfma_f32_16x16x32_bf16 v[64:67], v[184:187], v[216:219], v[64:67]
	v_mfma_f32_16x16x32_bf16 v[124:127], v[180:183], v[196:199], v[124:127]
	v_mfma_f32_16x16x32_bf16 v[120:123], v[188:191], v[196:199], v[120:123]
	v_mfma_f32_16x16x32_bf16 v[108:111], v[180:183], v[204:207], v[108:111]
	v_mfma_f32_16x16x32_bf16 v[104:107], v[188:191], v[204:207], v[104:107]
	v_mfma_f32_16x16x32_bf16 v[92:95], v[180:183], v[212:215], v[92:95]
	v_mfma_f32_16x16x32_bf16 v[88:91], v[188:191], v[212:215], v[88:91]
	v_mfma_f32_16x16x32_bf16 v[68:71], v[180:183], v[220:223], v[68:71]
	v_mfma_f32_16x16x32_bf16 v[64:67], v[188:191], v[220:223], v[64:67]
	s_barrier
	s_setprio 0
	s_add_i32 s48, s88, s97
	v_lshl_add_u64 v[152:153], v[152:153], 0, s[18:19]
	s_mov_b32 m0, s48
	ds_read_b128 v[192:195], v161 offset:49152
	ds_read_b128 v[196:199], v161 offset:50176
	ds_read_b128 v[200:203], v161 offset:51200
	ds_read_b128 v[204:207], v161 offset:52224
	ds_read_b128 v[208:211], v161 offset:53248
	ds_read_b128 v[212:215], v161 offset:54272
	ds_read_b128 v[216:219], v161 offset:55296
	ds_read_b128 v[220:223], v161 offset:56320
	global_load_lds_dwordx4 v[152:153], off
	s_add_i32 m0, s48, 0x2000
	s_add_u32 s46, s46, 0x100080
	v_lshl_add_u64 v[152:153], v[224:225], 0, s[18:19]
	s_addc_u32 s47, s47, 0
	s_add_i32 s48, s89, s97
	global_load_lds_dwordx4 v[152:153], off
	s_mov_b32 m0, s48
	s_nop 0
	global_load_lds_dwordx4 v132, s[46:47]
	s_add_i32 m0, s48, 0x2000
	s_nop 0
	global_load_lds_dwordx4 v136, s[46:47]
	v_lshl_add_u64 v[152:153], v[226:227], 0, s[18:19]
	s_mov_b32 m0, s68
	s_nop 0
	global_load_lds_dwordx4 v[152:153], off
	v_lshl_add_u64 v[152:153], v[228:229], 0, s[18:19]
	s_mov_b32 m0, s69
	s_nop 0
	global_load_lds_dwordx4 v[152:153], off
	s_waitcnt vmcnt(8)
	s_waitcnt lgkmcnt(0)
	s_setprio 1
	s_barrier
	v_mfma_f32_16x16x32_bf16 v[60:63], v[148:151], v[192:195], v[60:63]
	v_mfma_f32_16x16x32_bf16 v[56:59], v[168:171], v[192:195], v[56:59]
	v_mfma_f32_16x16x32_bf16 v[36:39], v[148:151], v[200:203], v[36:39]
	v_mfma_f32_16x16x32_bf16 v[32:35], v[168:171], v[200:203], v[32:35]
	v_mfma_f32_16x16x32_bf16 v[20:23], v[148:151], v[208:211], v[20:23]
	v_mfma_f32_16x16x32_bf16 v[16:19], v[168:171], v[208:211], v[16:19]
	v_mfma_f32_16x16x32_bf16 v[4:7], v[148:151], v[216:219], v[4:7]
	v_mfma_f32_16x16x32_bf16 v[0:3], v[168:171], v[216:219], v[0:3]
	v_mfma_f32_16x16x32_bf16 v[60:63], v[164:167], v[196:199], v[60:63]
	v_mfma_f32_16x16x32_bf16 v[56:59], v[172:175], v[196:199], v[56:59]
	v_mfma_f32_16x16x32_bf16 v[36:39], v[164:167], v[204:207], v[36:39]
	v_mfma_f32_16x16x32_bf16 v[32:35], v[172:175], v[204:207], v[32:35]
	v_mfma_f32_16x16x32_bf16 v[20:23], v[164:167], v[212:215], v[20:23]
	v_mfma_f32_16x16x32_bf16 v[16:19], v[172:175], v[212:215], v[16:19]
	v_mfma_f32_16x16x32_bf16 v[4:7], v[164:167], v[220:223], v[4:7]
	v_mfma_f32_16x16x32_bf16 v[0:3], v[172:175], v[220:223], v[0:3]
	s_setprio 0
	s_setprio 1
	v_mfma_f32_16x16x32_bf16 v[76:79], v[176:179], v[192:195], v[76:79]
	v_mfma_f32_16x16x32_bf16 v[72:75], v[184:187], v[192:195], v[72:75]
	v_mfma_f32_16x16x32_bf16 v[44:47], v[176:179], v[200:203], v[44:47]
	v_mfma_f32_16x16x32_bf16 v[40:43], v[184:187], v[200:203], v[40:43]
	v_mfma_f32_16x16x32_bf16 v[28:31], v[176:179], v[208:211], v[28:31]
	v_mfma_f32_16x16x32_bf16 v[24:27], v[184:187], v[208:211], v[24:27]
	v_mfma_f32_16x16x32_bf16 v[12:15], v[176:179], v[216:219], v[12:15]
	v_mfma_f32_16x16x32_bf16 v[8:11], v[184:187], v[216:219], v[8:11]
	v_mfma_f32_16x16x32_bf16 v[76:79], v[180:183], v[196:199], v[76:79]
	v_mfma_f32_16x16x32_bf16 v[72:75], v[188:191], v[196:199], v[72:75]
	v_mfma_f32_16x16x32_bf16 v[44:47], v[180:183], v[204:207], v[44:47]
	v_mfma_f32_16x16x32_bf16 v[40:43], v[188:191], v[204:207], v[40:43]
	v_mfma_f32_16x16x32_bf16 v[28:31], v[180:183], v[212:215], v[28:31]
	v_mfma_f32_16x16x32_bf16 v[24:27], v[188:191], v[212:215], v[24:27]
	v_mfma_f32_16x16x32_bf16 v[12:15], v[180:183], v[220:223], v[12:15]
	v_mfma_f32_16x16x32_bf16 v[8:11], v[188:191], v[220:223], v[8:11]
	s_barrier
	s_setprio 0
	s_add_u32 s85, s85, 0x100
	s_addc_u32 s86, s86, 0
	s_add_u32 s44, s44, 0x100
	s_addc_u32 s45, s45, 0
	s_cmp_ge_u32 s87, s84
	s_mov_b32 s46, s87
	s_cbranch_scc0 .LBB0_2289

.LBB0_2452:
	s_cmp_lt_u32 s35, 0x3fffffff
	s_cselect_b64 s[38:39], -1, 0
	s_ashr_i32 s35, s34, 31
	s_and_b64 s[38:39], s[4:5], s[38:39]
	s_lshl_b64 s[4:5], s[34:35], 23
	s_add_u32 s4, s2, s4
	s_addc_u32 s5, s3, s5
	s_add_u32 s4, s4, s36
	s_addc_u32 s5, s5, s37
	s_and_b64 s[48:49], s[38:39], exec
	s_cselect_b32 s35, s5, s47
	s_cselect_b32 s41, s4, s46
	s_ashr_i32 s31, s30, 31
	s_lshl_b64 s[48:49], s[30:31], 23
	v_readlane_b32 s78, v254, 54
	v_readlane_b32 s79, v254, 55
	s_add_u32 s31, s78, s48
	s_addc_u32 s43, s79, s49
	s_add_u32 s36, s31, s36
	s_addc_u32 s37, s43, s37
	s_and_b64 s[48:49], s[38:39], exec
	s_cselect_b32 s31, s37, s45
	s_cselect_b32 s43, s36, s44
	s_add_i32 s75, s76, -2
	s_add_u32 s77, s44, 0x100
	s_addc_u32 s78, s45, 0
	s_add_u32 s44, s46, 0x400080
	s_addc_u32 s45, s47, 0
	s_mov_b32 s46, 0
	ds_read_b128 v[128:131], v228
	ds_read_b128 v[132:135], v228 offset:1024
	ds_read_b128 v[136:139], v228 offset:2048
	ds_read_b128 v[140:143], v228 offset:3072
	ds_read_b128 v[144:147], v229
	ds_read_b128 v[148:151], v229 offset:1024
	ds_read_b128 v[152:155], v229 offset:2048
	ds_read_b128 v[156:159], v229 offset:3072
	s_add_i32 s79, s46, 2
	s_add_u32 s47, s44, 0xffc00080
	s_addc_u32 s48, s45, -1
	s_cmp_eq_u32 s75, s46
	s_cselect_b32 s46, s43, s77
	s_cselect_b32 s49, s35, s48
	s_cselect_b32 s48, s41, s47
	s_cselect_b32 s47, s31, s78
	s_add_i32 m0, s94, 0xc000
	ds_read_b128 v[160:163], v230
	ds_read_b128 v[164:167], v230 offset:1024
	ds_read_b128 v[168:171], v230 offset:2048
	ds_read_b128 v[172:175], v230 offset:3072
	ds_read_b128 v[176:179], v230 offset:4096
	ds_read_b128 v[180:183], v230 offset:5120
	ds_read_b128 v[184:187], v230 offset:6144
	ds_read_b128 v[188:191], v230 offset:7168
	global_load_lds_dwordx4 v202, s[44:45]
	s_add_i32 m0, s94, 0xe000
	s_nop 0
	global_load_lds_dwordx4 v204, s[44:45]
	s_waitcnt vmcnt(8)
	s_waitcnt lgkmcnt(0)
	s_setprio 1
	s_barrier
	v_mfma_f32_16x16x32_bf16 v[112:115], v[128:131], v[160:163], 0
	v_mfma_f32_16x16x32_bf16 v[116:119], v[136:139], v[160:163], 0
	v_mfma_f32_16x16x32_bf16 v[100:103], v[128:131], v[168:171], 0
	v_mfma_f32_16x16x32_bf16 v[96:99], v[136:139], v[168:171], 0
	v_mfma_f32_16x16x32_bf16 v[84:87], v[128:131], v[176:179], 0
	v_mfma_f32_16x16x32_bf16 v[80:83], v[136:139], v[176:179], 0
	v_mfma_f32_16x16x32_bf16 v[52:55], v[128:131], v[184:187], 0
	v_mfma_f32_16x16x32_bf16 v[48:51], v[136:139], v[184:187], 0
	v_mfma_f32_16x16x32_bf16 v[112:115], v[132:135], v[164:167], v[112:115]
	v_mfma_f32_16x16x32_bf16 v[116:119], v[140:143], v[164:167], v[116:119]
	v_mfma_f32_16x16x32_bf16 v[100:103], v[132:135], v[172:175], v[100:103]
	v_mfma_f32_16x16x32_bf16 v[96:99], v[140:143], v[172:175], v[96:99]
	v_mfma_f32_16x16x32_bf16 v[84:87], v[132:135], v[180:183], v[84:87]
	v_mfma_f32_16x16x32_bf16 v[80:83], v[140:143], v[180:183], v[80:83]
	v_mfma_f32_16x16x32_bf16 v[52:55], v[132:135], v[188:191], v[52:55]
	v_mfma_f32_16x16x32_bf16 v[48:51], v[140:143], v[188:191], v[48:51]
	s_setprio 0
	s_setprio 1
	v_mfma_f32_16x16x32_bf16 v[124:127], v[144:147], v[160:163], 0
	v_mfma_f32_16x16x32_bf16 v[120:123], v[152:155], v[160:163], 0
	v_mfma_f32_16x16x32_bf16 v[108:111], v[144:147], v[168:171], 0
	v_mfma_f32_16x16x32_bf16 v[104:107], v[152:155], v[168:171], 0
	v_mfma_f32_16x16x32_bf16 v[92:95], v[144:147], v[176:179], 0
	v_mfma_f32_16x16x32_bf16 v[88:91], v[152:155], v[176:179], 0
	v_mfma_f32_16x16x32_bf16 v[68:71], v[144:147], v[184:187], 0
	v_mfma_f32_16x16x32_bf16 v[64:67], v[152:155], v[184:187], 0
	v_mfma_f32_16x16x32_bf16 v[124:127], v[148:151], v[164:167], v[124:127]
	v_mfma_f32_16x16x32_bf16 v[120:123], v[156:159], v[164:167], v[120:123]
	v_mfma_f32_16x16x32_bf16 v[108:111], v[148:151], v[172:175], v[108:111]
	v_mfma_f32_16x16x32_bf16 v[104:107], v[156:159], v[172:175], v[104:107]
	v_mfma_f32_16x16x32_bf16 v[92:95], v[148:151], v[180:183], v[92:95]
	v_mfma_f32_16x16x32_bf16 v[88:91], v[156:159], v[180:183], v[88:91]
	v_mfma_f32_16x16x32_bf16 v[68:71], v[148:151], v[188:191], v[68:71]
	v_mfma_f32_16x16x32_bf16 v[64:67], v[156:159], v[188:191], v[64:67]
	s_barrier
	s_setprio 0
	s_add_i32 s80, s68, s97
	v_lshl_add_u64 v[208:209], s[46:47], 0, v[194:195]
	s_mov_b32 m0, s80
	ds_read_b128 v[160:163], v230 offset:16384
	ds_read_b128 v[164:167], v230 offset:17408
	ds_read_b128 v[168:171], v230 offset:18432
	ds_read_b128 v[172:175], v230 offset:19456
	ds_read_b128 v[176:179], v230 offset:20480
	ds_read_b128 v[180:183], v230 offset:21504
	ds_read_b128 v[184:187], v230 offset:22528
	ds_read_b128 v[188:191], v230 offset:23552
	global_load_lds_dwordx4 v[208:209], off
	s_add_i32 m0, s80, 0x2000
	s_add_u32 s80, s46, 0x400000
	v_lshl_add_u64 v[210:211], s[46:47], 0, v[198:199]
	s_addc_u32 s81, s47, 0
	s_add_i32 s84, s69, s97
	global_load_lds_dwordx4 v[210:211], off
	s_mov_b32 m0, s84
	v_lshl_add_u64 v[214:215], s[48:49], 0, v[196:197]
	global_load_lds_dwordx4 v194, s[80:81]
	s_add_i32 m0, s84, 0x2000
	s_nop 0
	global_load_lds_dwordx4 v198, s[80:81]
	v_lshl_add_u64 v[212:213], s[48:49], 0, v[192:193]
	s_mov_b32 m0, s94
	s_nop 0
	global_load_lds_dwordx4 v[212:213], off
	s_mov_b32 m0, s51
	s_nop 0
	global_load_lds_dwordx4 v[214:215], off
	s_waitcnt vmcnt(8)
	s_waitcnt lgkmcnt(0)
	s_setprio 1
	s_barrier
	v_mfma_f32_16x16x32_bf16 v[60:63], v[128:131], v[160:163], 0
	v_mfma_f32_16x16x32_bf16 v[56:59], v[136:139], v[160:163], 0
	v_mfma_f32_16x16x32_bf16 v[36:39], v[128:131], v[168:171], 0
	v_mfma_f32_16x16x32_bf16 v[32:35], v[136:139], v[168:171], 0
	v_mfma_f32_16x16x32_bf16 v[20:23], v[128:131], v[176:179], 0
	v_mfma_f32_16x16x32_bf16 v[16:19], v[136:139], v[176:179], 0
	v_mfma_f32_16x16x32_bf16 v[4:7], v[128:131], v[184:187], 0
	v_mfma_f32_16x16x32_bf16 v[0:3], v[136:139], v[184:187], 0
	v_mfma_f32_16x16x32_bf16 v[60:63], v[132:135], v[164:167], v[60:63]
	v_mfma_f32_16x16x32_bf16 v[56:59], v[140:143], v[164:167], v[56:59]
	v_mfma_f32_16x16x32_bf16 v[36:39], v[132:135], v[172:175], v[36:39]
	v_mfma_f32_16x16x32_bf16 v[32:35], v[140:143], v[172:175], v[32:35]
	v_mfma_f32_16x16x32_bf16 v[20:23], v[132:135], v[180:183], v[20:23]
	v_mfma_f32_16x16x32_bf16 v[16:19], v[140:143], v[180:183], v[16:19]
	v_mfma_f32_16x16x32_bf16 v[4:7], v[132:135], v[188:191], v[4:7]
	v_mfma_f32_16x16x32_bf16 v[0:3], v[140:143], v[188:191], v[0:3]
	s_setprio 0
	s_setprio 1
	v_mfma_f32_16x16x32_bf16 v[76:79], v[144:147], v[160:163], 0
	v_mfma_f32_16x16x32_bf16 v[72:75], v[152:155], v[160:163], 0
	v_mfma_f32_16x16x32_bf16 v[44:47], v[144:147], v[168:171], 0
	v_mfma_f32_16x16x32_bf16 v[40:43], v[152:155], v[168:171], 0
	v_mfma_f32_16x16x32_bf16 v[28:31], v[144:147], v[176:179], 0
	v_mfma_f32_16x16x32_bf16 v[24:27], v[152:155], v[176:179], 0
	v_mfma_f32_16x16x32_bf16 v[12:15], v[144:147], v[184:187], 0
	v_mfma_f32_16x16x32_bf16 v[8:11], v[152:155], v[184:187], 0
	v_mfma_f32_16x16x32_bf16 v[76:79], v[148:151], v[164:167], v[76:79]
	v_mfma_f32_16x16x32_bf16 v[72:75], v[156:159], v[164:167], v[72:75]
	v_mfma_f32_16x16x32_bf16 v[44:47], v[148:151], v[172:175], v[44:47]
	v_mfma_f32_16x16x32_bf16 v[40:43], v[156:159], v[172:175], v[40:43]
	v_mfma_f32_16x16x32_bf16 v[28:31], v[148:151], v[180:183], v[28:31]
	v_mfma_f32_16x16x32_bf16 v[24:27], v[156:159], v[180:183], v[24:27]
	v_mfma_f32_16x16x32_bf16 v[12:15], v[148:151], v[188:191], v[12:15]
	v_mfma_f32_16x16x32_bf16 v[8:11], v[156:159], v[188:191], v[8:11]
	s_barrier
	s_setprio 0
	s_add_i32 s80, 0, 0x18000
	s_add_i32 s81, 0, 0x1c000
	v_add_u32_e32 v140, s80, v226
	v_add_u32_e32 v156, s81, v226
	ds_read_b128 v[128:131], v140
	ds_read_b128 v[132:135], v140 offset:1024
	ds_read_b128 v[136:139], v140 offset:2048
	ds_read_b128 v[140:143], v140 offset:3072
	ds_read_b128 v[144:147], v156
	ds_read_b128 v[148:151], v156 offset:1024
	ds_read_b128 v[152:155], v156 offset:2048
	ds_read_b128 v[156:159], v156 offset:3072
	s_add_u32 s48, s48, 0x400000
	s_addc_u32 s49, s49, 0
	s_mov_b32 m0, s52
	ds_read_b128 v[160:163], v230 offset:32768
	ds_read_b128 v[164:167], v230 offset:33792
	ds_read_b128 v[168:171], v230 offset:34816
	ds_read_b128 v[172:175], v230 offset:35840
	ds_read_b128 v[176:179], v230 offset:36864
	ds_read_b128 v[180:183], v230 offset:37888
	ds_read_b128 v[184:187], v230 offset:38912
	ds_read_b128 v[188:191], v230 offset:39936
	global_load_lds_dwordx4 v192, s[48:49]
	s_mov_b32 m0, s53
	s_nop 0
	global_load_lds_dwordx4 v196, s[48:49]
	s_waitcnt vmcnt(8)
	s_waitcnt lgkmcnt(0)
	s_setprio 1
	s_barrier
	v_mfma_f32_16x16x32_bf16 v[112:115], v[128:131], v[160:163], v[112:115]
	v_mfma_f32_16x16x32_bf16 v[116:119], v[136:139], v[160:163], v[116:119]
	v_mfma_f32_16x16x32_bf16 v[100:103], v[128:131], v[168:171], v[100:103]
	v_mfma_f32_16x16x32_bf16 v[96:99], v[136:139], v[168:171], v[96:99]
	v_mfma_f32_16x16x32_bf16 v[84:87], v[128:131], v[176:179], v[84:87]
	v_mfma_f32_16x16x32_bf16 v[80:83], v[136:139], v[176:179], v[80:83]
	v_mfma_f32_16x16x32_bf16 v[52:55], v[128:131], v[184:187], v[52:55]
	v_mfma_f32_16x16x32_bf16 v[48:51], v[136:139], v[184:187], v[48:51]
	v_mfma_f32_16x16x32_bf16 v[112:115], v[132:135], v[164:167], v[112:115]
	v_mfma_f32_16x16x32_bf16 v[116:119], v[140:143], v[164:167], v[116:119]
	v_mfma_f32_16x16x32_bf16 v[100:103], v[132:135], v[172:175], v[100:103]
	v_mfma_f32_16x16x32_bf16 v[96:99], v[140:143], v[172:175], v[96:99]
	v_mfma_f32_16x16x32_bf16 v[84:87], v[132:135], v[180:183], v[84:87]
	v_mfma_f32_16x16x32_bf16 v[80:83], v[140:143], v[180:183], v[80:83]
	v_mfma_f32_16x16x32_bf16 v[52:55], v[132:135], v[188:191], v[52:55]
	v_mfma_f32_16x16x32_bf16 v[48:51], v[140:143], v[188:191], v[48:51]
	s_setprio 0
	s_setprio 1
	v_mfma_f32_16x16x32_bf16 v[124:127], v[144:147], v[160:163], v[124:127]
	v_mfma_f32_16x16x32_bf16 v[120:123], v[152:155], v[160:163], v[120:123]
	v_mfma_f32_16x16x32_bf16 v[108:111], v[144:147], v[168:171], v[108:111]
	v_mfma_f32_16x16x32_bf16 v[104:107], v[152:155], v[168:171], v[104:107]
	v_mfma_f32_16x16x32_bf16 v[92:95], v[144:147], v[176:179], v[92:95]
	v_mfma_f32_16x16x32_bf16 v[88:91], v[152:155], v[176:179], v[88:91]
	v_mfma_f32_16x16x32_bf16 v[68:71], v[144:147], v[184:187], v[68:71]
	v_mfma_f32_16x16x32_bf16 v[64:67], v[152:155], v[184:187], v[64:67]
	v_mfma_f32_16x16x32_bf16 v[124:127], v[148:151], v[164:167], v[124:127]
	v_mfma_f32_16x16x32_bf16 v[120:123], v[156:159], v[164:167], v[120:123]
	v_mfma_f32_16x16x32_bf16 v[108:111], v[148:151], v[172:175], v[108:111]
	v_mfma_f32_16x16x32_bf16 v[104:107], v[156:159], v[172:175], v[104:107]
	v_mfma_f32_16x16x32_bf16 v[92:95], v[148:151], v[180:183], v[92:95]
	v_mfma_f32_16x16x32_bf16 v[88:91], v[156:159], v[180:183], v[88:91]
	v_mfma_f32_16x16x32_bf16 v[68:71], v[148:151], v[188:191], v[68:71]
	v_mfma_f32_16x16x32_bf16 v[64:67], v[156:159], v[188:191], v[64:67]
	s_barrier
	s_setprio 0
	s_add_i32 s48, s80, s97
	v_lshl_add_u64 v[208:209], v[208:209], 0, s[12:13]
	s_mov_b32 m0, s48
	ds_read_b128 v[160:163], v230 offset:49152
	ds_read_b128 v[164:167], v230 offset:50176
	ds_read_b128 v[168:171], v230 offset:51200
	ds_read_b128 v[172:175], v230 offset:52224
	ds_read_b128 v[176:179], v230 offset:53248
	ds_read_b128 v[180:183], v230 offset:54272
	ds_read_b128 v[184:187], v230 offset:55296
	ds_read_b128 v[188:191], v230 offset:56320
	global_load_lds_dwordx4 v[208:209], off
	s_add_i32 m0, s48, 0x2000
	s_add_u32 s46, s46, 0x400080
	v_lshl_add_u64 v[208:209], v[210:211], 0, s[12:13]
	s_addc_u32 s47, s47, 0
	s_add_i32 s48, s81, s97
	global_load_lds_dwordx4 v[208:209], off
	s_mov_b32 m0, s48
	s_nop 0
	global_load_lds_dwordx4 v194, s[46:47]
	s_add_i32 m0, s48, 0x2000
	s_nop 0
	global_load_lds_dwordx4 v198, s[46:47]
	v_lshl_add_u64 v[208:209], v[212:213], 0, s[12:13]
	s_mov_b32 m0, s54
	s_nop 0
	global_load_lds_dwordx4 v[208:209], off
	v_lshl_add_u64 v[208:209], v[214:215], 0, s[12:13]
	s_mov_b32 m0, s55
	s_nop 0
	global_load_lds_dwordx4 v[208:209], off
	s_waitcnt vmcnt(8)
	s_waitcnt lgkmcnt(0)
	s_setprio 1
	s_barrier
	v_mfma_f32_16x16x32_bf16 v[60:63], v[128:131], v[160:163], v[60:63]
	v_mfma_f32_16x16x32_bf16 v[56:59], v[136:139], v[160:163], v[56:59]
	v_mfma_f32_16x16x32_bf16 v[36:39], v[128:131], v[168:171], v[36:39]
	v_mfma_f32_16x16x32_bf16 v[32:35], v[136:139], v[168:171], v[32:35]
	v_mfma_f32_16x16x32_bf16 v[20:23], v[128:131], v[176:179], v[20:23]
	v_mfma_f32_16x16x32_bf16 v[16:19], v[136:139], v[176:179], v[16:19]
	v_mfma_f32_16x16x32_bf16 v[4:7], v[128:131], v[184:187], v[4:7]
	v_mfma_f32_16x16x32_bf16 v[0:3], v[136:139], v[184:187], v[0:3]
	v_mfma_f32_16x16x32_bf16 v[60:63], v[132:135], v[164:167], v[60:63]
	v_mfma_f32_16x16x32_bf16 v[56:59], v[140:143], v[164:167], v[56:59]
	v_mfma_f32_16x16x32_bf16 v[36:39], v[132:135], v[172:175], v[36:39]
	v_mfma_f32_16x16x32_bf16 v[32:35], v[140:143], v[172:175], v[32:35]
	v_mfma_f32_16x16x32_bf16 v[20:23], v[132:135], v[180:183], v[20:23]
	v_mfma_f32_16x16x32_bf16 v[16:19], v[140:143], v[180:183], v[16:19]
	v_mfma_f32_16x16x32_bf16 v[4:7], v[132:135], v[188:191], v[4:7]
	v_mfma_f32_16x16x32_bf16 v[0:3], v[140:143], v[188:191], v[0:3]
	s_setprio 0
	s_setprio 1
	v_mfma_f32_16x16x32_bf16 v[76:79], v[144:147], v[160:163], v[76:79]
	v_mfma_f32_16x16x32_bf16 v[72:75], v[152:155], v[160:163], v[72:75]
	v_mfma_f32_16x16x32_bf16 v[44:47], v[144:147], v[168:171], v[44:47]
	v_mfma_f32_16x16x32_bf16 v[40:43], v[152:155], v[168:171], v[40:43]
	v_mfma_f32_16x16x32_bf16 v[28:31], v[144:147], v[176:179], v[28:31]
	v_mfma_f32_16x16x32_bf16 v[24:27], v[152:155], v[176:179], v[24:27]
	v_mfma_f32_16x16x32_bf16 v[12:15], v[144:147], v[184:187], v[12:15]
	v_mfma_f32_16x16x32_bf16 v[8:11], v[152:155], v[184:187], v[8:11]
	v_mfma_f32_16x16x32_bf16 v[76:79], v[148:151], v[164:167], v[76:79]
	v_mfma_f32_16x16x32_bf16 v[72:75], v[156:159], v[164:167], v[72:75]
	v_mfma_f32_16x16x32_bf16 v[44:47], v[148:151], v[172:175], v[44:47]
	v_mfma_f32_16x16x32_bf16 v[40:43], v[156:159], v[172:175], v[40:43]
	v_mfma_f32_16x16x32_bf16 v[28:31], v[148:151], v[180:183], v[28:31]
	v_mfma_f32_16x16x32_bf16 v[24:27], v[156:159], v[180:183], v[24:27]
	v_mfma_f32_16x16x32_bf16 v[12:15], v[148:151], v[188:191], v[12:15]
	v_mfma_f32_16x16x32_bf16 v[8:11], v[156:159], v[188:191], v[8:11]
	s_barrier
	s_setprio 0
	s_add_u32 s77, s77, 0x100
	s_addc_u32 s78, s78, 0
	s_add_u32 s44, s44, 0x100
	s_addc_u32 s45, s45, 0
	s_cmp_ge_u32 s79, s76
	s_mov_b32 s46, s79
	s_cbranch_scc1 .Lpeel_done_4
.LBB0_2453:
	ds_read_b128 v[128:131], v228
	ds_read_b128 v[132:135], v228 offset:1024
	ds_read_b128 v[136:139], v228 offset:2048
	ds_read_b128 v[140:143], v228 offset:3072
	ds_read_b128 v[144:147], v229
	ds_read_b128 v[148:151], v229 offset:1024
	ds_read_b128 v[152:155], v229 offset:2048
	ds_read_b128 v[156:159], v229 offset:3072
	s_add_i32 s79, s46, 2
	s_add_u32 s47, s44, 0xffc00080
	s_addc_u32 s48, s45, -1
	s_cmp_eq_u32 s75, s46
	s_cselect_b32 s46, s43, s77
	s_cselect_b32 s49, s35, s48
	s_cselect_b32 s48, s41, s47
	s_cselect_b32 s47, s31, s78
	s_add_i32 m0, s94, 0xc000
	ds_read_b128 v[160:163], v230
	ds_read_b128 v[164:167], v230 offset:1024
	ds_read_b128 v[168:171], v230 offset:2048
	ds_read_b128 v[172:175], v230 offset:3072
	ds_read_b128 v[176:179], v230 offset:4096
	ds_read_b128 v[180:183], v230 offset:5120
	ds_read_b128 v[184:187], v230 offset:6144
	ds_read_b128 v[188:191], v230 offset:7168
	global_load_lds_dwordx4 v202, s[44:45]
	s_add_i32 m0, s94, 0xe000
	s_nop 0
	global_load_lds_dwordx4 v204, s[44:45]
	s_waitcnt vmcnt(8)
	s_waitcnt lgkmcnt(0)
	s_setprio 1
	s_barrier
	v_mfma_f32_16x16x32_bf16 v[112:115], v[128:131], v[160:163], v[112:115]
	v_mfma_f32_16x16x32_bf16 v[116:119], v[136:139], v[160:163], v[116:119]
	v_mfma_f32_16x16x32_bf16 v[100:103], v[128:131], v[168:171], v[100:103]
	v_mfma_f32_16x16x32_bf16 v[96:99], v[136:139], v[168:171], v[96:99]
	v_mfma_f32_16x16x32_bf16 v[84:87], v[128:131], v[176:179], v[84:87]
	v_mfma_f32_16x16x32_bf16 v[80:83], v[136:139], v[176:179], v[80:83]
	v_mfma_f32_16x16x32_bf16 v[52:55], v[128:131], v[184:187], v[52:55]
	v_mfma_f32_16x16x32_bf16 v[48:51], v[136:139], v[184:187], v[48:51]
	v_mfma_f32_16x16x32_bf16 v[112:115], v[132:135], v[164:167], v[112:115]
	v_mfma_f32_16x16x32_bf16 v[116:119], v[140:143], v[164:167], v[116:119]
	v_mfma_f32_16x16x32_bf16 v[100:103], v[132:135], v[172:175], v[100:103]
	v_mfma_f32_16x16x32_bf16 v[96:99], v[140:143], v[172:175], v[96:99]
	v_mfma_f32_16x16x32_bf16 v[84:87], v[132:135], v[180:183], v[84:87]
	v_mfma_f32_16x16x32_bf16 v[80:83], v[140:143], v[180:183], v[80:83]
	v_mfma_f32_16x16x32_bf16 v[52:55], v[132:135], v[188:191], v[52:55]
	v_mfma_f32_16x16x32_bf16 v[48:51], v[140:143], v[188:191], v[48:51]
	s_setprio 0
	s_setprio 1
	v_mfma_f32_16x16x32_bf16 v[124:127], v[144:147], v[160:163], v[124:127]
	v_mfma_f32_16x16x32_bf16 v[120:123], v[152:155], v[160:163], v[120:123]
	v_mfma_f32_16x16x32_bf16 v[108:111], v[144:147], v[168:171], v[108:111]
	v_mfma_f32_16x16x32_bf16 v[104:107], v[152:155], v[168:171], v[104:107]
	v_mfma_f32_16x16x32_bf16 v[92:95], v[144:147], v[176:179], v[92:95]
	v_mfma_f32_16x16x32_bf16 v[88:91], v[152:155], v[176:179], v[88:91]
	v_mfma_f32_16x16x32_bf16 v[68:71], v[144:147], v[184:187], v[68:71]
	v_mfma_f32_16x16x32_bf16 v[64:67], v[152:155], v[184:187], v[64:67]
	v_mfma_f32_16x16x32_bf16 v[124:127], v[148:151], v[164:167], v[124:127]
	v_mfma_f32_16x16x32_bf16 v[120:123], v[156:159], v[164:167], v[120:123]
	v_mfma_f32_16x16x32_bf16 v[108:111], v[148:151], v[172:175], v[108:111]
	v_mfma_f32_16x16x32_bf16 v[104:107], v[156:159], v[172:175], v[104:107]
	v_mfma_f32_16x16x32_bf16 v[92:95], v[148:151], v[180:183], v[92:95]
	v_mfma_f32_16x16x32_bf16 v[88:91], v[156:159], v[180:183], v[88:91]
	v_mfma_f32_16x16x32_bf16 v[68:71], v[148:151], v[188:191], v[68:71]
	v_mfma_f32_16x16x32_bf16 v[64:67], v[156:159], v[188:191], v[64:67]
	s_barrier
	s_setprio 0
	s_add_i32 s80, s68, s97
	v_lshl_add_u64 v[208:209], s[46:47], 0, v[194:195]
	s_mov_b32 m0, s80
	ds_read_b128 v[160:163], v230 offset:16384
	ds_read_b128 v[164:167], v230 offset:17408
	ds_read_b128 v[168:171], v230 offset:18432
	ds_read_b128 v[172:175], v230 offset:19456
	ds_read_b128 v[176:179], v230 offset:20480
	ds_read_b128 v[180:183], v230 offset:21504
	ds_read_b128 v[184:187], v230 offset:22528
	ds_read_b128 v[188:191], v230 offset:23552
	global_load_lds_dwordx4 v[208:209], off
	s_add_i32 m0, s80, 0x2000
	s_add_u32 s80, s46, 0x400000
	v_lshl_add_u64 v[210:211], s[46:47], 0, v[198:199]
	s_addc_u32 s81, s47, 0
	s_add_i32 s84, s69, s97
	global_load_lds_dwordx4 v[210:211], off
	s_mov_b32 m0, s84
	v_lshl_add_u64 v[214:215], s[48:49], 0, v[196:197]
	global_load_lds_dwordx4 v194, s[80:81]
	s_add_i32 m0, s84, 0x2000
	s_nop 0
	global_load_lds_dwordx4 v198, s[80:81]
	v_lshl_add_u64 v[212:213], s[48:49], 0, v[192:193]
	s_mov_b32 m0, s94
	s_nop 0
	global_load_lds_dwordx4 v[212:213], off
	s_mov_b32 m0, s51
	s_nop 0
	global_load_lds_dwordx4 v[214:215], off
	s_waitcnt vmcnt(8)
	s_waitcnt lgkmcnt(0)
	s_setprio 1
	s_barrier
	v_mfma_f32_16x16x32_bf16 v[60:63], v[128:131], v[160:163], v[60:63]
	v_mfma_f32_16x16x32_bf16 v[56:59], v[136:139], v[160:163], v[56:59]
	v_mfma_f32_16x16x32_bf16 v[36:39], v[128:131], v[168:171], v[36:39]
	v_mfma_f32_16x16x32_bf16 v[32:35], v[136:139], v[168:171], v[32:35]
	v_mfma_f32_16x16x32_bf16 v[20:23], v[128:131], v[176:179], v[20:23]
	v_mfma_f32_16x16x32_bf16 v[16:19], v[136:139], v[176:179], v[16:19]
	v_mfma_f32_16x16x32_bf16 v[4:7], v[128:131], v[184:187], v[4:7]
	v_mfma_f32_16x16x32_bf16 v[0:3], v[136:139], v[184:187], v[0:3]
	v_mfma_f32_16x16x32_bf16 v[60:63], v[132:135], v[164:167], v[60:63]
	v_mfma_f32_16x16x32_bf16 v[56:59], v[140:143], v[164:167], v[56:59]
	v_mfma_f32_16x16x32_bf16 v[36:39], v[132:135], v[172:175], v[36:39]
	v_mfma_f32_16x16x32_bf16 v[32:35], v[140:143], v[172:175], v[32:35]
	v_mfma_f32_16x16x32_bf16 v[20:23], v[132:135], v[180:183], v[20:23]
	v_mfma_f32_16x16x32_bf16 v[16:19], v[140:143], v[180:183], v[16:19]
	v_mfma_f32_16x16x32_bf16 v[4:7], v[132:135], v[188:191], v[4:7]
	v_mfma_f32_16x16x32_bf16 v[0:3], v[140:143], v[188:191], v[0:3]
	s_setprio 0
	s_setprio 1
	v_mfma_f32_16x16x32_bf16 v[76:79], v[144:147], v[160:163], v[76:79]
	v_mfma_f32_16x16x32_bf16 v[72:75], v[152:155], v[160:163], v[72:75]
	v_mfma_f32_16x16x32_bf16 v[44:47], v[144:147], v[168:171], v[44:47]
	v_mfma_f32_16x16x32_bf16 v[40:43], v[152:155], v[168:171], v[40:43]
	v_mfma_f32_16x16x32_bf16 v[28:31], v[144:147], v[176:179], v[28:31]
	v_mfma_f32_16x16x32_bf16 v[24:27], v[152:155], v[176:179], v[24:27]
	v_mfma_f32_16x16x32_bf16 v[12:15], v[144:147], v[184:187], v[12:15]
	v_mfma_f32_16x16x32_bf16 v[8:11], v[152:155], v[184:187], v[8:11]
	v_mfma_f32_16x16x32_bf16 v[76:79], v[148:151], v[164:167], v[76:79]
	v_mfma_f32_16x16x32_bf16 v[72:75], v[156:159], v[164:167], v[72:75]
	v_mfma_f32_16x16x32_bf16 v[44:47], v[148:151], v[172:175], v[44:47]
	v_mfma_f32_16x16x32_bf16 v[40:43], v[156:159], v[172:175], v[40:43]
	v_mfma_f32_16x16x32_bf16 v[28:31], v[148:151], v[180:183], v[28:31]
	v_mfma_f32_16x16x32_bf16 v[24:27], v[156:159], v[180:183], v[24:27]
	v_mfma_f32_16x16x32_bf16 v[12:15], v[148:151], v[188:191], v[12:15]
	v_mfma_f32_16x16x32_bf16 v[8:11], v[156:159], v[188:191], v[8:11]
	s_barrier
	s_setprio 0
	s_add_i32 s80, 0, 0x18000
	s_add_i32 s81, 0, 0x1c000
	v_add_u32_e32 v140, s80, v226
	v_add_u32_e32 v156, s81, v226
	ds_read_b128 v[128:131], v140
	ds_read_b128 v[132:135], v140 offset:1024
	ds_read_b128 v[136:139], v140 offset:2048
	ds_read_b128 v[140:143], v140 offset:3072
	ds_read_b128 v[144:147], v156
	ds_read_b128 v[148:151], v156 offset:1024
	ds_read_b128 v[152:155], v156 offset:2048
	ds_read_b128 v[156:159], v156 offset:3072
	s_add_u32 s48, s48, 0x400000
	s_addc_u32 s49, s49, 0
	s_mov_b32 m0, s52
	ds_read_b128 v[160:163], v230 offset:32768
	ds_read_b128 v[164:167], v230 offset:33792
	ds_read_b128 v[168:171], v230 offset:34816
	ds_read_b128 v[172:175], v230 offset:35840
	ds_read_b128 v[176:179], v230 offset:36864
	ds_read_b128 v[180:183], v230 offset:37888
	ds_read_b128 v[184:187], v230 offset:38912
	ds_read_b128 v[188:191], v230 offset:39936
	global_load_lds_dwordx4 v192, s[48:49]
	s_mov_b32 m0, s53
	s_nop 0
	global_load_lds_dwordx4 v196, s[48:49]
	s_waitcnt vmcnt(8)
	s_waitcnt lgkmcnt(0)
	s_setprio 1
	s_barrier
	v_mfma_f32_16x16x32_bf16 v[112:115], v[128:131], v[160:163], v[112:115]
	v_mfma_f32_16x16x32_bf16 v[116:119], v[136:139], v[160:163], v[116:119]
	v_mfma_f32_16x16x32_bf16 v[100:103], v[128:131], v[168:171], v[100:103]
	v_mfma_f32_16x16x32_bf16 v[96:99], v[136:139], v[168:171], v[96:99]
	v_mfma_f32_16x16x32_bf16 v[84:87], v[128:131], v[176:179], v[84:87]
	v_mfma_f32_16x16x32_bf16 v[80:83], v[136:139], v[176:179], v[80:83]
	v_mfma_f32_16x16x32_bf16 v[52:55], v[128:131], v[184:187], v[52:55]
	v_mfma_f32_16x16x32_bf16 v[48:51], v[136:139], v[184:187], v[48:51]
	v_mfma_f32_16x16x32_bf16 v[112:115], v[132:135], v[164:167], v[112:115]
	v_mfma_f32_16x16x32_bf16 v[116:119], v[140:143], v[164:167], v[116:119]
	v_mfma_f32_16x16x32_bf16 v[100:103], v[132:135], v[172:175], v[100:103]
	v_mfma_f32_16x16x32_bf16 v[96:99], v[140:143], v[172:175], v[96:99]
	v_mfma_f32_16x16x32_bf16 v[84:87], v[132:135], v[180:183], v[84:87]
	v_mfma_f32_16x16x32_bf16 v[80:83], v[140:143], v[180:183], v[80:83]
	v_mfma_f32_16x16x32_bf16 v[52:55], v[132:135], v[188:191], v[52:55]
	v_mfma_f32_16x16x32_bf16 v[48:51], v[140:143], v[188:191], v[48:51]
	s_setprio 0
	s_setprio 1
	v_mfma_f32_16x16x32_bf16 v[124:127], v[144:147], v[160:163], v[124:127]
	v_mfma_f32_16x16x32_bf16 v[120:123], v[152:155], v[160:163], v[120:123]
	v_mfma_f32_16x16x32_bf16 v[108:111], v[144:147], v[168:171], v[108:111]
	v_mfma_f32_16x16x32_bf16 v[104:107], v[152:155], v[168:171], v[104:107]
	v_mfma_f32_16x16x32_bf16 v[92:95], v[144:147], v[176:179], v[92:95]
	v_mfma_f32_16x16x32_bf16 v[88:91], v[152:155], v[176:179], v[88:91]
	v_mfma_f32_16x16x32_bf16 v[68:71], v[144:147], v[184:187], v[68:71]
	v_mfma_f32_16x16x32_bf16 v[64:67], v[152:155], v[184:187], v[64:67]
	v_mfma_f32_16x16x32_bf16 v[124:127], v[148:151], v[164:167], v[124:127]
	v_mfma_f32_16x16x32_bf16 v[120:123], v[156:159], v[164:167], v[120:123]
	v_mfma_f32_16x16x32_bf16 v[108:111], v[148:151], v[172:175], v[108:111]
	v_mfma_f32_16x16x32_bf16 v[104:107], v[156:159], v[172:175], v[104:107]
	v_mfma_f32_16x16x32_bf16 v[92:95], v[148:151], v[180:183], v[92:95]
	v_mfma_f32_16x16x32_bf16 v[88:91], v[156:159], v[180:183], v[88:91]
	v_mfma_f32_16x16x32_bf16 v[68:71], v[148:151], v[188:191], v[68:71]
	v_mfma_f32_16x16x32_bf16 v[64:67], v[156:159], v[188:191], v[64:67]
	s_barrier
	s_setprio 0
	s_add_i32 s48, s80, s97
	v_lshl_add_u64 v[208:209], v[208:209], 0, s[12:13]
	s_mov_b32 m0, s48
	ds_read_b128 v[160:163], v230 offset:49152
	ds_read_b128 v[164:167], v230 offset:50176
	ds_read_b128 v[168:171], v230 offset:51200
	ds_read_b128 v[172:175], v230 offset:52224
	ds_read_b128 v[176:179], v230 offset:53248
	ds_read_b128 v[180:183], v230 offset:54272
	ds_read_b128 v[184:187], v230 offset:55296
	ds_read_b128 v[188:191], v230 offset:56320
	global_load_lds_dwordx4 v[208:209], off
	s_add_i32 m0, s48, 0x2000
	s_add_u32 s46, s46, 0x400080
	v_lshl_add_u64 v[208:209], v[210:211], 0, s[12:13]
	s_addc_u32 s47, s47, 0
	s_add_i32 s48, s81, s97
	global_load_lds_dwordx4 v[208:209], off
	s_mov_b32 m0, s48
	s_nop 0
	global_load_lds_dwordx4 v194, s[46:47]
	s_add_i32 m0, s48, 0x2000
	s_nop 0
	global_load_lds_dwordx4 v198, s[46:47]
	v_lshl_add_u64 v[208:209], v[212:213], 0, s[12:13]
	s_mov_b32 m0, s54
	s_nop 0
	global_load_lds_dwordx4 v[208:209], off
	v_lshl_add_u64 v[208:209], v[214:215], 0, s[12:13]
	s_mov_b32 m0, s55
	s_nop 0
	global_load_lds_dwordx4 v[208:209], off
	s_waitcnt vmcnt(8)
	s_waitcnt lgkmcnt(0)
	s_setprio 1
	s_barrier
	v_mfma_f32_16x16x32_bf16 v[60:63], v[128:131], v[160:163], v[60:63]
	v_mfma_f32_16x16x32_bf16 v[56:59], v[136:139], v[160:163], v[56:59]
	v_mfma_f32_16x16x32_bf16 v[36:39], v[128:131], v[168:171], v[36:39]
	v_mfma_f32_16x16x32_bf16 v[32:35], v[136:139], v[168:171], v[32:35]
	v_mfma_f32_16x16x32_bf16 v[20:23], v[128:131], v[176:179], v[20:23]
	v_mfma_f32_16x16x32_bf16 v[16:19], v[136:139], v[176:179], v[16:19]
	v_mfma_f32_16x16x32_bf16 v[4:7], v[128:131], v[184:187], v[4:7]
	v_mfma_f32_16x16x32_bf16 v[0:3], v[136:139], v[184:187], v[0:3]
	v_mfma_f32_16x16x32_bf16 v[60:63], v[132:135], v[164:167], v[60:63]
	v_mfma_f32_16x16x32_bf16 v[56:59], v[140:143], v[164:167], v[56:59]
	v_mfma_f32_16x16x32_bf16 v[36:39], v[132:135], v[172:175], v[36:39]
	v_mfma_f32_16x16x32_bf16 v[32:35], v[140:143], v[172:175], v[32:35]
	v_mfma_f32_16x16x32_bf16 v[20:23], v[132:135], v[180:183], v[20:23]
	v_mfma_f32_16x16x32_bf16 v[16:19], v[140:143], v[180:183], v[16:19]
	v_mfma_f32_16x16x32_bf16 v[4:7], v[132:135], v[188:191], v[4:7]
	v_mfma_f32_16x16x32_bf16 v[0:3], v[140:143], v[188:191], v[0:3]
	s_setprio 0
	s_setprio 1
	v_mfma_f32_16x16x32_bf16 v[76:79], v[144:147], v[160:163], v[76:79]
	v_mfma_f32_16x16x32_bf16 v[72:75], v[152:155], v[160:163], v[72:75]
	v_mfma_f32_16x16x32_bf16 v[44:47], v[144:147], v[168:171], v[44:47]
	v_mfma_f32_16x16x32_bf16 v[40:43], v[152:155], v[168:171], v[40:43]
	v_mfma_f32_16x16x32_bf16 v[28:31], v[144:147], v[176:179], v[28:31]
	v_mfma_f32_16x16x32_bf16 v[24:27], v[152:155], v[176:179], v[24:27]
	v_mfma_f32_16x16x32_bf16 v[12:15], v[144:147], v[184:187], v[12:15]
	v_mfma_f32_16x16x32_bf16 v[8:11], v[152:155], v[184:187], v[8:11]
	v_mfma_f32_16x16x32_bf16 v[76:79], v[148:151], v[164:167], v[76:79]
	v_mfma_f32_16x16x32_bf16 v[72:75], v[156:159], v[164:167], v[72:75]
	v_mfma_f32_16x16x32_bf16 v[44:47], v[148:151], v[172:175], v[44:47]
	v_mfma_f32_16x16x32_bf16 v[40:43], v[156:159], v[172:175], v[40:43]
	v_mfma_f32_16x16x32_bf16 v[28:31], v[148:151], v[180:183], v[28:31]
	v_mfma_f32_16x16x32_bf16 v[24:27], v[156:159], v[180:183], v[24:27]
	v_mfma_f32_16x16x32_bf16 v[12:15], v[148:151], v[188:191], v[12:15]
	v_mfma_f32_16x16x32_bf16 v[8:11], v[156:159], v[188:191], v[8:11]
	s_barrier
	s_setprio 0
	s_add_u32 s77, s77, 0x100
	s_addc_u32 s78, s78, 0
	s_add_u32 s44, s44, 0x100
	s_addc_u32 s45, s45, 0
	s_cmp_ge_u32 s79, s76
	s_mov_b32 s46, s79
	s_cbranch_scc0 .LBB0_2453
